# v16: v10 + diff-attn softmax reference folded into the QK MFMA C operand (no v_sub), row sums on VALU partial sums (no ones-MFMA)
# speedup vs baseline: 1.0071x; 1.0013x over previous
.LBB0_34:
	s_lshl_b32 s1, s68, 1
	s_ashr_i32 s70, s69, 6
	s_and_b32 s36, s1, 0x700
	s_mul_i32 s28, s70, 0x1800000
	s_mul_hi_i32 s29, s70, 0x1800000
	s_add_u32 s1, s9, s28
	s_addc_u32 s4, s40, s29
	s_lshl_b32 s5, s69, 4
	s_and_b32 s71, s5, 0x380
	s_lshl_b32 s5, s71, 1
	s_add_u32 s48, s1, s5
	s_addc_u32 s49, s4, 0
	v_mov_b32_e32 v6, v227
	v_mov_b32_e32 v162, v226
	s_add_u32 s30, s48, 0x1000
	s_addc_u32 s31, s49, 0
	v_mov_b64_e32 v[2:3], s[48:49]
	v_ashrrev_i32_e32 v10, 3, v6
	s_movk_i32 s23, 0x1800
	v_lshlrev_b32_e32 v7, 4, v6
	s_lshl_b32 s1, s69, 8
	v_mad_i64_i32 v[4:5], s[4:5], v10, s23, v[2:3]
	v_and_b32_e32 v0, 0x70, v7
	v_and_b32_e32 v144, 0xf0, v7
	v_mov_b32_e32 v145, v1
	v_ashrrev_i32_e32 v11, 4, v6
	v_add_u32_e32 v6, 0x200, v6
	s_and_b32 s11, s1, 0x700
	v_lshl_add_u64 v[150:151], v[4:5], 0, v[0:1]
	v_lshl_add_u64 v[4:5], s[30:31], 0, v[144:145]
	v_ashrrev_i32_e32 v12, 4, v6
	s_xor_b32 s22, s11, 0xf00
	v_readlane_b32 s1, v251, 7
	v_mad_i64_i32 v[152:153], s[4:5], v11, s23, v[4:5]
	v_mad_i64_i32 v[154:155], s[4:5], v12, s23, v[4:5]
	v_and_b32_e32 v145, 31, v162
	v_ashrrev_i32_e32 v5, 5, v162
	s_add_i32 s1, s22, s1
	v_lshlrev_b32_e32 v4, 3, v5
	v_or_b32_e32 v176, s1, v145
	v_lshlrev_b32_e32 v172, 4, v5
	v_lshlrev_b32_e32 v173, 2, v5
	v_ashrrev_i32_e32 v5, 31, v4
	v_mad_u64_u32 v[2:3], s[4:5], v176, s23, v[2:3]
	v_lshl_add_u64 v[156:157], v[4:5], 1, v[2:3]
	global_load_dwordx4 v[114:117], v[150:151], off offset:2048
	global_load_dwordx4 v[118:121], v[152:153], off
	global_load_dwordx4 v[122:125], v[154:155], off
	global_load_dwordx4 v[126:129], v[156:157], off
	global_load_dwordx4 v[130:133], v[156:157], off offset:32
	global_load_dwordx4 v[134:137], v[156:157], off offset:64
	global_load_dwordx4 v[138:141], v[156:157], off offset:96
	v_lshrrev_b32_e32 v14, 2, v162
	v_mad_i64_i32 v[6:7], s[4:5], v10, s23, 0
	v_mad_i64_i32 v[8:9], s[4:5], v11, s23, 0
	v_mul_lo_u32 v163, v10, s96
	s_movk_i32 s78, 0x140
	v_mul_lo_u32 v164, v11, s78
	v_mad_i64_i32 v[10:11], s[4:5], v12, s23, 0
	v_and_or_b32 v2, v14, 3, v173
	s_addk_i32 s22, 0x100
	v_mov_b32_e32 v4, 0x1800000
	s_movk_i32 s78, 0x140
	v_mul_lo_u32 v178, v2, s78
	s_lshr_b32 s4, s22, 6
	v_mad_i64_i32 v[2:3], s[22:23], s70, v4, v[10:11]
	v_or3_b32 v2, v2, s36, v144
	v_lshlrev_b32_e32 v237, 2, v162
	v_and_b32_e32 v13, 16, v162
	v_add_u32_e32 v16, 0, v144
	s_movk_i32 s78, 0x140
	v_mul_lo_u32 v175, v12, s78
	v_lshl_add_u64 v[146:147], s[16:17], 0, v[2:3]
	v_mad_i64_i32 v[2:3], s[22:23], s70, v4, v[8:9]
	v_and_or_b32 v13, v237, 12, v13
	v_add_u32_e32 v15, 0, v163
	v_add_u32_e32 v235, v16, v164
	v_add_u32_e32 v236, v16, v175
	v_or3_b32 v2, v2, s36, v144
	v_mad_i64_i32 v[158:159], s[22:23], s70, v4, v[6:7]
	v_mov_b32_e32 v16, v1
	v_mov_b32_e32 v17, v1
	v_lshlrev_b32_e32 v177, 1, v13
	v_add_u32_e32 v234, v15, v0
	v_lshl_add_u64 v[148:149], s[16:17], 0, v[2:3]
	v_or3_b32 v158, v158, s36, v0
	v_mov_b32_e32 v2, v1
	v_mov_b32_e32 v3, v1
	v_mov_b32_e32 v4, v1
	v_mov_b32_e32 v5, v1
	v_mov_b32_e32 v6, v1
	v_mov_b32_e32 v7, v1
	v_mov_b32_e32 v8, v1
	v_mov_b32_e32 v9, v1
	v_mov_b32_e32 v10, v1
	v_mov_b32_e32 v11, v1
	v_mov_b32_e32 v12, v1
	v_mov_b32_e32 v13, v1
	v_mov_b32_e32 v14, v1
	v_mov_b32_e32 v15, v1
	v_mov_b64_e32 v[64:65], v[16:17]
	v_mov_b64_e32 v[48:49], v[16:17]
	v_mov_b64_e32 v[32:33], v[16:17]
	v_mov_b64_e32 v[80:81], v[16:17]
	s_mov_b32 s10, 1
	v_cmp_gt_u32_e64 s[42:43], 32, v162
	v_mul_u32_u24_e32 v165, 0x90, v145
	v_lshl_add_u32 v174, v145, 2, s91
	s_or_b32 s5, s1, 31
	v_subrev_u32_e32 v179, 32, v176
	v_subrev_u32_e32 v180, 33, v176
	v_subrev_u32_e32 v181, 34, v176
	v_subrev_u32_e32 v182, 35, v176
	v_add_u32_e32 v183, -8, v176
	v_subrev_u32_e32 v184, 40, v176
	v_add_u32_e32 v185, -9, v176
	v_subrev_u32_e32 v186, 41, v176
	v_add_u32_e32 v187, -10, v176
	v_subrev_u32_e32 v188, 42, v176
	v_add_u32_e32 v189, -11, v176
	v_subrev_u32_e32 v195, 43, v176
	v_add_u32_e32 v196, -16, v176
	v_subrev_u32_e32 v197, 48, v176
	v_subrev_u32_e32 v198, 17, v176
	v_subrev_u32_e32 v199, 49, v176
	v_subrev_u32_e32 v200, 18, v176
	v_subrev_u32_e32 v201, 50, v176
	v_subrev_u32_e32 v202, 19, v176
	v_subrev_u32_e32 v203, 51, v176
	v_subrev_u32_e32 v204, 24, v176
	v_subrev_u32_e32 v205, 56, v176
	v_subrev_u32_e32 v228, 25, v176
	v_subrev_u32_e32 v229, 57, v176
	v_subrev_u32_e32 v230, 26, v176
	v_subrev_u32_e32 v231, 58, v176
	v_subrev_u32_e32 v232, 27, v176
	v_subrev_u32_e32 v233, 59, v176
	v_lshl_add_u64 v[160:161], s[44:45], 0, v[158:159]
	s_mov_b32 s22, 63
	s_mov_b64 s[50:51], 0
	v_mov_b64_e32 v[62:63], v[14:15]
	v_mov_b64_e32 v[60:61], v[12:13]
	v_mov_b64_e32 v[58:59], v[10:11]
	v_mov_b64_e32 v[56:57], v[8:9]
	v_mov_b64_e32 v[54:55], v[6:7]
	v_mov_b64_e32 v[52:53], v[4:5]
	v_mov_b64_e32 v[50:51], v[2:3]
	v_mov_b64_e32 v[46:47], v[14:15]
	v_mov_b64_e32 v[44:45], v[12:13]
	v_mov_b64_e32 v[42:43], v[10:11]
	v_mov_b64_e32 v[40:41], v[8:9]
	v_mov_b64_e32 v[38:39], v[6:7]
	v_mov_b64_e32 v[36:37], v[4:5]
	v_mov_b64_e32 v[34:35], v[2:3]
	v_mov_b64_e32 v[30:31], v[14:15]
	v_mov_b64_e32 v[28:29], v[12:13]
	v_mov_b64_e32 v[26:27], v[10:11]
	v_mov_b64_e32 v[24:25], v[8:9]
	v_mov_b64_e32 v[22:23], v[6:7]
	v_mov_b64_e32 v[20:21], v[4:5]
	v_mov_b64_e32 v[18:19], v[2:3]
	v_mov_b64_e32 v[78:79], v[14:15]
	v_mov_b64_e32 v[76:77], v[12:13]
	v_mov_b64_e32 v[74:75], v[10:11]
	v_mov_b64_e32 v[72:73], v[8:9]
	v_mov_b64_e32 v[70:71], v[6:7]
	v_mov_b64_e32 v[68:69], v[4:5]
	v_mov_b64_e32 v[66:67], v[2:3]
	s_waitcnt vmcnt(6)
	ds_write_b128 v234, v[114:117]
	s_waitcnt vmcnt(5)
	ds_write_b128 v235, v[118:121] offset:9216
	s_waitcnt vmcnt(4)
	ds_write_b128 v236, v[122:125] offset:9216
	s_waitcnt vmcnt(0) lgkmcnt(0)
	s_barrier
	v_mov_b32_e32 v239, 0
	s_mov_b32 s79, 1
	s_cmp_lt_u32 s10, s4
	s_cselect_b64 s[60:61], -1, 0
	s_cmp_ge_u32 s10, s4
	s_cbranch_scc1 .LBB0_36

.LBB0_36:
	s_add_i32 s23, s10, -1
	s_and_b32 s23, s23, 1
	s_sub_i32 s26, s22, 63
	s_cmp_gt_u32 s26, s5
	s_cbranch_scc1 .LBB0_43
	s_mul_i32 s26, s23, 0x7400
	s_add_i32 s26, s26, 0
	s_cmp_le_u32 s22, s1
	v_add3_u32 v190, s26, v165, v172
	ds_read_b128 v[98:101], v190
	ds_read_b128 v[102:105], v190 offset:32
	ds_read_b128 v[106:109], v190 offset:64
	ds_read_b128 v[110:113], v190 offset:96
	ds_read_b128 v[240:243], v190 offset:4608
	ds_read_b128 v[244:247], v190 offset:4640
	ds_read_b128 v[214:217], v190 offset:4672
	ds_read_b128 v[190:193], v190 offset:4704
	s_setprio 1
	s_waitcnt lgkmcnt(7)
	v_mfma_f32_32x32x16_bf16 v[82:97], v[98:101], v[126:129], v[66:81]
	s_waitcnt lgkmcnt(6)
	v_mfma_f32_32x32x16_bf16 v[82:97], v[102:105], v[130:133], v[82:97]
	s_waitcnt lgkmcnt(5)
	v_mfma_f32_32x32x16_bf16 v[82:97], v[106:109], v[134:137], v[82:97]
	s_waitcnt lgkmcnt(4)
	v_mfma_f32_32x32x16_bf16 v[82:97], v[110:113], v[138:141], v[82:97]
	s_waitcnt lgkmcnt(3)
	v_mfma_f32_32x32x16_bf16 v[98:113], v[240:243], v[126:129], v[66:81]
	s_waitcnt lgkmcnt(2)
	v_mfma_f32_32x32x16_bf16 v[98:113], v[244:247], v[130:133], v[98:113]
	s_waitcnt lgkmcnt(1)
	v_mfma_f32_32x32x16_bf16 v[98:113], v[214:217], v[134:137], v[98:113]
	s_waitcnt lgkmcnt(0)
	v_mfma_f32_32x32x16_bf16 v[98:113], v[190:193], v[138:141], v[98:113]
	s_setprio 0
	s_cbranch_scc1 .LBB0_39
	v_add_u32_e32 v190, s22, v173
	v_subrev_u32_e32 v191, 63, v190
	v_cmp_le_i32_e32 vcc, v191, v179
	v_subrev_u32_e32 v192, 61, v190
	v_subrev_u32_e32 v190, 60, v190
	s_nop 5
	v_cndmask_b32_e32 v98, v220, v98, vcc
	v_cmp_lt_i32_e32 vcc, v191, v176
	s_nop 1
	v_cndmask_b32_e32 v83, v220, v83, vcc
	v_cmp_le_i32_e32 vcc, v191, v176
	s_nop 1
	v_cndmask_b32_e32 v82, v220, v82, vcc
	v_cmp_le_i32_e32 vcc, v191, v180
	s_nop 1
	v_cndmask_b32_e32 v99, v220, v99, vcc
	v_cmp_le_i32_e32 vcc, v192, v176
	s_nop 1
	v_cndmask_b32_e32 v84, v220, v84, vcc
	v_cmp_le_i32_e32 vcc, v191, v181
	s_nop 1
	v_cndmask_b32_e32 v100, v220, v100, vcc
	v_cmp_le_i32_e32 vcc, v190, v176
	s_nop 1
	v_cndmask_b32_e32 v85, v220, v85, vcc
	v_cmp_le_i32_e32 vcc, v191, v182
	s_nop 1
	v_cndmask_b32_e32 v101, v220, v101, vcc
	v_cmp_le_i32_e32 vcc, v191, v183
	s_nop 1
	v_cndmask_b32_e32 v86, v220, v86, vcc
	v_cmp_le_i32_e32 vcc, v191, v184
	s_nop 1
	v_cndmask_b32_e32 v102, v220, v102, vcc
	v_cmp_le_i32_e32 vcc, v191, v185
	s_nop 1
	v_cndmask_b32_e32 v87, v220, v87, vcc
	v_cmp_le_i32_e32 vcc, v191, v186
	s_nop 1
	v_cndmask_b32_e32 v103, v220, v103, vcc
	v_cmp_le_i32_e32 vcc, v191, v187
	s_nop 1
	v_cndmask_b32_e32 v88, v220, v88, vcc
	v_cmp_le_i32_e32 vcc, v191, v188
	s_nop 1
	v_cndmask_b32_e32 v104, v220, v104, vcc
	v_cmp_le_i32_e32 vcc, v191, v189
	s_nop 1
	v_cndmask_b32_e32 v89, v220, v89, vcc
	v_cmp_le_i32_e32 vcc, v191, v195
	s_nop 1
	v_cndmask_b32_e32 v105, v220, v105, vcc
	v_cmp_le_i32_e32 vcc, v191, v196
	s_nop 1
	v_cndmask_b32_e32 v90, v220, v90, vcc
	v_cmp_le_i32_e32 vcc, v191, v197
	s_nop 1
	v_cndmask_b32_e32 v106, v220, v106, vcc
	v_cmp_le_i32_e32 vcc, v191, v198
	s_nop 1
	v_cndmask_b32_e32 v91, v220, v91, vcc
	v_cmp_le_i32_e32 vcc, v191, v199
	s_nop 1
	v_cndmask_b32_e32 v107, v220, v107, vcc
	v_cmp_le_i32_e32 vcc, v191, v200
	s_nop 1
	v_cndmask_b32_e32 v92, v220, v92, vcc
	v_cmp_le_i32_e32 vcc, v191, v201
	s_nop 1
	v_cndmask_b32_e32 v108, v220, v108, vcc
	v_cmp_le_i32_e32 vcc, v191, v202
	s_nop 1
	v_cndmask_b32_e32 v93, v220, v93, vcc
	v_cmp_le_i32_e32 vcc, v191, v203
	s_nop 1
	v_cndmask_b32_e32 v109, v220, v109, vcc
	v_cmp_le_i32_e32 vcc, v191, v204
	s_nop 1
	v_cndmask_b32_e32 v94, v220, v94, vcc
	v_cmp_le_i32_e32 vcc, v191, v205
	s_nop 1
	v_cndmask_b32_e32 v110, v220, v110, vcc
	v_cmp_le_i32_e32 vcc, v191, v228
	s_nop 1
	v_cndmask_b32_e32 v95, v220, v95, vcc
	v_cmp_le_i32_e32 vcc, v191, v229
	s_nop 1
	v_cndmask_b32_e32 v111, v220, v111, vcc
	v_cmp_le_i32_e32 vcc, v191, v230
	s_nop 1
	v_cndmask_b32_e32 v96, v220, v96, vcc
	v_cmp_le_i32_e32 vcc, v191, v231
	s_nop 1
	v_cndmask_b32_e32 v112, v220, v112, vcc
	v_cmp_le_i32_e32 vcc, v191, v232
	s_nop 1
	v_cndmask_b32_e32 v97, v220, v97, vcc
	v_cmp_le_i32_e32 vcc, v191, v233
	s_nop 1
	v_cndmask_b32_e32 v113, v220, v113, vcc
.LBB0_39:
	s_nop 10
	v_max3_f32 v240, v82, v83, v84
	v_max3_f32 v241, v98, v99, v100
	v_max3_f32 v242, v90, v91, v92
	v_max3_f32 v243, v106, v107, v108
	v_max3_f32 v240, v240, v85, v86
	v_max3_f32 v241, v241, v101, v102
	v_max3_f32 v242, v242, v93, v94
	v_max3_f32 v243, v243, v109, v110
	v_max3_f32 v240, v240, v87, v88
	v_max3_f32 v241, v241, v103, v104
	v_max3_f32 v242, v242, v95, v96
	v_max3_f32 v243, v243, v111, v112
	v_max3_f32 v240, v240, v89, v105
	v_max3_f32 v242, v242, v97, v113
	v_max3_f32 v240, v240, v241, v242
	v_max_f32_e32 v240, v240, v243
	v_mov_b32_e32 v241, v240
	s_nop 1
	v_permlane32_swap_b32_e32 v240, v241
	v_max_f32_e32 v238, v240, v241
	s_cmp_lg_u32 s79, 0
	s_cbranch_scc1 .Lfo_first_c1
	v_cmp_lt_f32_e32 vcc, 0x41000000, v238
	s_cbranch_vccz .LBB0_44
	v_max_f32_e32 v238, 0, v238
	v_mov_b32_e32 v241, v238
	s_branch .Lfo_resc_c1
.Lfo_first_c1:
	s_mov_b32 s79, 0
	v_max_f32_e32 v241, 0, v238
.Lfo_resc_c1:
	v_exp_f32_e64 v241, -v241
	v_sub_f32_e32 v66, v66, v238
	v_sub_f32_e32 v82, v82, v238
	v_sub_f32_e32 v83, v83, v238
	v_sub_f32_e32 v84, v84, v238
	v_sub_f32_e32 v85, v85, v238
	v_sub_f32_e32 v86, v86, v238
	v_sub_f32_e32 v87, v87, v238
	v_sub_f32_e32 v88, v88, v238
	v_sub_f32_e32 v89, v89, v238
	v_sub_f32_e32 v90, v90, v238
	v_sub_f32_e32 v91, v91, v238
	v_sub_f32_e32 v92, v92, v238
	v_sub_f32_e32 v93, v93, v238
	v_sub_f32_e32 v94, v94, v238
	v_sub_f32_e32 v95, v95, v238
	v_sub_f32_e32 v96, v96, v238
	v_sub_f32_e32 v97, v97, v238
	v_sub_f32_e32 v98, v98, v238
	v_sub_f32_e32 v99, v99, v238
	v_sub_f32_e32 v100, v100, v238
	v_sub_f32_e32 v101, v101, v238
	v_sub_f32_e32 v102, v102, v238
	v_sub_f32_e32 v103, v103, v238
	v_sub_f32_e32 v104, v104, v238
	v_sub_f32_e32 v105, v105, v238
	v_sub_f32_e32 v106, v106, v238
	v_sub_f32_e32 v107, v107, v238
	v_sub_f32_e32 v108, v108, v238
	v_sub_f32_e32 v109, v109, v238
	v_sub_f32_e32 v110, v110, v238
	v_sub_f32_e32 v111, v111, v238
	v_sub_f32_e32 v112, v112, v238
	v_sub_f32_e32 v113, v113, v238
	v_mov_b32_e32 v67, v66
	v_mov_b32_e32 v68, v66
	v_mov_b32_e32 v69, v66
	v_mov_b32_e32 v70, v66
	v_mov_b32_e32 v71, v66
	v_mov_b32_e32 v72, v66
	v_mov_b32_e32 v73, v66
	v_mov_b32_e32 v74, v66
	v_mov_b32_e32 v75, v66
	v_mov_b32_e32 v76, v66
	v_mov_b32_e32 v77, v66
	v_mov_b32_e32 v78, v66
	v_mov_b32_e32 v79, v66
	v_mov_b32_e32 v80, v66
	v_mov_b32_e32 v81, v66
	v_mul_f32_e32 v239, v239, v241
	s_and_saveexec_b64 s[62:63], s[42:43]
	s_cbranch_execz .LBB0_42
	ds_write_b32 v174, v241 offset:59392
.LBB0_42:
	s_or_b64 exec, exec, s[62:63]
	v_add_u32_e32 v206, s91, v172
	ds_read_b128 v[240:243], v206 offset:59488
	ds_read_b128 v[244:247], v206 offset:59456
	ds_read_b128 v[190:193], v206 offset:59424
	ds_read_b128 v[214:217], v206 offset:59392
	s_waitcnt lgkmcnt(3)
	v_pk_mul_f32 v[14:15], v[14:15], v[240:241]
	s_waitcnt lgkmcnt(2)
	v_pk_mul_f32 v[10:11], v[10:11], v[244:245]
	s_waitcnt lgkmcnt(1)
	v_pk_mul_f32 v[6:7], v[6:7], v[190:191]
	v_pk_mul_f32 v[16:17], v[16:17], v[242:243]
	v_pk_mul_f32 v[12:13], v[12:13], v[246:247]
	v_pk_mul_f32 v[8:9], v[8:9], v[192:193]
	s_waitcnt lgkmcnt(0)
	v_pk_mul_f32 v[4:5], v[4:5], v[216:217]
	v_pk_mul_f32 v[2:3], v[2:3], v[214:215]
	v_pk_mul_f32 v[62:63], v[62:63], v[240:241]
	v_pk_mul_f32 v[58:59], v[58:59], v[244:245]
	v_pk_mul_f32 v[54:55], v[54:55], v[190:191]
	v_pk_mul_f32 v[64:65], v[64:65], v[242:243]
	v_pk_mul_f32 v[60:61], v[60:61], v[246:247]
	v_pk_mul_f32 v[56:57], v[56:57], v[192:193]
	v_pk_mul_f32 v[52:53], v[52:53], v[216:217]
	v_pk_mul_f32 v[50:51], v[50:51], v[214:215]
	v_pk_mul_f32 v[46:47], v[46:47], v[240:241]
	v_pk_mul_f32 v[42:43], v[42:43], v[244:245]
	v_pk_mul_f32 v[38:39], v[38:39], v[190:191]
	v_pk_mul_f32 v[48:49], v[48:49], v[242:243]
	v_pk_mul_f32 v[44:45], v[44:45], v[246:247]
	v_pk_mul_f32 v[40:41], v[40:41], v[192:193]
	v_pk_mul_f32 v[36:37], v[36:37], v[216:217]
	v_pk_mul_f32 v[34:35], v[34:35], v[214:215]
	v_pk_mul_f32 v[30:31], v[30:31], v[240:241]
	v_pk_mul_f32 v[26:27], v[26:27], v[244:245]
	v_pk_mul_f32 v[22:23], v[22:23], v[190:191]
	v_pk_mul_f32 v[32:33], v[32:33], v[242:243]
	v_pk_mul_f32 v[28:29], v[28:29], v[246:247]
	v_pk_mul_f32 v[24:25], v[24:25], v[192:193]
	v_pk_mul_f32 v[20:21], v[20:21], v[216:217]
	v_pk_mul_f32 v[18:19], v[18:19], v[214:215]
	s_branch .LBB0_45
.LBB0_43:
	s_andn2_b64 vcc, exec, s[60:61]
	s_cbranch_vccz .LBB0_46
	s_branch .LBB0_47
.LBB0_44:
.LBB0_45:
	v_add3_u32 v190, s26, v178, v177
	ds_read_b64_tr_b16 v[240:241], v190 offset:9216
	ds_read_b64_tr_b16 v[242:243], v190 offset:11776
	ds_read_b64_tr_b16 v[244:245], v190 offset:9280
	ds_read_b64_tr_b16 v[246:247], v190 offset:11840
	ds_read_b64_tr_b16 v[214:215], v190 offset:9344
	ds_read_b64_tr_b16 v[216:217], v190 offset:11904
	v_exp_f32_e32 v82, v82
	v_exp_f32_e32 v83, v83
	v_exp_f32_e32 v84, v84
	v_exp_f32_e32 v85, v85
	v_exp_f32_e32 v86, v86
	v_exp_f32_e32 v87, v87
	v_exp_f32_e32 v88, v88
	v_exp_f32_e32 v89, v89
	v_add_f32_e32 v238, v82, v83
	v_add_f32_e32 v239, v239, v84
	v_add_f32_e32 v238, v238, v85
	v_cvt_pk_bf16_f32 v82, v82, v83
	v_cvt_pk_bf16_f32 v83, v84, v85
	v_cvt_pk_bf16_f32 v84, v86, v87
	v_cvt_pk_bf16_f32 v85, v88, v89
	s_setprio 1
	s_waitcnt lgkmcnt(4)
	v_mfma_f32_32x32x16_bf16 v[2:17], v[82:85], v[240:243], v[2:17]
	v_add_f32_e32 v239, v239, v86
	v_add_f32_e32 v238, v238, v87
	v_add_f32_e32 v239, v239, v88
	v_add_f32_e32 v238, v238, v89
	v_exp_f32_e32 v90, v90
	v_exp_f32_e32 v91, v91
	ds_read_b64_tr_b16 v[240:241], v190 offset:9408
	ds_read_b64_tr_b16 v[242:243], v190 offset:11968
	s_waitcnt lgkmcnt(4)
	v_mfma_f32_32x32x16_bf16 v[50:65], v[82:85], v[244:247], v[50:65]
	v_exp_f32_e32 v92, v92
	v_exp_f32_e32 v93, v93
	v_exp_f32_e32 v94, v94
	ds_read_b64_tr_b16 v[244:245], v190 offset:14336
	ds_read_b64_tr_b16 v[246:247], v190 offset:16896
	s_waitcnt lgkmcnt(4)
	v_mfma_f32_32x32x16_bf16 v[34:49], v[82:85], v[214:217], v[34:49]
	v_exp_f32_e32 v95, v95
	v_exp_f32_e32 v96, v96
	v_exp_f32_e32 v97, v97
	v_add_f32_e32 v239, v239, v90
	ds_read_b64_tr_b16 v[214:215], v190 offset:14400
	ds_read_b64_tr_b16 v[216:217], v190 offset:16960
	s_waitcnt lgkmcnt(4)
	v_mfma_f32_32x32x16_bf16 v[18:33], v[82:85], v[240:243], v[18:33]
	v_add_f32_e32 v238, v238, v91
	v_add_f32_e32 v239, v239, v92
	v_add_f32_e32 v238, v238, v93
	v_cvt_pk_bf16_f32 v90, v90, v91
	v_cvt_pk_bf16_f32 v91, v92, v93
	v_cvt_pk_bf16_f32 v92, v94, v95
	v_cvt_pk_bf16_f32 v93, v96, v97
	s_nop 0
	ds_read_b64_tr_b16 v[240:241], v190 offset:14464
	ds_read_b64_tr_b16 v[242:243], v190 offset:17024
	s_waitcnt lgkmcnt(4)
	v_mfma_f32_32x32x16_bf16 v[2:17], v[90:93], v[244:247], v[2:17]
	v_add_f32_e32 v239, v239, v94
	v_add_f32_e32 v238, v238, v95
	v_add_f32_e32 v239, v239, v96
	v_add_f32_e32 v238, v238, v97
	v_exp_f32_e32 v98, v98
	v_exp_f32_e32 v99, v99
	ds_read_b64_tr_b16 v[244:245], v190 offset:14528
	ds_read_b64_tr_b16 v[246:247], v190 offset:17088
	s_waitcnt lgkmcnt(4)
	v_mfma_f32_32x32x16_bf16 v[50:65], v[90:93], v[214:217], v[50:65]
	v_exp_f32_e32 v100, v100
	v_exp_f32_e32 v101, v101
	v_exp_f32_e32 v102, v102
	ds_read_b64_tr_b16 v[214:215], v190 offset:19456
	ds_read_b64_tr_b16 v[216:217], v190 offset:22016
	s_waitcnt lgkmcnt(4)
	v_mfma_f32_32x32x16_bf16 v[34:49], v[90:93], v[240:243], v[34:49]
	v_exp_f32_e32 v103, v103
	v_exp_f32_e32 v104, v104
	v_exp_f32_e32 v105, v105
	v_add_f32_e32 v239, v239, v98
	ds_read_b64_tr_b16 v[240:241], v190 offset:19520
	ds_read_b64_tr_b16 v[242:243], v190 offset:22080
	s_waitcnt lgkmcnt(4)
	v_mfma_f32_32x32x16_bf16 v[18:33], v[90:93], v[244:247], v[18:33]
	v_add_f32_e32 v238, v238, v99
	v_add_f32_e32 v239, v239, v100
	v_add_f32_e32 v238, v238, v101
	v_cvt_pk_bf16_f32 v98, v98, v99
	v_cvt_pk_bf16_f32 v99, v100, v101
	v_cvt_pk_bf16_f32 v100, v102, v103
	v_cvt_pk_bf16_f32 v101, v104, v105
	s_nop 0
	ds_read_b64_tr_b16 v[244:245], v190 offset:19584
	ds_read_b64_tr_b16 v[246:247], v190 offset:22144
	s_waitcnt lgkmcnt(4)
	v_mfma_f32_32x32x16_bf16 v[2:17], v[98:101], v[214:217], v[2:17]
	v_add_f32_e32 v239, v239, v102
	v_add_f32_e32 v238, v238, v103
	v_add_f32_e32 v239, v239, v104
	v_add_f32_e32 v238, v238, v105
	v_exp_f32_e32 v106, v106
	v_exp_f32_e32 v107, v107
	ds_read_b64_tr_b16 v[214:215], v190 offset:19648
	ds_read_b64_tr_b16 v[216:217], v190 offset:22208
	s_waitcnt lgkmcnt(4)
	v_mfma_f32_32x32x16_bf16 v[50:65], v[98:101], v[240:243], v[50:65]
	v_exp_f32_e32 v108, v108
	v_exp_f32_e32 v109, v109
	v_exp_f32_e32 v110, v110
	ds_read_b64_tr_b16 v[240:241], v190 offset:24576
	ds_read_b64_tr_b16 v[242:243], v190 offset:27136
	s_waitcnt lgkmcnt(4)
	v_mfma_f32_32x32x16_bf16 v[34:49], v[98:101], v[244:247], v[34:49]
	v_exp_f32_e32 v111, v111
	v_exp_f32_e32 v112, v112
	v_exp_f32_e32 v113, v113
	v_add_f32_e32 v239, v239, v106
	ds_read_b64_tr_b16 v[244:245], v190 offset:24640
	ds_read_b64_tr_b16 v[246:247], v190 offset:27200
	s_waitcnt lgkmcnt(4)
	v_mfma_f32_32x32x16_bf16 v[18:33], v[98:101], v[214:217], v[18:33]
	v_add_f32_e32 v238, v238, v107
	v_add_f32_e32 v239, v239, v108
	v_add_f32_e32 v238, v238, v109
	v_cvt_pk_bf16_f32 v106, v106, v107
	v_cvt_pk_bf16_f32 v107, v108, v109
	v_cvt_pk_bf16_f32 v108, v110, v111
	v_cvt_pk_bf16_f32 v109, v112, v113
	s_nop 0
	ds_read_b64_tr_b16 v[214:215], v190 offset:24704
	ds_read_b64_tr_b16 v[216:217], v190 offset:27264
	s_waitcnt lgkmcnt(4)
	v_mfma_f32_32x32x16_bf16 v[2:17], v[106:109], v[240:243], v[2:17]
	v_add_f32_e32 v239, v239, v110
	v_add_f32_e32 v238, v238, v111
	v_add_f32_e32 v239, v239, v112
	v_add_f32_e32 v238, v238, v113
	v_add_f32_e32 v239, v239, v238
	ds_read_b64_tr_b16 v[240:241], v190 offset:24768
	ds_read_b64_tr_b16 v[242:243], v190 offset:27328
	s_waitcnt lgkmcnt(4)
	v_mfma_f32_32x32x16_bf16 v[50:65], v[106:109], v[244:247], v[50:65]
	s_waitcnt lgkmcnt(2)
	v_mfma_f32_32x32x16_bf16 v[34:49], v[106:109], v[214:217], v[34:49]
	s_waitcnt lgkmcnt(0)
	v_mfma_f32_32x32x16_bf16 v[18:33], v[106:109], v[240:243], v[18:33]
	s_setprio 0
	s_movk_i32 s77, 0x110
	s_andn2_b64 vcc, exec, s[60:61]
	s_cbranch_vccnz .LBB0_47

.LBB0_47:
	s_add_i32 s22, s22, 64
	s_add_u32 s50, s50, 0x60000
	s_addc_u32 s51, s51, 0
	s_add_i32 s10, s10, 1
	s_mul_i32 s23, s4, 0x60000
	s_cmp_lg_u32 s23, s50
	s_waitcnt lgkmcnt(0)
	s_barrier
	s_cbranch_scc0 .Lfo_out_c1
	s_cmp_lt_u32 s10, s4
	s_cselect_b64 s[60:61], -1, 0
	s_cmp_ge_u32 s10, s4
	s_cbranch_scc0 .LBB0_35
	s_branch .LBB0_36
.Lfo_out_c1:
	v_mov_b32_e32 v241, v239
	s_nop 1
	v_permlane32_swap_b32_e32 v239, v241
	v_add_f32_e32 v239, v239, v241
	ds_write_b32 v174, v239 offset:59392
	v_add_u32_e32 v240, s91, v172
	s_waitcnt lgkmcnt(0)
	ds_read_b128 v[66:69], v240 offset:59392
	ds_read_b128 v[70:73], v240 offset:59424
	ds_read_b128 v[74:77], v240 offset:59456
	ds_read_b128 v[78:81], v240 offset:59488
	s_waitcnt lgkmcnt(0)
	s_branch .LBB0_49
.LBB0_49:
	v_mov_b32_e32 v82, v2
	v_rcp_f32_e32 v2, v67
	v_mov_b32_e32 v83, v50
	v_mov_b32_e32 v85, v18
	v_mov_b32_e32 v50, v3
	v_mov_b32_e32 v18, v35
	v_pk_mul_f32 v[50:51], v[50:51], v[2:3] op_sel_hi:[1,0]
	v_pk_mul_f32 v[2:3], v[18:19], v[2:3] op_sel_hi:[1,0]
	v_mov_b32_e32 v18, v4
	v_rcp_f32_e32 v4, v69
	v_mov_b32_e32 v84, v34
	v_rcp_f32_e32 v34, v68
	v_mov_b32_e32 v19, v52
	v_mov_b32_e32 v69, v20
	v_mov_b32_e32 v52, v5
	v_mov_b32_e32 v20, v37
	v_pk_mul_f32 v[52:53], v[52:53], v[4:5] op_sel_hi:[1,0]
	v_pk_mul_f32 v[4:5], v[20:21], v[4:5] op_sel_hi:[1,0]
	v_mov_b32_e32 v20, v6
	v_rcp_f32_e32 v6, v71
	v_mov_b32_e32 v68, v36
	v_pk_mul_f32 v[18:19], v[18:19], v[34:35] op_sel_hi:[1,0]
	v_pk_mul_f32 v[34:35], v[68:69], v[34:35] op_sel_hi:[1,0]
	v_rcp_f32_e32 v36, v70
	v_mov_b32_e32 v21, v54
	v_mov_b32_e32 v69, v22
	v_mov_b32_e32 v54, v7
	v_mov_b32_e32 v22, v39
	v_pk_mul_f32 v[54:55], v[54:55], v[6:7] op_sel_hi:[1,0]
	v_pk_mul_f32 v[6:7], v[22:23], v[6:7] op_sel_hi:[1,0]
	v_mov_b32_e32 v22, v8
	v_rcp_f32_e32 v8, v73
	v_mov_b32_e32 v68, v38
	v_pk_mul_f32 v[20:21], v[20:21], v[36:37] op_sel_hi:[1,0]
	v_pk_mul_f32 v[36:37], v[68:69], v[36:37] op_sel_hi:[1,0]
	v_rcp_f32_e32 v38, v72
	v_mov_b32_e32 v23, v56
	v_mov_b32_e32 v69, v24
	v_mov_b32_e32 v56, v9
	v_mov_b32_e32 v24, v41
	v_pk_mul_f32 v[56:57], v[56:57], v[8:9] op_sel_hi:[1,0]
	v_pk_mul_f32 v[8:9], v[24:25], v[8:9] op_sel_hi:[1,0]
	v_mov_b32_e32 v24, v10
	v_rcp_f32_e32 v10, v75
	v_mov_b32_e32 v68, v40
	v_pk_mul_f32 v[22:23], v[22:23], v[38:39] op_sel_hi:[1,0]
	v_pk_mul_f32 v[38:39], v[68:69], v[38:39] op_sel_hi:[1,0]
	v_rcp_f32_e32 v40, v74
	v_mov_b32_e32 v25, v58
	v_mov_b32_e32 v69, v26
	v_mov_b32_e32 v58, v11
	v_mov_b32_e32 v26, v43
	v_pk_mul_f32 v[58:59], v[58:59], v[10:11] op_sel_hi:[1,0]
	v_pk_mul_f32 v[10:11], v[26:27], v[10:11] op_sel_hi:[1,0]
	v_mov_b32_e32 v26, v12
	v_rcp_f32_e32 v12, v77
	v_mov_b32_e32 v68, v42
	v_pk_mul_f32 v[24:25], v[24:25], v[40:41] op_sel_hi:[1,0]
	v_pk_mul_f32 v[40:41], v[68:69], v[40:41] op_sel_hi:[1,0]
	v_rcp_f32_e32 v42, v76
	v_mov_b32_e32 v27, v60
	v_mov_b32_e32 v69, v28
	v_mov_b32_e32 v60, v13
	v_mov_b32_e32 v28, v45
	v_pk_mul_f32 v[60:61], v[60:61], v[12:13] op_sel_hi:[1,0]
	v_pk_mul_f32 v[12:13], v[28:29], v[12:13] op_sel_hi:[1,0]
	v_mov_b32_e32 v28, v14
	v_rcp_f32_e32 v14, v79
	v_mov_b32_e32 v68, v44
	v_rcp_f32_e32 v66, v66
	v_pk_mul_f32 v[26:27], v[26:27], v[42:43] op_sel_hi:[1,0]
	v_pk_mul_f32 v[42:43], v[68:69], v[42:43] op_sel_hi:[1,0]
	v_rcp_f32_e32 v44, v78
	v_mov_b32_e32 v29, v62
	v_mov_b32_e32 v69, v30
	v_mov_b32_e32 v62, v15
	v_mov_b32_e32 v30, v47
	v_pk_mul_f32 v[62:63], v[62:63], v[14:15] op_sel_hi:[1,0]
	v_pk_mul_f32 v[14:15], v[30:31], v[14:15] op_sel_hi:[1,0]
	v_mov_b32_e32 v30, v16
	v_rcp_f32_e32 v16, v81
	v_readlane_b32 s10, v251, 9
	v_mov_b32_e32 v68, v46
	v_pk_mul_f32 v[82:83], v[82:83], v[66:67] op_sel_hi:[1,0]
	v_add_u32_e32 v160, s10, v237
	v_pk_mul_f32 v[66:67], v[84:85], v[66:67] op_sel_hi:[1,0]
	v_pk_mul_f32 v[28:29], v[28:29], v[44:45] op_sel_hi:[1,0]
	v_pk_mul_f32 v[44:45], v[68:69], v[44:45] op_sel_hi:[1,0]
	v_mov_b32_e32 v31, v64
	v_mov_b32_e32 v69, v32
	v_mov_b32_e32 v64, v17
	v_mov_b32_e32 v32, v49
	v_mov_b32_e32 v68, v48
	v_pk_mul_f32 v[64:65], v[64:65], v[16:17] op_sel_hi:[1,0]
	v_pk_mul_f32 v[16:17], v[32:33], v[16:17] op_sel_hi:[1,0]
	v_cvt_pk_bf16_f32 v33, v82, v83
	v_add_u32_e32 v32, 0, v160
	v_cvt_pk_bf16_f32 v48, v66, v67
	ds_write2st64_b32 v32, v33, v48 offset1:1
	v_cvt_pk_bf16_f32 v33, v50, v51
	v_cvt_pk_bf16_f32 v2, v2, v3
	ds_write2st64_b32 v32, v33, v2 offset0:2 offset1:3
	v_cvt_pk_bf16_f32 v2, v18, v19
	v_cvt_pk_bf16_f32 v3, v34, v35
	ds_write2st64_b32 v32, v2, v3 offset0:4 offset1:5
	v_cvt_pk_bf16_f32 v2, v52, v53
	v_cvt_pk_bf16_f32 v3, v4, v5
	ds_write2st64_b32 v32, v2, v3 offset0:6 offset1:7
	v_cvt_pk_bf16_f32 v2, v20, v21
	v_cvt_pk_bf16_f32 v3, v36, v37
	ds_write2st64_b32 v32, v2, v3 offset0:8 offset1:9
	v_cvt_pk_bf16_f32 v2, v54, v55
	v_cvt_pk_bf16_f32 v3, v6, v7
	ds_write2st64_b32 v32, v2, v3 offset0:10 offset1:11
	v_cvt_pk_bf16_f32 v2, v22, v23
	v_cvt_pk_bf16_f32 v3, v38, v39
	ds_write2st64_b32 v32, v2, v3 offset0:12 offset1:13
	v_cvt_pk_bf16_f32 v2, v56, v57
	v_cvt_pk_bf16_f32 v3, v8, v9
	ds_write2st64_b32 v32, v2, v3 offset0:14 offset1:15
	v_cvt_pk_bf16_f32 v2, v24, v25
	v_cvt_pk_bf16_f32 v3, v40, v41
	v_rcp_f32_e32 v46, v80
	ds_write2st64_b32 v32, v2, v3 offset0:16 offset1:17
	v_cvt_pk_bf16_f32 v2, v58, v59
	v_cvt_pk_bf16_f32 v3, v10, v11
	ds_write2st64_b32 v32, v2, v3 offset0:18 offset1:19
	v_cvt_pk_bf16_f32 v2, v26, v27
	v_cvt_pk_bf16_f32 v3, v42, v43
	ds_write2st64_b32 v32, v2, v3 offset0:20 offset1:21
	v_cvt_pk_bf16_f32 v2, v60, v61
	v_cvt_pk_bf16_f32 v3, v12, v13
	ds_write2st64_b32 v32, v2, v3 offset0:22 offset1:23
	v_cvt_pk_bf16_f32 v2, v28, v29
	v_cvt_pk_bf16_f32 v3, v44, v45
	v_pk_mul_f32 v[30:31], v[30:31], v[46:47] op_sel_hi:[1,0]
	v_pk_mul_f32 v[46:47], v[68:69], v[46:47] op_sel_hi:[1,0]
	ds_write2st64_b32 v32, v2, v3 offset0:24 offset1:25
	v_cvt_pk_bf16_f32 v2, v62, v63
	v_cvt_pk_bf16_f32 v3, v14, v15
	ds_write2st64_b32 v32, v2, v3 offset0:26 offset1:27
	v_cvt_pk_bf16_f32 v2, v30, v31
	v_cvt_pk_bf16_f32 v3, v46, v47
	ds_write2st64_b32 v32, v2, v3 offset0:28 offset1:29
	v_cvt_pk_bf16_f32 v2, v64, v65
	v_cvt_pk_bf16_f32 v3, v16, v17
	ds_write2st64_b32 v32, v2, v3 offset0:30 offset1:31
	global_load_dwordx4 v[122:125], v[150:151], off offset:2176
	global_load_dwordx4 v[134:137], v[152:153], off
	global_load_dwordx4 v[138:141], v[154:155], off
	global_load_dwordx4 v[114:117], v[156:157], off offset:128
	global_load_dwordx4 v[118:121], v[156:157], off offset:160
	global_load_dwordx4 v[126:129], v[156:157], off offset:192
	global_load_dwordx4 v[130:133], v[156:157], off offset:224
	v_mov_b32_e32 v16, v1
	v_mov_b32_e32 v17, v1
	v_mov_b32_e32 v2, v1
	v_mov_b32_e32 v3, v1
	v_mov_b32_e32 v4, v1
	v_mov_b32_e32 v5, v1
	v_mov_b32_e32 v6, v1
	v_mov_b32_e32 v7, v1
	v_mov_b32_e32 v8, v1
	v_mov_b32_e32 v9, v1
	v_mov_b32_e32 v10, v1
	v_mov_b32_e32 v11, v1
	v_mov_b32_e32 v12, v1
	v_mov_b32_e32 v13, v1
	v_mov_b32_e32 v14, v1
	v_mov_b32_e32 v15, v1
	v_mov_b64_e32 v[64:65], v[16:17]
	v_mov_b64_e32 v[32:33], v[16:17]
	v_mov_b64_e32 v[48:49], v[16:17]
	v_mov_b64_e32 v[80:81], v[16:17]
	v_lshl_add_u64 v[150:151], s[46:47], 0, v[158:159]
	s_mov_b32 s10, 63
	s_mov_b64 s[60:61], 0
	s_mov_b32 s22, 1
	v_mov_b64_e32 v[62:63], v[14:15]
	v_mov_b64_e32 v[60:61], v[12:13]
	v_mov_b64_e32 v[58:59], v[10:11]
	v_mov_b64_e32 v[56:57], v[8:9]
	v_mov_b64_e32 v[54:55], v[6:7]
	v_mov_b64_e32 v[52:53], v[4:5]
	v_mov_b64_e32 v[50:51], v[2:3]
	v_mov_b64_e32 v[30:31], v[14:15]
	v_mov_b64_e32 v[28:29], v[12:13]
	v_mov_b64_e32 v[26:27], v[10:11]
	v_mov_b64_e32 v[24:25], v[8:9]
	v_mov_b64_e32 v[22:23], v[6:7]
	v_mov_b64_e32 v[20:21], v[4:5]
	v_mov_b64_e32 v[18:19], v[2:3]
	v_mov_b64_e32 v[46:47], v[14:15]
	v_mov_b64_e32 v[44:45], v[12:13]
	v_mov_b64_e32 v[42:43], v[10:11]
	v_mov_b64_e32 v[40:41], v[8:9]
	v_mov_b64_e32 v[38:39], v[6:7]
	v_mov_b64_e32 v[36:37], v[4:5]
	v_mov_b64_e32 v[34:35], v[2:3]
	v_mov_b64_e32 v[78:79], v[14:15]
	v_mov_b64_e32 v[76:77], v[12:13]
	v_mov_b64_e32 v[74:75], v[10:11]
	v_mov_b64_e32 v[72:73], v[8:9]
	v_mov_b64_e32 v[70:71], v[6:7]
	v_mov_b64_e32 v[68:69], v[4:5]
	v_mov_b64_e32 v[66:67], v[2:3]
	s_waitcnt vmcnt(6)
	ds_write_b128 v234, v[122:125]
	s_waitcnt vmcnt(5)
	ds_write_b128 v235, v[134:137] offset:9216
	s_waitcnt vmcnt(4)
	ds_write_b128 v236, v[138:141] offset:9216
	s_waitcnt vmcnt(0) lgkmcnt(0)
	s_barrier
	v_mov_b32_e32 v238, 0
	s_mov_b32 s79, 1
	s_cmp_lt_u32 s22, s4
	s_cselect_b64 s[62:63], -1, 0
	s_cmp_ge_u32 s22, s4
	s_cbranch_scc1 .LBB0_51

.LBB0_51:
	s_add_i32 s23, s22, -1
	s_and_b32 s23, s23, 1
	s_sub_i32 s26, s10, 63
	s_cmp_gt_u32 s26, s5
	s_cbranch_scc1 .LBB0_58
	s_mul_i32 s26, s23, 0x7400
	s_add_i32 s26, s26, 0
	s_cmp_le_u32 s10, s1
	v_add3_u32 v152, s26, v165, v172
	ds_read_b128 v[98:101], v152
	ds_read_b128 v[102:105], v152 offset:32
	ds_read_b128 v[106:109], v152 offset:64
	ds_read_b128 v[110:113], v152 offset:96
	ds_read_b128 v[154:157], v152 offset:4608
	ds_read_b128 v[190:193], v152 offset:4640
	ds_read_b128 v[214:217], v152 offset:4672
	ds_read_b128 v[234:237], v152 offset:4704
	s_setprio 1
	s_waitcnt lgkmcnt(7)
	v_mfma_f32_32x32x16_bf16 v[82:97], v[98:101], v[114:117], v[66:81]
	s_waitcnt lgkmcnt(6)
	v_mfma_f32_32x32x16_bf16 v[82:97], v[102:105], v[118:121], v[82:97]
	s_waitcnt lgkmcnt(5)
	v_mfma_f32_32x32x16_bf16 v[82:97], v[106:109], v[126:129], v[82:97]
	s_waitcnt lgkmcnt(4)
	v_mfma_f32_32x32x16_bf16 v[82:97], v[110:113], v[130:133], v[82:97]
	s_waitcnt lgkmcnt(3)
	v_mfma_f32_32x32x16_bf16 v[98:113], v[154:157], v[114:117], v[66:81]
	s_waitcnt lgkmcnt(2)
	v_mfma_f32_32x32x16_bf16 v[98:113], v[190:193], v[118:121], v[98:113]
	s_waitcnt lgkmcnt(1)
	v_mfma_f32_32x32x16_bf16 v[98:113], v[214:217], v[126:129], v[98:113]
	s_waitcnt lgkmcnt(0)
	v_mfma_f32_32x32x16_bf16 v[98:113], v[234:237], v[130:133], v[98:113]
	s_setprio 0
	s_cbranch_scc1 .LBB0_54
	v_add_u32_e32 v152, s10, v173
	v_subrev_u32_e32 v154, 63, v152
	v_cmp_le_i32_e32 vcc, v154, v179
	v_subrev_u32_e32 v155, 61, v152
	v_subrev_u32_e32 v152, 60, v152
	s_nop 5
	v_cndmask_b32_e32 v98, v220, v98, vcc
	v_cmp_lt_i32_e32 vcc, v154, v176
	s_nop 1
	v_cndmask_b32_e32 v83, v220, v83, vcc
	v_cmp_le_i32_e32 vcc, v154, v176
	s_nop 1
	v_cndmask_b32_e32 v82, v220, v82, vcc
	v_cmp_le_i32_e32 vcc, v154, v180
	s_nop 1
	v_cndmask_b32_e32 v99, v220, v99, vcc
	v_cmp_le_i32_e32 vcc, v155, v176
	s_nop 1
	v_cndmask_b32_e32 v84, v220, v84, vcc
	v_cmp_le_i32_e32 vcc, v154, v181
	s_nop 1
	v_cndmask_b32_e32 v100, v220, v100, vcc
	v_cmp_le_i32_e32 vcc, v152, v176
	s_nop 1
	v_cndmask_b32_e32 v85, v220, v85, vcc
	v_cmp_le_i32_e32 vcc, v154, v182
	s_nop 1
	v_cndmask_b32_e32 v101, v220, v101, vcc
	v_cmp_le_i32_e32 vcc, v154, v183
	s_nop 1
	v_cndmask_b32_e32 v86, v220, v86, vcc
	v_cmp_le_i32_e32 vcc, v154, v184
	s_nop 1
	v_cndmask_b32_e32 v102, v220, v102, vcc
	v_cmp_le_i32_e32 vcc, v154, v185
	s_nop 1
	v_cndmask_b32_e32 v87, v220, v87, vcc
	v_cmp_le_i32_e32 vcc, v154, v186
	s_nop 1
	v_cndmask_b32_e32 v103, v220, v103, vcc
	v_cmp_le_i32_e32 vcc, v154, v187
	s_nop 1
	v_cndmask_b32_e32 v88, v220, v88, vcc
	v_cmp_le_i32_e32 vcc, v154, v188
	s_nop 1
	v_cndmask_b32_e32 v104, v220, v104, vcc
	v_cmp_le_i32_e32 vcc, v154, v189
	s_nop 1
	v_cndmask_b32_e32 v89, v220, v89, vcc
	v_cmp_le_i32_e32 vcc, v154, v195
	s_nop 1
	v_cndmask_b32_e32 v105, v220, v105, vcc
	v_cmp_le_i32_e32 vcc, v154, v196
	s_nop 1
	v_cndmask_b32_e32 v90, v220, v90, vcc
	v_cmp_le_i32_e32 vcc, v154, v197
	s_nop 1
	v_cndmask_b32_e32 v106, v220, v106, vcc
	v_cmp_le_i32_e32 vcc, v154, v198
	s_nop 1
	v_cndmask_b32_e32 v91, v220, v91, vcc
	v_cmp_le_i32_e32 vcc, v154, v199
	s_nop 1
	v_cndmask_b32_e32 v107, v220, v107, vcc
	v_cmp_le_i32_e32 vcc, v154, v200
	s_nop 1
	v_cndmask_b32_e32 v92, v220, v92, vcc
	v_cmp_le_i32_e32 vcc, v154, v201
	s_nop 1
	v_cndmask_b32_e32 v108, v220, v108, vcc
	v_cmp_le_i32_e32 vcc, v154, v202
	s_nop 1
	v_cndmask_b32_e32 v93, v220, v93, vcc
	v_cmp_le_i32_e32 vcc, v154, v203
	s_nop 1
	v_cndmask_b32_e32 v109, v220, v109, vcc
	v_cmp_le_i32_e32 vcc, v154, v204
	s_nop 1
	v_cndmask_b32_e32 v94, v220, v94, vcc
	v_cmp_le_i32_e32 vcc, v154, v205
	s_nop 1
	v_cndmask_b32_e32 v110, v220, v110, vcc
	v_cmp_le_i32_e32 vcc, v154, v228
	s_nop 1
	v_cndmask_b32_e32 v95, v220, v95, vcc
	v_cmp_le_i32_e32 vcc, v154, v229
	s_nop 1
	v_cndmask_b32_e32 v111, v220, v111, vcc
	v_cmp_le_i32_e32 vcc, v154, v230
	s_nop 1
	v_cndmask_b32_e32 v96, v220, v96, vcc
	v_cmp_le_i32_e32 vcc, v154, v231
	s_nop 1
	v_cndmask_b32_e32 v112, v220, v112, vcc
	v_cmp_le_i32_e32 vcc, v154, v232
	s_nop 1
	v_cndmask_b32_e32 v97, v220, v97, vcc
	v_cmp_le_i32_e32 vcc, v154, v233
	s_nop 1
	v_cndmask_b32_e32 v113, v220, v113, vcc
.LBB0_54:
	s_nop 10
	v_max3_f32 v154, v82, v83, v84
	v_max3_f32 v155, v98, v99, v100
	v_max3_f32 v156, v90, v91, v92
	v_max3_f32 v157, v106, v107, v108
	v_max3_f32 v154, v154, v85, v86
	v_max3_f32 v155, v155, v101, v102
	v_max3_f32 v156, v156, v93, v94
	v_max3_f32 v157, v157, v109, v110
	v_max3_f32 v154, v154, v87, v88
	v_max3_f32 v155, v155, v103, v104
	v_max3_f32 v156, v156, v95, v96
	v_max3_f32 v157, v157, v111, v112
	v_max3_f32 v154, v154, v89, v105
	v_max3_f32 v156, v156, v97, v113
	v_max3_f32 v154, v154, v155, v156
	v_max_f32_e32 v154, v154, v157
	v_mov_b32_e32 v155, v154
	s_nop 1
	v_permlane32_swap_b32_e32 v154, v155
	v_max_f32_e32 v152, v154, v155
	s_cmp_lg_u32 s79, 0
	s_cbranch_scc1 .Lfo_first_c2
	v_cmp_lt_f32_e32 vcc, 0x41000000, v152
	s_cbranch_vccz .LBB0_59
	v_max_f32_e32 v152, 0, v152
	v_mov_b32_e32 v155, v152
	s_branch .Lfo_resc_c2
.Lfo_first_c2:
	s_mov_b32 s79, 0
	v_max_f32_e32 v155, 0, v152
.Lfo_resc_c2:
	v_exp_f32_e64 v155, -v155
	v_sub_f32_e32 v66, v66, v152
	v_sub_f32_e32 v82, v82, v152
	v_sub_f32_e32 v83, v83, v152
	v_sub_f32_e32 v84, v84, v152
	v_sub_f32_e32 v85, v85, v152
	v_sub_f32_e32 v86, v86, v152
	v_sub_f32_e32 v87, v87, v152
	v_sub_f32_e32 v88, v88, v152
	v_sub_f32_e32 v89, v89, v152
	v_sub_f32_e32 v90, v90, v152
	v_sub_f32_e32 v91, v91, v152
	v_sub_f32_e32 v92, v92, v152
	v_sub_f32_e32 v93, v93, v152
	v_sub_f32_e32 v94, v94, v152
	v_sub_f32_e32 v95, v95, v152
	v_sub_f32_e32 v96, v96, v152
	v_sub_f32_e32 v97, v97, v152
	v_sub_f32_e32 v98, v98, v152
	v_sub_f32_e32 v99, v99, v152
	v_sub_f32_e32 v100, v100, v152
	v_sub_f32_e32 v101, v101, v152
	v_sub_f32_e32 v102, v102, v152
	v_sub_f32_e32 v103, v103, v152
	v_sub_f32_e32 v104, v104, v152
	v_sub_f32_e32 v105, v105, v152
	v_sub_f32_e32 v106, v106, v152
	v_sub_f32_e32 v107, v107, v152
	v_sub_f32_e32 v108, v108, v152
	v_sub_f32_e32 v109, v109, v152
	v_sub_f32_e32 v110, v110, v152
	v_sub_f32_e32 v111, v111, v152
	v_sub_f32_e32 v112, v112, v152
	v_sub_f32_e32 v113, v113, v152
	v_mov_b32_e32 v67, v66
	v_mov_b32_e32 v68, v66
	v_mov_b32_e32 v69, v66
	v_mov_b32_e32 v70, v66
	v_mov_b32_e32 v71, v66
	v_mov_b32_e32 v72, v66
	v_mov_b32_e32 v73, v66
	v_mov_b32_e32 v74, v66
	v_mov_b32_e32 v75, v66
	v_mov_b32_e32 v76, v66
	v_mov_b32_e32 v77, v66
	v_mov_b32_e32 v78, v66
	v_mov_b32_e32 v79, v66
	v_mov_b32_e32 v80, v66
	v_mov_b32_e32 v81, v66
	v_mul_f32_e32 v238, v238, v155
	s_and_saveexec_b64 s[64:65], s[42:43]
	s_cbranch_execz .LBB0_57
	ds_write_b32 v174, v155 offset:59392
.LBB0_57:
	s_or_b64 exec, exec, s[64:65]
	v_add_u32_e32 v153, s91, v172
	ds_read_b128 v[154:157], v153 offset:59488
	ds_read_b128 v[190:193], v153 offset:59456
	ds_read_b128 v[214:217], v153 offset:59424
	ds_read_b128 v[234:237], v153 offset:59392
	s_waitcnt lgkmcnt(3)
	v_pk_mul_f32 v[14:15], v[14:15], v[154:155]
	s_waitcnt lgkmcnt(2)
	v_pk_mul_f32 v[10:11], v[10:11], v[190:191]
	s_waitcnt lgkmcnt(1)
	v_pk_mul_f32 v[6:7], v[6:7], v[214:215]
	v_pk_mul_f32 v[16:17], v[16:17], v[156:157]
	v_pk_mul_f32 v[12:13], v[12:13], v[192:193]
	v_pk_mul_f32 v[8:9], v[8:9], v[216:217]
	s_waitcnt lgkmcnt(0)
	v_pk_mul_f32 v[4:5], v[4:5], v[236:237]
	v_pk_mul_f32 v[2:3], v[2:3], v[234:235]
	v_pk_mul_f32 v[62:63], v[62:63], v[154:155]
	v_pk_mul_f32 v[58:59], v[58:59], v[190:191]
	v_pk_mul_f32 v[54:55], v[54:55], v[214:215]
	v_pk_mul_f32 v[64:65], v[64:65], v[156:157]
	v_pk_mul_f32 v[60:61], v[60:61], v[192:193]
	v_pk_mul_f32 v[56:57], v[56:57], v[216:217]
	v_pk_mul_f32 v[52:53], v[52:53], v[236:237]
	v_pk_mul_f32 v[50:51], v[50:51], v[234:235]
	v_pk_mul_f32 v[30:31], v[30:31], v[154:155]
	v_pk_mul_f32 v[26:27], v[26:27], v[190:191]
	v_pk_mul_f32 v[22:23], v[22:23], v[214:215]
	v_pk_mul_f32 v[32:33], v[32:33], v[156:157]
	v_pk_mul_f32 v[28:29], v[28:29], v[192:193]
	v_pk_mul_f32 v[24:25], v[24:25], v[216:217]
	v_pk_mul_f32 v[20:21], v[20:21], v[236:237]
	v_pk_mul_f32 v[18:19], v[18:19], v[234:235]
	v_pk_mul_f32 v[46:47], v[46:47], v[154:155]
	v_pk_mul_f32 v[42:43], v[42:43], v[190:191]
	v_pk_mul_f32 v[38:39], v[38:39], v[214:215]
	v_pk_mul_f32 v[48:49], v[48:49], v[156:157]
	v_pk_mul_f32 v[44:45], v[44:45], v[192:193]
	v_pk_mul_f32 v[40:41], v[40:41], v[216:217]
	v_pk_mul_f32 v[36:37], v[36:37], v[236:237]
	v_pk_mul_f32 v[34:35], v[34:35], v[234:235]
	s_branch .LBB0_60
.LBB0_58:
	s_andn2_b64 vcc, exec, s[62:63]
	s_cbranch_vccz .LBB0_61
	s_branch .LBB0_62
.LBB0_59:
.LBB0_60:
	v_add3_u32 v153, s26, v178, v177
	ds_read_b64_tr_b16 v[154:155], v153 offset:9216
	ds_read_b64_tr_b16 v[156:157], v153 offset:11776
	ds_read_b64_tr_b16 v[190:191], v153 offset:9280
	ds_read_b64_tr_b16 v[192:193], v153 offset:11840
	ds_read_b64_tr_b16 v[214:215], v153 offset:9344
	ds_read_b64_tr_b16 v[216:217], v153 offset:11904
	ds_read_b64_tr_b16 v[234:235], v153 offset:9408
	ds_read_b64_tr_b16 v[236:237], v153 offset:11968
	v_exp_f32_e32 v82, v82
	v_exp_f32_e32 v83, v83
	v_exp_f32_e32 v84, v84
	v_exp_f32_e32 v85, v85
	v_exp_f32_e32 v86, v86
	v_exp_f32_e32 v87, v87
	v_exp_f32_e32 v88, v88
	v_exp_f32_e32 v89, v89
	v_add_f32_e32 v239, v82, v83
	v_add_f32_e32 v238, v238, v84
	v_add_f32_e32 v239, v239, v85
	v_cvt_pk_bf16_f32 v82, v82, v83
	v_cvt_pk_bf16_f32 v83, v84, v85
	v_cvt_pk_bf16_f32 v84, v86, v87
	v_cvt_pk_bf16_f32 v85, v88, v89
	s_setprio 1
	s_waitcnt lgkmcnt(6)
	v_mfma_f32_32x32x16_bf16 v[2:17], v[82:85], v[154:157], v[2:17]
	v_add_f32_e32 v238, v238, v86
	v_add_f32_e32 v239, v239, v87
	v_add_f32_e32 v238, v238, v88
	v_add_f32_e32 v239, v239, v89
	v_exp_f32_e32 v90, v90
	v_exp_f32_e32 v91, v91
	ds_read_b64_tr_b16 v[154:155], v153 offset:14336
	ds_read_b64_tr_b16 v[156:157], v153 offset:16896
	s_waitcnt lgkmcnt(6)
	v_mfma_f32_32x32x16_bf16 v[50:65], v[82:85], v[190:193], v[50:65]
	v_exp_f32_e32 v92, v92
	v_exp_f32_e32 v93, v93
	v_exp_f32_e32 v94, v94
	ds_read_b64_tr_b16 v[190:191], v153 offset:14400
	ds_read_b64_tr_b16 v[192:193], v153 offset:16960
	s_waitcnt lgkmcnt(6)
	v_mfma_f32_32x32x16_bf16 v[18:33], v[82:85], v[214:217], v[18:33]
	v_exp_f32_e32 v95, v95
	v_exp_f32_e32 v96, v96
	v_exp_f32_e32 v97, v97
	v_add_f32_e32 v238, v238, v90
	ds_read_b64_tr_b16 v[214:215], v153 offset:14464
	ds_read_b64_tr_b16 v[216:217], v153 offset:17024
	s_waitcnt lgkmcnt(6)
	v_mfma_f32_32x32x16_bf16 v[34:49], v[82:85], v[234:237], v[34:49]
	v_add_f32_e32 v239, v239, v91
	v_add_f32_e32 v238, v238, v92
	v_add_f32_e32 v239, v239, v93
	v_cvt_pk_bf16_f32 v90, v90, v91
	v_cvt_pk_bf16_f32 v91, v92, v93
	v_cvt_pk_bf16_f32 v92, v94, v95
	v_cvt_pk_bf16_f32 v93, v96, v97
	s_nop 0
	ds_read_b64_tr_b16 v[234:235], v153 offset:14528
	ds_read_b64_tr_b16 v[236:237], v153 offset:17088
	s_waitcnt lgkmcnt(6)
	v_mfma_f32_32x32x16_bf16 v[2:17], v[90:93], v[154:157], v[2:17]
	v_add_f32_e32 v238, v238, v94
	v_add_f32_e32 v239, v239, v95
	v_add_f32_e32 v238, v238, v96
	v_add_f32_e32 v239, v239, v97
	v_exp_f32_e32 v98, v98
	v_exp_f32_e32 v99, v99
	ds_read_b64_tr_b16 v[154:155], v153 offset:19456
	ds_read_b64_tr_b16 v[156:157], v153 offset:22016
	s_waitcnt lgkmcnt(6)
	v_mfma_f32_32x32x16_bf16 v[50:65], v[90:93], v[190:193], v[50:65]
	v_exp_f32_e32 v100, v100
	v_exp_f32_e32 v101, v101
	v_exp_f32_e32 v102, v102
	ds_read_b64_tr_b16 v[190:191], v153 offset:19520
	ds_read_b64_tr_b16 v[192:193], v153 offset:22080
	s_waitcnt lgkmcnt(6)
	v_mfma_f32_32x32x16_bf16 v[18:33], v[90:93], v[214:217], v[18:33]
	v_exp_f32_e32 v103, v103
	v_exp_f32_e32 v104, v104
	v_exp_f32_e32 v105, v105
	v_add_f32_e32 v238, v238, v98
	ds_read_b64_tr_b16 v[214:215], v153 offset:19584
	ds_read_b64_tr_b16 v[216:217], v153 offset:22144
	s_waitcnt lgkmcnt(6)
	v_mfma_f32_32x32x16_bf16 v[34:49], v[90:93], v[234:237], v[34:49]
	v_add_f32_e32 v239, v239, v99
	v_add_f32_e32 v238, v238, v100
	v_add_f32_e32 v239, v239, v101
	v_cvt_pk_bf16_f32 v98, v98, v99
	v_cvt_pk_bf16_f32 v99, v100, v101
	v_cvt_pk_bf16_f32 v100, v102, v103
	v_cvt_pk_bf16_f32 v101, v104, v105
	s_nop 0
	ds_read_b64_tr_b16 v[234:235], v153 offset:19648
	ds_read_b64_tr_b16 v[236:237], v153 offset:22208
	s_waitcnt lgkmcnt(6)
	v_mfma_f32_32x32x16_bf16 v[2:17], v[98:101], v[154:157], v[2:17]
	v_add_f32_e32 v238, v238, v102
	v_add_f32_e32 v239, v239, v103
	v_add_f32_e32 v238, v238, v104
	v_add_f32_e32 v239, v239, v105
	v_exp_f32_e32 v106, v106
	v_exp_f32_e32 v107, v107
	ds_read_b64_tr_b16 v[154:155], v153 offset:24576
	ds_read_b64_tr_b16 v[156:157], v153 offset:27136
	s_waitcnt lgkmcnt(6)
	v_mfma_f32_32x32x16_bf16 v[50:65], v[98:101], v[190:193], v[50:65]
	v_exp_f32_e32 v108, v108
	v_exp_f32_e32 v109, v109
	v_exp_f32_e32 v110, v110
	ds_read_b64_tr_b16 v[190:191], v153 offset:24640
	ds_read_b64_tr_b16 v[192:193], v153 offset:27200
	s_waitcnt lgkmcnt(6)
	v_mfma_f32_32x32x16_bf16 v[18:33], v[98:101], v[214:217], v[18:33]
	v_exp_f32_e32 v111, v111
	v_exp_f32_e32 v112, v112
	v_exp_f32_e32 v113, v113
	v_add_f32_e32 v238, v238, v106
	ds_read_b64_tr_b16 v[214:215], v153 offset:24704
	ds_read_b64_tr_b16 v[216:217], v153 offset:27264
	s_waitcnt lgkmcnt(6)
	v_mfma_f32_32x32x16_bf16 v[34:49], v[98:101], v[234:237], v[34:49]
	v_add_f32_e32 v239, v239, v107
	v_add_f32_e32 v238, v238, v108
	v_add_f32_e32 v239, v239, v109
	v_cvt_pk_bf16_f32 v106, v106, v107
	v_cvt_pk_bf16_f32 v107, v108, v109
	v_cvt_pk_bf16_f32 v108, v110, v111
	v_cvt_pk_bf16_f32 v109, v112, v113
	s_nop 0
	ds_read_b64_tr_b16 v[234:235], v153 offset:24768
	ds_read_b64_tr_b16 v[236:237], v153 offset:27328
	s_waitcnt lgkmcnt(6)
	v_mfma_f32_32x32x16_bf16 v[2:17], v[106:109], v[154:157], v[2:17]
	v_add_f32_e32 v238, v238, v110
	v_add_f32_e32 v239, v239, v111
	v_add_f32_e32 v238, v238, v112
	v_add_f32_e32 v239, v239, v113
	v_add_f32_e32 v238, v238, v239
	s_waitcnt lgkmcnt(4)
	v_mfma_f32_32x32x16_bf16 v[50:65], v[106:109], v[190:193], v[50:65]
	s_waitcnt lgkmcnt(2)
	v_mfma_f32_32x32x16_bf16 v[18:33], v[106:109], v[214:217], v[18:33]
	s_waitcnt lgkmcnt(0)
	v_mfma_f32_32x32x16_bf16 v[34:49], v[106:109], v[234:237], v[34:49]
	s_setprio 0
	s_movk_i32 s77, 0x110
	s_andn2_b64 vcc, exec, s[62:63]
	s_cbranch_vccnz .LBB0_62

.LBB0_62:
	s_add_i32 s10, s10, 64
	s_add_u32 s60, s60, 0x60000
	s_addc_u32 s61, s61, 0
	s_add_i32 s22, s22, 1
	s_cmp_lg_u32 s50, s60
	s_waitcnt lgkmcnt(0)
	s_barrier
	s_cbranch_scc0 .Lfo_out_c2
	s_cmp_lt_u32 s22, s4
	s_cselect_b64 s[62:63], -1, 0
	s_cmp_ge_u32 s22, s4
	s_cbranch_scc0 .LBB0_50
	s_branch .LBB0_51
.Lfo_out_c2:
	v_mov_b32_e32 v155, v238
	s_nop 1
	v_permlane32_swap_b32_e32 v238, v155
	v_add_f32_e32 v238, v238, v155
	ds_write_b32 v174, v238 offset:59392
	v_add_u32_e32 v154, s91, v172
	s_waitcnt lgkmcnt(0)
	ds_read_b128 v[66:69], v154 offset:59392
	ds_read_b128 v[70:73], v154 offset:59424
	ds_read_b128 v[74:77], v154 offset:59456
	ds_read_b128 v[78:81], v154 offset:59488
	s_waitcnt lgkmcnt(0)
	s_branch .LBB0_64
.LBB0_64:
	v_readlane_b32 s4, v255, 34
	v_readlane_b32 s5, v255, 35
	s_load_dwordx2 s[50:51], s[4:5], 0xb0
	v_rcp_f32_e32 v94, v69
	v_lshlrev_b32_e32 v69, 2, v145
	v_rcp_f32_e32 v98, v67
	v_rcp_f32_e32 v90, v71
	v_rcp_f32_e32 v86, v73
	s_waitcnt lgkmcnt(0)
	global_load_dword v67, v69, s[50:51]
	global_load_dword v71, v69, s[50:51] offset:128
	global_load_dword v73, v69, s[50:51] offset:256
	v_readlane_b32 s4, v251, 48
	global_load_dword v69, v69, s[50:51] offset:384
	v_rcp_f32_e32 v82, v75
	v_rcp_f32_e32 v96, v68
	v_rcp_f32_e32 v68, v79
	v_rcp_f32_e32 v88, v72
	v_rcp_f32_e32 v84, v74
	v_rcp_f32_e32 v74, v76
	v_rcp_f32_e32 v72, v77
	v_rcp_f32_e32 v100, v66
	v_mov_b32_e32 v106, v34
	v_mov_b32_e32 v107, v18
	s_mov_b32 s5, 0x800000
	v_rcp_f32_e32 v66, v80
	v_ashrrev_i32_e32 v80, 3, v162
	v_rcp_f32_e32 v92, v70
	v_rcp_f32_e32 v70, v78
	v_rcp_f32_e32 v0, v81
	v_and_b32_e32 v81, 0xffffffc, v80
	s_and_b32 s10, s67, 0x700
	s_addk_i32 s10, 0x100
	s_waitcnt vmcnt(3)
	v_mul_f32_e32 v67, 0x3f24fd5c, v67
	s_waitcnt vmcnt(2)
	v_mul_f32_e32 v71, 0x3f24fd5c, v71
	s_waitcnt vmcnt(1)
	v_mul_f32_e32 v73, 0x3f24fd5c, v73
	s_waitcnt vmcnt(0)
	v_mul_f32_e32 v75, 0x3f24fd5c, v69
	v_mov_b32_e32 v69, s4
	s_mov_b32 s4, 1
	v_add_u32_e32 v79, 0, v160
	ds_read2st64_b32 v[76:77], v79 offset1:1
	v_add_u32_e32 v69, 0, v69
	v_lshl_add_u32 v78, v145, 1, v69
	s_waitcnt lgkmcnt(0)
	v_lshlrev_b32_e32 v102, 16, v76
	v_and_b32_e32 v103, 0xffff0000, v76
	v_lshlrev_b32_e32 v105, 16, v77
	v_and_b32_e32 v104, 0xffff0000, v77
	v_mov_b32_e32 v76, v2
	v_mov_b32_e32 v77, v50
	v_pk_mul_f32 v[76:77], v[76:77], v[100:101] op_sel_hi:[1,0]
	v_pk_mul_f32 v[100:101], v[106:107], v[100:101] op_sel_hi:[1,0]
	v_pk_fma_f32 v[102:103], v[142:143], v[76:77], v[102:103] neg_lo:[1,0,0] neg_hi:[1,0,0]
	v_pk_fma_f32 v[100:101], v[142:143], v[100:101], v[104:105] neg_lo:[1,0,0] neg_hi:[1,0,0]
	v_pk_mul_f32 v[76:77], v[102:103], v[102:103]
	v_pk_mul_f32 v[104:105], v[100:101], v[100:101]
	v_add_f32_e32 v2, v76, v77
	v_add_f32_e32 v2, v2, v105
	v_add_f32_e32 v2, v104, v2
	v_mad_u64_u32 v[76:77], s[22:23], v81, s77, v[78:79]
	s_waitcnt lgkmcnt(0)
	s_nop 1
	v_add_f32_dpp v2, v2, v2 quad_perm:[1,0,3,2] row_mask:0xf bank_mask:0xf
	s_waitcnt lgkmcnt(0)
	s_nop 1
	v_add_f32_dpp v2, v2, v2 quad_perm:[2,3,0,1] row_mask:0xf bank_mask:0xf
	s_waitcnt lgkmcnt(0)
	s_nop 1
	v_add_f32_dpp v2, v2, v2 row_half_mirror row_mask:0xf bank_mask:0xf
	s_waitcnt lgkmcnt(0)
	s_nop 1
	v_add_f32_dpp v2, v2, v2 row_mirror row_mask:0xf bank_mask:0xf
	ds_bpermute_b32 v18, v170, v2
	s_waitcnt lgkmcnt(0)
	v_add_f32_e32 v2, v2, v18
	v_fmamk_f32 v2, v2, 0x3c000000, v249
	v_cmp_gt_f32_e32 vcc, s5, v2
	v_mul_f32_e32 v18, 0x4b800000, v2
	s_nop 0
	v_cndmask_b32_e32 v2, v2, v18, vcc
	v_rsq_f32_e32 v2, v2
	s_nop 0
	v_mul_f32_e32 v18, 0x45800000, v2
	v_cndmask_b32_e32 v2, v2, v18, vcc
	v_mul_f32_e32 v18, v102, v2
	v_mul_f32_e32 v18, v67, v18
	v_cvt_pk_bf16_f32 v18, v18, s0
	ds_write_b16 v76, v18
	v_mul_f32_e32 v18, v103, v2
	v_mul_f32_e32 v18, v71, v18
	v_cvt_pk_bf16_f32 v18, v18, s0
	ds_write_b16 v76, v18 offset:64
	v_mul_f32_e32 v18, v101, v2
	v_mul_f32_e32 v2, v100, v2
	v_mul_f32_e32 v18, v73, v18
	v_mul_f32_e32 v2, v75, v2
	v_cvt_pk_bf16_f32 v18, v18, s0
	v_cvt_pk_bf16_f32 v2, v2, s0
	ds_write_b16 v76, v18 offset:128
	ds_write_b16 v76, v2 offset:192
	ds_read2st64_b32 v[100:101], v79 offset0:2 offset1:3
	v_mov_b32_e32 v50, v3
	v_pk_mul_f32 v[50:51], v[50:51], v[98:99] op_sel_hi:[1,0]
	v_mov_b32_e32 v18, v35
	v_pk_mul_f32 v[18:19], v[18:19], v[98:99] op_sel_hi:[1,0]
	s_waitcnt lgkmcnt(0)
	v_lshlrev_b32_e32 v2, 16, v100
	v_and_b32_e32 v3, 0xffff0000, v100
	v_lshlrev_b32_e32 v103, 16, v101
	v_and_b32_e32 v102, 0xffff0000, v101
	v_pk_fma_f32 v[2:3], v[142:143], v[50:51], v[2:3] neg_lo:[1,0,0] neg_hi:[1,0,0]
	v_pk_fma_f32 v[18:19], v[142:143], v[18:19], v[102:103] neg_lo:[1,0,0] neg_hi:[1,0,0]
	v_pk_mul_f32 v[50:51], v[2:3], v[2:3]
	v_pk_mul_f32 v[34:35], v[18:19], v[18:19]
	v_add_f32_e32 v50, v50, v51
	v_add_f32_e32 v35, v50, v35
	v_add_f32_e32 v34, v34, v35
	s_waitcnt lgkmcnt(0)
	s_nop 1
	v_add_f32_dpp v34, v34, v34 quad_perm:[1,0,3,2] row_mask:0xf bank_mask:0xf
	s_waitcnt lgkmcnt(0)
	s_nop 1
	v_add_f32_dpp v34, v34, v34 quad_perm:[2,3,0,1] row_mask:0xf bank_mask:0xf
	s_waitcnt lgkmcnt(0)
	s_nop 1
	v_add_f32_dpp v34, v34, v34 row_half_mirror row_mask:0xf bank_mask:0xf
	s_waitcnt lgkmcnt(0)
	s_nop 1
	v_add_f32_dpp v34, v34, v34 row_mirror row_mask:0xf bank_mask:0xf
	ds_bpermute_b32 v35, v170, v34
	s_waitcnt lgkmcnt(0)
	v_add_f32_e32 v34, v34, v35
	v_fmamk_f32 v34, v34, 0x3c000000, v249
	v_mul_f32_e32 v35, 0x4b800000, v34
	v_cmp_gt_f32_e32 vcc, s5, v34
	s_nop 1
	v_cndmask_b32_e32 v34, v34, v35, vcc
	v_rsq_f32_e32 v34, v34
	s_nop 0
	v_mul_f32_e32 v35, 0x45800000, v34
	v_cndmask_b32_e32 v34, v34, v35, vcc
	v_mul_f32_e32 v2, v2, v34
	v_mul_f32_e32 v3, v3, v34
	v_mul_f32_e32 v19, v19, v34
	v_mul_f32_e32 v18, v18, v34
	v_mul_f32_e32 v2, v67, v2
	v_mul_f32_e32 v3, v71, v3
	v_mul_f32_e32 v19, v73, v19
	v_mul_f32_e32 v18, v75, v18
	v_cvt_pk_bf16_f32 v2, v2, s0
	v_cvt_pk_bf16_f32 v3, v3, s0
	v_cvt_pk_bf16_f32 v19, v19, s0
	v_cvt_pk_bf16_f32 v18, v18, s0
	ds_write_b16 v76, v2 offset:272
	ds_write_b16 v76, v3 offset:336
	ds_write_b16 v76, v19 offset:400
	ds_write_b16 v76, v18 offset:464
	ds_read2st64_b32 v[2:3], v79 offset0:4 offset1:5
	v_mov_b32_e32 v18, v4
	v_mov_b32_e32 v19, v52
	s_waitcnt lgkmcnt(0)
	v_lshlrev_b32_e32 v34, 16, v2
	v_and_b32_e32 v35, 0xffff0000, v2
	v_lshlrev_b32_e32 v51, 16, v3
	v_and_b32_e32 v50, 0xffff0000, v3
	v_pk_mul_f32 v[2:3], v[18:19], v[96:97] op_sel_hi:[1,0]
	s_nop 0
	v_pk_fma_f32 v[2:3], v[142:143], v[2:3], v[34:35] neg_lo:[1,0,0] neg_hi:[1,0,0]
	v_mov_b32_e32 v34, v36
	v_mov_b32_e32 v35, v20
	v_pk_mul_f32 v[34:35], v[34:35], v[96:97] op_sel_hi:[1,0]
	v_pk_mul_f32 v[18:19], v[2:3], v[2:3]
	v_pk_fma_f32 v[34:35], v[142:143], v[34:35], v[50:51] neg_lo:[1,0,0] neg_hi:[1,0,0]
	v_add_f32_e32 v4, v18, v19
	v_pk_mul_f32 v[50:51], v[34:35], v[34:35]
	s_nop 0
	v_add_f32_e32 v4, v4, v51
	v_add_f32_e32 v4, v50, v4
	s_waitcnt lgkmcnt(0)
	s_nop 1
	v_add_f32_dpp v4, v4, v4 quad_perm:[1,0,3,2] row_mask:0xf bank_mask:0xf
	s_waitcnt lgkmcnt(0)
	s_nop 1
	v_add_f32_dpp v4, v4, v4 quad_perm:[2,3,0,1] row_mask:0xf bank_mask:0xf
	s_waitcnt lgkmcnt(0)
	s_nop 1
	v_add_f32_dpp v4, v4, v4 row_half_mirror row_mask:0xf bank_mask:0xf
	s_waitcnt lgkmcnt(0)
	s_nop 1
	v_add_f32_dpp v4, v4, v4 row_mirror row_mask:0xf bank_mask:0xf
	ds_bpermute_b32 v18, v170, v4
	s_waitcnt lgkmcnt(0)
	v_add_f32_e32 v4, v4, v18
	v_fmamk_f32 v4, v4, 0x3c000000, v249
	v_mul_f32_e32 v18, 0x4b800000, v4
	v_cmp_gt_f32_e32 vcc, s5, v4
	s_nop 1
	v_cndmask_b32_e32 v4, v4, v18, vcc
	v_rsq_f32_e32 v4, v4
	s_nop 0
	v_mul_f32_e32 v18, 0x45800000, v4
	v_cndmask_b32_e32 v4, v4, v18, vcc
	v_mul_f32_e32 v2, v2, v4
	v_mul_f32_e32 v3, v3, v4
	v_mul_f32_e32 v18, v35, v4
	v_mul_f32_e32 v4, v34, v4
	v_mul_f32_e32 v2, v67, v2
	v_mul_f32_e32 v3, v71, v3
	v_mul_f32_e32 v18, v73, v18
	v_mul_f32_e32 v4, v75, v4
	v_cvt_pk_bf16_f32 v2, v2, s0
	v_cvt_pk_bf16_f32 v3, v3, s0
	v_cvt_pk_bf16_f32 v18, v18, s0
	v_cvt_pk_bf16_f32 v4, v4, s0
	ds_write_b16 v76, v2 offset:544
	ds_write_b16 v76, v3 offset:608
	ds_write_b16 v76, v18 offset:672
	ds_write_b16 v76, v4 offset:736
	ds_read2st64_b32 v[2:3], v79 offset0:6 offset1:7
	v_mov_b32_e32 v52, v5
	v_mov_b32_e32 v20, v37
	s_waitcnt lgkmcnt(0)
	v_lshlrev_b32_e32 v18, 16, v2
	v_and_b32_e32 v19, 0xffff0000, v2
	v_lshlrev_b32_e32 v35, 16, v3
	v_and_b32_e32 v34, 0xffff0000, v3
	v_pk_mul_f32 v[2:3], v[52:53], v[94:95] op_sel_hi:[1,0]
	s_nop 0
	v_pk_fma_f32 v[4:5], v[142:143], v[2:3], v[18:19] neg_lo:[1,0,0] neg_hi:[1,0,0]
	v_pk_mul_f32 v[18:19], v[20:21], v[94:95] op_sel_hi:[1,0]
	v_pk_mul_f32 v[2:3], v[4:5], v[4:5]
	v_pk_fma_f32 v[18:19], v[142:143], v[18:19], v[34:35] neg_lo:[1,0,0] neg_hi:[1,0,0]
	v_add_f32_e32 v2, v2, v3
	v_pk_mul_f32 v[20:21], v[18:19], v[18:19]
	s_nop 0
	v_add_f32_e32 v2, v2, v21
	v_add_f32_e32 v2, v20, v2
	s_waitcnt lgkmcnt(0)
	s_nop 1
	v_add_f32_dpp v2, v2, v2 quad_perm:[1,0,3,2] row_mask:0xf bank_mask:0xf
	s_waitcnt lgkmcnt(0)
	s_nop 1
	v_add_f32_dpp v2, v2, v2 quad_perm:[2,3,0,1] row_mask:0xf bank_mask:0xf
	s_waitcnt lgkmcnt(0)
	s_nop 1
	v_add_f32_dpp v2, v2, v2 row_half_mirror row_mask:0xf bank_mask:0xf
	s_waitcnt lgkmcnt(0)
	s_nop 1
	v_add_f32_dpp v2, v2, v2 row_mirror row_mask:0xf bank_mask:0xf
	ds_bpermute_b32 v3, v170, v2
	s_waitcnt lgkmcnt(0)
	v_add_f32_e32 v2, v2, v3
	v_fmamk_f32 v2, v2, 0x3c000000, v249
	v_cmp_gt_f32_e32 vcc, s5, v2
	v_mul_f32_e32 v3, 0x4b800000, v2
	s_nop 0
	v_cndmask_b32_e32 v2, v2, v3, vcc
	v_rsq_f32_e32 v2, v2
	s_nop 0
	v_mul_f32_e32 v3, 0x45800000, v2
	v_cndmask_b32_e32 v20, v2, v3, vcc
	v_or_b32_e32 v2, 3, v80
	v_mad_u64_u32 v[2:3], s[22:23], v2, s77, v[78:79]
	v_mul_f32_e32 v3, v4, v20
	v_mul_f32_e32 v3, v67, v3
	v_cvt_pk_bf16_f32 v3, v3, s0
	ds_write_b16 v2, v3
	v_mul_f32_e32 v3, v5, v20
	v_mul_f32_e32 v3, v71, v3
	v_cvt_pk_bf16_f32 v3, v3, s0
	ds_write_b16 v2, v3 offset:64
	v_mul_f32_e32 v3, v19, v20
	v_mul_f32_e32 v3, v73, v3
	v_cvt_pk_bf16_f32 v3, v3, s0
	ds_write_b16 v2, v3 offset:128
	v_mul_f32_e32 v3, v18, v20
	v_mul_f32_e32 v3, v75, v3
	v_cvt_pk_bf16_f32 v3, v3, s0
	ds_write_b16 v2, v3 offset:192
	ds_read2st64_b32 v[4:5], v79 offset0:8 offset1:9
	v_mov_b32_e32 v18, v6
	v_mov_b32_e32 v19, v54
	s_waitcnt lgkmcnt(0)
	v_lshlrev_b32_e32 v20, 16, v4
	v_and_b32_e32 v21, 0xffff0000, v4
	v_lshlrev_b32_e32 v35, 16, v5
	v_and_b32_e32 v34, 0xffff0000, v5
	v_pk_mul_f32 v[4:5], v[18:19], v[92:93] op_sel_hi:[1,0]
	s_nop 0
	v_pk_fma_f32 v[4:5], v[142:143], v[4:5], v[20:21] neg_lo:[1,0,0] neg_hi:[1,0,0]
	v_mov_b32_e32 v20, v38
	v_mov_b32_e32 v21, v22
	v_pk_mul_f32 v[20:21], v[20:21], v[92:93] op_sel_hi:[1,0]
	v_pk_mul_f32 v[18:19], v[4:5], v[4:5]
	v_pk_fma_f32 v[20:21], v[142:143], v[20:21], v[34:35] neg_lo:[1,0,0] neg_hi:[1,0,0]
	v_add_f32_e32 v3, v18, v19
	v_pk_mul_f32 v[34:35], v[20:21], v[20:21]
	s_nop 0
	v_add_f32_e32 v3, v3, v35
	v_add_f32_e32 v3, v34, v3
	s_waitcnt lgkmcnt(0)
	s_nop 1
	v_add_f32_dpp v3, v3, v3 quad_perm:[1,0,3,2] row_mask:0xf bank_mask:0xf
	s_waitcnt lgkmcnt(0)
	s_nop 1
	v_add_f32_dpp v3, v3, v3 quad_perm:[2,3,0,1] row_mask:0xf bank_mask:0xf
	s_waitcnt lgkmcnt(0)
	s_nop 1
	v_add_f32_dpp v3, v3, v3 row_half_mirror row_mask:0xf bank_mask:0xf
	s_waitcnt lgkmcnt(0)
	s_nop 1
	v_add_f32_dpp v3, v3, v3 row_mirror row_mask:0xf bank_mask:0xf
	ds_bpermute_b32 v6, v170, v3
	s_waitcnt lgkmcnt(0)
	v_add_f32_e32 v3, v3, v6
	v_fmamk_f32 v3, v3, 0x3c000000, v249
	v_mul_f32_e32 v6, 0x4b800000, v3
	v_cmp_gt_f32_e32 vcc, s5, v3
	s_nop 1
	v_cndmask_b32_e32 v3, v3, v6, vcc
	v_rsq_f32_e32 v3, v3
	s_nop 0
	v_mul_f32_e32 v6, 0x45800000, v3
	v_cndmask_b32_e32 v3, v3, v6, vcc
	v_mul_f32_e32 v4, v4, v3
	v_mul_f32_e32 v5, v5, v3
	v_mul_f32_e32 v6, v21, v3
	v_mul_f32_e32 v3, v20, v3
	v_mul_f32_e32 v4, v67, v4
	v_mul_f32_e32 v5, v71, v5
	v_mul_f32_e32 v6, v73, v6
	v_mul_f32_e32 v3, v75, v3
	v_cvt_pk_bf16_f32 v4, v4, s0
	v_cvt_pk_bf16_f32 v5, v5, s0
	v_cvt_pk_bf16_f32 v6, v6, s0
	v_cvt_pk_bf16_f32 v3, v3, s0
	ds_write_b16 v76, v4 offset:2176
	ds_write_b16 v76, v5 offset:2240
	ds_write_b16 v76, v6 offset:2304
	ds_write_b16 v76, v3 offset:2368
	ds_read2st64_b32 v[4:5], v79 offset0:10 offset1:11
	v_mov_b32_e32 v54, v7
	v_mov_b32_e32 v22, v39
	v_pk_mul_f32 v[20:21], v[22:23], v[90:91] op_sel_hi:[1,0]
	s_waitcnt lgkmcnt(0)
	v_lshlrev_b32_e32 v6, 16, v4
	v_and_b32_e32 v7, 0xffff0000, v4
	v_lshlrev_b32_e32 v19, 16, v5
	v_and_b32_e32 v18, 0xffff0000, v5
	v_pk_mul_f32 v[4:5], v[54:55], v[90:91] op_sel_hi:[1,0]
	v_pk_fma_f32 v[18:19], v[142:143], v[20:21], v[18:19] neg_lo:[1,0,0] neg_hi:[1,0,0]
	v_pk_fma_f32 v[4:5], v[142:143], v[4:5], v[6:7] neg_lo:[1,0,0] neg_hi:[1,0,0]
	v_pk_mul_f32 v[20:21], v[18:19], v[18:19]
	v_pk_mul_f32 v[6:7], v[4:5], v[4:5]
	s_nop 0
	v_add_f32_e32 v3, v6, v7
	v_add_f32_e32 v3, v3, v21
	v_add_f32_e32 v3, v20, v3
	s_waitcnt lgkmcnt(0)
	s_nop 1
	v_add_f32_dpp v3, v3, v3 quad_perm:[1,0,3,2] row_mask:0xf bank_mask:0xf
	s_waitcnt lgkmcnt(0)
	s_nop 1
	v_add_f32_dpp v3, v3, v3 quad_perm:[2,3,0,1] row_mask:0xf bank_mask:0xf
	s_waitcnt lgkmcnt(0)
	s_nop 1
	v_add_f32_dpp v3, v3, v3 row_half_mirror row_mask:0xf bank_mask:0xf
	s_waitcnt lgkmcnt(0)
	s_nop 1
	v_add_f32_dpp v3, v3, v3 row_mirror row_mask:0xf bank_mask:0xf
	ds_bpermute_b32 v6, v170, v3
	s_waitcnt lgkmcnt(0)
	v_add_f32_e32 v3, v3, v6
	v_fmamk_f32 v3, v3, 0x3c000000, v249
	v_mul_f32_e32 v6, 0x4b800000, v3
	v_cmp_gt_f32_e32 vcc, s5, v3
	s_nop 1
	v_cndmask_b32_e32 v3, v3, v6, vcc
	v_rsq_f32_e32 v3, v3
	s_nop 0
	v_mul_f32_e32 v6, 0x45800000, v3
	v_cndmask_b32_e32 v3, v3, v6, vcc
	v_mul_f32_e32 v4, v4, v3
	v_mul_f32_e32 v5, v5, v3
	v_mul_f32_e32 v6, v19, v3
	v_mul_f32_e32 v3, v18, v3
	v_mul_f32_e32 v4, v67, v4
	v_mul_f32_e32 v5, v71, v5
	v_mul_f32_e32 v6, v73, v6
	v_mul_f32_e32 v3, v75, v3
	v_cvt_pk_bf16_f32 v4, v4, s0
	v_cvt_pk_bf16_f32 v5, v5, s0
	v_cvt_pk_bf16_f32 v6, v6, s0
	v_cvt_pk_bf16_f32 v3, v3, s0
	ds_write_b16 v76, v4 offset:2448
	ds_write_b16 v76, v5 offset:2512
	ds_write_b16 v76, v6 offset:2576
	ds_write_b16 v76, v3 offset:2640
	ds_read2st64_b32 v[4:5], v79 offset0:12 offset1:13
	v_mov_b32_e32 v6, v8
	v_mov_b32_e32 v7, v56
	s_waitcnt lgkmcnt(0)
	v_lshlrev_b32_e32 v18, 16, v4
	v_and_b32_e32 v19, 0xffff0000, v4
	v_lshlrev_b32_e32 v21, 16, v5
	v_and_b32_e32 v20, 0xffff0000, v5
	v_pk_mul_f32 v[4:5], v[6:7], v[88:89] op_sel_hi:[1,0]
	s_nop 0
	v_pk_fma_f32 v[4:5], v[142:143], v[4:5], v[18:19] neg_lo:[1,0,0] neg_hi:[1,0,0]
	v_mov_b32_e32 v18, v40
	v_mov_b32_e32 v19, v24
	v_pk_mul_f32 v[18:19], v[18:19], v[88:89] op_sel_hi:[1,0]
	v_pk_mul_f32 v[6:7], v[4:5], v[4:5]
	v_pk_fma_f32 v[18:19], v[142:143], v[18:19], v[20:21] neg_lo:[1,0,0] neg_hi:[1,0,0]
	v_add_f32_e32 v3, v6, v7
	v_pk_mul_f32 v[20:21], v[18:19], v[18:19]
	s_nop 0
	v_add_f32_e32 v3, v3, v21
	v_add_f32_e32 v3, v20, v3
	s_waitcnt lgkmcnt(0)
	s_nop 1
	v_add_f32_dpp v3, v3, v3 quad_perm:[1,0,3,2] row_mask:0xf bank_mask:0xf
	s_waitcnt lgkmcnt(0)
	s_nop 1
	v_add_f32_dpp v3, v3, v3 quad_perm:[2,3,0,1] row_mask:0xf bank_mask:0xf
	s_waitcnt lgkmcnt(0)
	s_nop 1
	v_add_f32_dpp v3, v3, v3 row_half_mirror row_mask:0xf bank_mask:0xf
	s_waitcnt lgkmcnt(0)
	s_nop 1
	v_add_f32_dpp v3, v3, v3 row_mirror row_mask:0xf bank_mask:0xf
	ds_bpermute_b32 v6, v170, v3
	s_waitcnt lgkmcnt(0)
	v_add_f32_e32 v3, v3, v6
	v_fmamk_f32 v3, v3, 0x3c000000, v249
	v_mul_f32_e32 v6, 0x4b800000, v3
	v_cmp_gt_f32_e32 vcc, s5, v3
	s_nop 1
	v_cndmask_b32_e32 v3, v3, v6, vcc
	v_rsq_f32_e32 v3, v3
	s_nop 0
	v_mul_f32_e32 v6, 0x45800000, v3
	v_cndmask_b32_e32 v3, v3, v6, vcc
	v_mul_f32_e32 v4, v4, v3
	v_mul_f32_e32 v5, v5, v3
	v_mul_f32_e32 v6, v19, v3
	v_mul_f32_e32 v3, v18, v3
	v_mul_f32_e32 v4, v67, v4
	v_mul_f32_e32 v5, v71, v5
	v_mul_f32_e32 v6, v73, v6
	v_mul_f32_e32 v3, v75, v3
	v_cvt_pk_bf16_f32 v4, v4, s0
	v_cvt_pk_bf16_f32 v5, v5, s0
	v_cvt_pk_bf16_f32 v6, v6, s0
	v_cvt_pk_bf16_f32 v3, v3, s0
	ds_write_b16 v76, v4 offset:2720
	ds_write_b16 v76, v5 offset:2784
	ds_write_b16 v76, v6 offset:2848
	ds_write_b16 v76, v3 offset:2912
	ds_read2st64_b32 v[4:5], v79 offset0:14 offset1:15
	v_mov_b32_e32 v56, v9
	v_mov_b32_e32 v24, v41
	v_pk_mul_f32 v[18:19], v[24:25], v[86:87] op_sel_hi:[1,0]
	s_waitcnt lgkmcnt(0)
	v_lshlrev_b32_e32 v6, 16, v4
	v_and_b32_e32 v7, 0xffff0000, v4
	v_lshlrev_b32_e32 v9, 16, v5
	v_and_b32_e32 v8, 0xffff0000, v5
	v_pk_mul_f32 v[4:5], v[56:57], v[86:87] op_sel_hi:[1,0]
	v_pk_fma_f32 v[8:9], v[142:143], v[18:19], v[8:9] neg_lo:[1,0,0] neg_hi:[1,0,0]
	v_pk_fma_f32 v[4:5], v[142:143], v[4:5], v[6:7] neg_lo:[1,0,0] neg_hi:[1,0,0]
	v_pk_mul_f32 v[18:19], v[8:9], v[8:9]
	v_pk_mul_f32 v[6:7], v[4:5], v[4:5]
	s_nop 0
	v_add_f32_e32 v3, v6, v7
	v_add_f32_e32 v3, v3, v19
	v_add_f32_e32 v3, v18, v3
	s_waitcnt lgkmcnt(0)
	s_nop 1
	v_add_f32_dpp v3, v3, v3 quad_perm:[1,0,3,2] row_mask:0xf bank_mask:0xf
	s_waitcnt lgkmcnt(0)
	s_nop 1
	v_add_f32_dpp v3, v3, v3 quad_perm:[2,3,0,1] row_mask:0xf bank_mask:0xf
	s_waitcnt lgkmcnt(0)
	s_nop 1
	v_add_f32_dpp v3, v3, v3 row_half_mirror row_mask:0xf bank_mask:0xf
	s_waitcnt lgkmcnt(0)
	s_nop 1
	v_add_f32_dpp v3, v3, v3 row_mirror row_mask:0xf bank_mask:0xf
	ds_bpermute_b32 v6, v170, v3
	s_waitcnt lgkmcnt(0)
	v_add_f32_e32 v3, v3, v6
	v_fmamk_f32 v3, v3, 0x3c000000, v249
	v_mul_f32_e32 v6, 0x4b800000, v3
	v_cmp_gt_f32_e32 vcc, s5, v3
	s_nop 1
	v_cndmask_b32_e32 v3, v3, v6, vcc
	v_rsq_f32_e32 v3, v3
	s_nop 0
	v_mul_f32_e32 v6, 0x45800000, v3
	v_cndmask_b32_e32 v3, v3, v6, vcc
	v_mul_f32_e32 v4, v4, v3
	v_mul_f32_e32 v5, v5, v3
	v_mul_f32_e32 v6, v9, v3
	v_mul_f32_e32 v3, v8, v3
	v_mul_f32_e32 v4, v67, v4
	v_mul_f32_e32 v5, v71, v5
	v_mul_f32_e32 v6, v73, v6
	v_mul_f32_e32 v3, v75, v3
	v_cvt_pk_bf16_f32 v4, v4, s0
	v_cvt_pk_bf16_f32 v5, v5, s0
	v_cvt_pk_bf16_f32 v6, v6, s0
	v_cvt_pk_bf16_f32 v3, v3, s0
	ds_write_b16 v2, v4 offset:2176
	ds_write_b16 v2, v5 offset:2240
	ds_write_b16 v2, v6 offset:2304
	ds_write_b16 v2, v3 offset:2368
	ds_read2st64_b32 v[4:5], v79 offset0:16 offset1:17
	v_mov_b32_e32 v6, v10
	v_mov_b32_e32 v7, v58
	s_waitcnt lgkmcnt(0)
	v_lshlrev_b32_e32 v8, 16, v4
	v_and_b32_e32 v9, 0xffff0000, v4
	v_lshlrev_b32_e32 v19, 16, v5
	v_and_b32_e32 v18, 0xffff0000, v5
	v_pk_mul_f32 v[4:5], v[6:7], v[84:85] op_sel_hi:[1,0]
	s_nop 0
	v_pk_fma_f32 v[4:5], v[142:143], v[4:5], v[8:9] neg_lo:[1,0,0] neg_hi:[1,0,0]
	v_mov_b32_e32 v8, v42
	v_mov_b32_e32 v9, v26
	v_pk_mul_f32 v[8:9], v[8:9], v[84:85] op_sel_hi:[1,0]
	v_pk_mul_f32 v[6:7], v[4:5], v[4:5]
	v_pk_fma_f32 v[8:9], v[142:143], v[8:9], v[18:19] neg_lo:[1,0,0] neg_hi:[1,0,0]
	v_add_f32_e32 v3, v6, v7
	v_pk_mul_f32 v[18:19], v[8:9], v[8:9]
	s_nop 0
	v_add_f32_e32 v3, v3, v19
	v_add_f32_e32 v3, v18, v3
	s_waitcnt lgkmcnt(0)
	s_nop 1
	v_add_f32_dpp v3, v3, v3 quad_perm:[1,0,3,2] row_mask:0xf bank_mask:0xf
	s_waitcnt lgkmcnt(0)
	s_nop 1
	v_add_f32_dpp v3, v3, v3 quad_perm:[2,3,0,1] row_mask:0xf bank_mask:0xf
	s_waitcnt lgkmcnt(0)
	s_nop 1
	v_add_f32_dpp v3, v3, v3 row_half_mirror row_mask:0xf bank_mask:0xf
	s_waitcnt lgkmcnt(0)
	s_nop 1
	v_add_f32_dpp v3, v3, v3 row_mirror row_mask:0xf bank_mask:0xf
	ds_bpermute_b32 v6, v170, v3
	s_waitcnt lgkmcnt(0)
	v_add_f32_e32 v3, v3, v6
	v_fmamk_f32 v3, v3, 0x3c000000, v249
	v_mul_f32_e32 v6, 0x4b800000, v3
	v_cmp_gt_f32_e32 vcc, s5, v3
	s_nop 1
	v_cndmask_b32_e32 v3, v3, v6, vcc
	v_rsq_f32_e32 v3, v3
	s_nop 0
	v_mul_f32_e32 v6, 0x45800000, v3
	v_cndmask_b32_e32 v3, v3, v6, vcc
	v_mul_f32_e32 v4, v4, v3
	v_mul_f32_e32 v5, v5, v3
	v_mul_f32_e32 v6, v9, v3
	v_mul_f32_e32 v3, v8, v3
	v_mul_f32_e32 v4, v67, v4
	v_mul_f32_e32 v5, v71, v5
	v_mul_f32_e32 v6, v73, v6
	v_mul_f32_e32 v3, v75, v3
	v_cvt_pk_bf16_f32 v4, v4, s0
	v_cvt_pk_bf16_f32 v5, v5, s0
	v_cvt_pk_bf16_f32 v6, v6, s0
	v_cvt_pk_bf16_f32 v3, v3, s0
	ds_write_b16 v76, v4 offset:4352
	ds_write_b16 v76, v5 offset:4416
	ds_write_b16 v76, v6 offset:4480
	ds_write_b16 v76, v3 offset:4544
	ds_read2st64_b32 v[4:5], v79 offset0:18 offset1:19
	v_mov_b32_e32 v58, v11
	v_mov_b32_e32 v26, v43
	v_pk_mul_f32 v[10:11], v[26:27], v[82:83] op_sel_hi:[1,0]
	s_waitcnt lgkmcnt(0)
	v_lshlrev_b32_e32 v6, 16, v4
	v_and_b32_e32 v7, 0xffff0000, v4
	v_lshlrev_b32_e32 v9, 16, v5
	v_and_b32_e32 v8, 0xffff0000, v5
	v_pk_mul_f32 v[4:5], v[58:59], v[82:83] op_sel_hi:[1,0]
	v_pk_fma_f32 v[8:9], v[142:143], v[10:11], v[8:9] neg_lo:[1,0,0] neg_hi:[1,0,0]
	v_pk_fma_f32 v[4:5], v[142:143], v[4:5], v[6:7] neg_lo:[1,0,0] neg_hi:[1,0,0]
	v_pk_mul_f32 v[10:11], v[8:9], v[8:9]
	v_pk_mul_f32 v[6:7], v[4:5], v[4:5]
	s_nop 0
	v_add_f32_e32 v3, v6, v7
	v_add_f32_e32 v3, v3, v11
	v_add_f32_e32 v3, v10, v3
	s_waitcnt lgkmcnt(0)
	s_nop 1
	v_add_f32_dpp v3, v3, v3 quad_perm:[1,0,3,2] row_mask:0xf bank_mask:0xf
	s_waitcnt lgkmcnt(0)
	s_nop 1
	v_add_f32_dpp v3, v3, v3 quad_perm:[2,3,0,1] row_mask:0xf bank_mask:0xf
	s_waitcnt lgkmcnt(0)
	s_nop 1
	v_add_f32_dpp v3, v3, v3 row_half_mirror row_mask:0xf bank_mask:0xf
	s_waitcnt lgkmcnt(0)
	s_nop 1
	v_add_f32_dpp v3, v3, v3 row_mirror row_mask:0xf bank_mask:0xf
	ds_bpermute_b32 v6, v170, v3
	s_waitcnt lgkmcnt(0)
	v_add_f32_e32 v3, v3, v6
	v_fmamk_f32 v3, v3, 0x3c000000, v249
	v_mul_f32_e32 v6, 0x4b800000, v3
	v_cmp_gt_f32_e32 vcc, s5, v3
	s_nop 1
	v_cndmask_b32_e32 v3, v3, v6, vcc
	v_rsq_f32_e32 v3, v3
	s_nop 0
	v_mul_f32_e32 v6, 0x45800000, v3
	v_cndmask_b32_e32 v3, v3, v6, vcc
	v_mul_f32_e32 v4, v4, v3
	v_mul_f32_e32 v5, v5, v3
	v_mul_f32_e32 v6, v9, v3
	v_mul_f32_e32 v3, v8, v3
	v_mul_f32_e32 v4, v67, v4
	v_mul_f32_e32 v5, v71, v5
	v_mul_f32_e32 v6, v73, v6
	v_mul_f32_e32 v3, v75, v3
	v_cvt_pk_bf16_f32 v4, v4, s0
	v_cvt_pk_bf16_f32 v5, v5, s0
	v_cvt_pk_bf16_f32 v6, v6, s0
	v_cvt_pk_bf16_f32 v3, v3, s0
	ds_write_b16 v76, v4 offset:4624
	ds_write_b16 v76, v5 offset:4688
	ds_write_b16 v76, v6 offset:4752
	ds_write_b16 v76, v3 offset:4816
	ds_read2st64_b32 v[4:5], v79 offset0:20 offset1:21
	v_mov_b32_e32 v6, v12
	v_mov_b32_e32 v7, v60
	s_waitcnt lgkmcnt(0)
	v_lshlrev_b32_e32 v8, 16, v4
	v_and_b32_e32 v9, 0xffff0000, v4
	v_lshlrev_b32_e32 v11, 16, v5
	v_and_b32_e32 v10, 0xffff0000, v5
	v_pk_mul_f32 v[4:5], v[6:7], v[74:75] op_sel_hi:[1,0]
	s_nop 0
	v_pk_fma_f32 v[4:5], v[142:143], v[4:5], v[8:9] neg_lo:[1,0,0] neg_hi:[1,0,0]
	v_mov_b32_e32 v8, v44
	v_mov_b32_e32 v9, v28
	v_pk_mul_f32 v[8:9], v[8:9], v[74:75] op_sel_hi:[1,0]
	v_pk_mul_f32 v[6:7], v[4:5], v[4:5]
	v_pk_fma_f32 v[8:9], v[142:143], v[8:9], v[10:11] neg_lo:[1,0,0] neg_hi:[1,0,0]
	v_add_f32_e32 v3, v6, v7
	v_pk_mul_f32 v[10:11], v[8:9], v[8:9]
	s_nop 0
	v_add_f32_e32 v3, v3, v11
	v_add_f32_e32 v3, v10, v3
	s_waitcnt lgkmcnt(0)
	s_nop 1
	v_add_f32_dpp v3, v3, v3 quad_perm:[1,0,3,2] row_mask:0xf bank_mask:0xf
	s_waitcnt lgkmcnt(0)
	s_nop 1
	v_add_f32_dpp v3, v3, v3 quad_perm:[2,3,0,1] row_mask:0xf bank_mask:0xf
	s_waitcnt lgkmcnt(0)
	s_nop 1
	v_add_f32_dpp v3, v3, v3 row_half_mirror row_mask:0xf bank_mask:0xf
	s_waitcnt lgkmcnt(0)
	s_nop 1
	v_add_f32_dpp v3, v3, v3 row_mirror row_mask:0xf bank_mask:0xf
	ds_bpermute_b32 v6, v170, v3
	s_waitcnt lgkmcnt(0)
	v_add_f32_e32 v3, v3, v6
	v_fmamk_f32 v3, v3, 0x3c000000, v249
	v_mul_f32_e32 v6, 0x4b800000, v3
	v_cmp_gt_f32_e32 vcc, s5, v3
	s_nop 1
	v_cndmask_b32_e32 v3, v3, v6, vcc
	v_rsq_f32_e32 v3, v3
	s_nop 0
	v_mul_f32_e32 v6, 0x45800000, v3
	v_cndmask_b32_e32 v3, v3, v6, vcc
	v_mul_f32_e32 v4, v4, v3
	v_mul_f32_e32 v5, v5, v3
	v_mul_f32_e32 v6, v9, v3
	v_mul_f32_e32 v3, v8, v3
	v_mul_f32_e32 v4, v67, v4
	v_mul_f32_e32 v5, v71, v5
	v_mul_f32_e32 v6, v73, v6
	v_mul_f32_e32 v3, v75, v3
	v_cvt_pk_bf16_f32 v4, v4, s0
	v_cvt_pk_bf16_f32 v5, v5, s0
	v_cvt_pk_bf16_f32 v6, v6, s0
	v_cvt_pk_bf16_f32 v3, v3, s0
	ds_write_b16 v76, v4 offset:4896
	ds_write_b16 v76, v5 offset:4960
	ds_write_b16 v76, v6 offset:5024
	ds_write_b16 v76, v3 offset:5088
	ds_read2st64_b32 v[4:5], v79 offset0:22 offset1:23
	v_mov_b32_e32 v60, v13
	v_mov_b32_e32 v28, v45
	v_pk_mul_f32 v[10:11], v[28:29], v[72:73] op_sel_hi:[1,0]
	s_waitcnt lgkmcnt(0)
	v_lshlrev_b32_e32 v6, 16, v4
	v_and_b32_e32 v7, 0xffff0000, v4
	v_lshlrev_b32_e32 v9, 16, v5
	v_and_b32_e32 v8, 0xffff0000, v5
	v_pk_mul_f32 v[4:5], v[60:61], v[72:73] op_sel_hi:[1,0]
	v_pk_fma_f32 v[8:9], v[142:143], v[10:11], v[8:9] neg_lo:[1,0,0] neg_hi:[1,0,0]
	v_pk_fma_f32 v[4:5], v[142:143], v[4:5], v[6:7] neg_lo:[1,0,0] neg_hi:[1,0,0]
	v_pk_mul_f32 v[10:11], v[8:9], v[8:9]
	v_pk_mul_f32 v[6:7], v[4:5], v[4:5]
	s_nop 0
	v_add_f32_e32 v3, v6, v7
	v_add_f32_e32 v3, v3, v11
	v_add_f32_e32 v3, v10, v3
	s_waitcnt lgkmcnt(0)
	s_nop 1
	v_add_f32_dpp v3, v3, v3 quad_perm:[1,0,3,2] row_mask:0xf bank_mask:0xf
	s_waitcnt lgkmcnt(0)
	s_nop 1
	v_add_f32_dpp v3, v3, v3 quad_perm:[2,3,0,1] row_mask:0xf bank_mask:0xf
	s_waitcnt lgkmcnt(0)
	s_nop 1
	v_add_f32_dpp v3, v3, v3 row_half_mirror row_mask:0xf bank_mask:0xf
	s_waitcnt lgkmcnt(0)
	s_nop 1
	v_add_f32_dpp v3, v3, v3 row_mirror row_mask:0xf bank_mask:0xf
	ds_bpermute_b32 v6, v170, v3
	s_waitcnt lgkmcnt(0)
	v_add_f32_e32 v3, v3, v6
	v_fmamk_f32 v3, v3, 0x3c000000, v249
	v_mul_f32_e32 v6, 0x4b800000, v3
	v_cmp_gt_f32_e32 vcc, s5, v3
	s_nop 1
	v_cndmask_b32_e32 v3, v3, v6, vcc
	v_rsq_f32_e32 v3, v3
	s_nop 0
	v_mul_f32_e32 v6, 0x45800000, v3
	v_cndmask_b32_e32 v3, v3, v6, vcc
	v_mul_f32_e32 v4, v4, v3
	v_mul_f32_e32 v5, v5, v3
	v_mul_f32_e32 v6, v9, v3
	v_mul_f32_e32 v3, v8, v3
	v_mul_f32_e32 v4, v67, v4
	v_mul_f32_e32 v5, v71, v5
	v_mul_f32_e32 v6, v73, v6
	v_mul_f32_e32 v3, v75, v3
	v_cvt_pk_bf16_f32 v4, v4, s0
	v_cvt_pk_bf16_f32 v5, v5, s0
	v_cvt_pk_bf16_f32 v6, v6, s0
	v_cvt_pk_bf16_f32 v3, v3, s0
	ds_write_b16 v2, v4 offset:4352
	ds_write_b16 v2, v5 offset:4416
	ds_write_b16 v2, v6 offset:4480
	ds_write_b16 v2, v3 offset:4544
	ds_read2st64_b32 v[4:5], v79 offset0:24 offset1:25
	v_mov_b32_e32 v6, v14
	v_mov_b32_e32 v7, v62
	s_waitcnt lgkmcnt(0)
	v_lshlrev_b32_e32 v8, 16, v4
	v_and_b32_e32 v9, 0xffff0000, v4
	v_lshlrev_b32_e32 v11, 16, v5
	v_and_b32_e32 v10, 0xffff0000, v5
	v_pk_mul_f32 v[4:5], v[6:7], v[70:71] op_sel_hi:[1,0]
	s_nop 0
	v_pk_fma_f32 v[4:5], v[142:143], v[4:5], v[8:9] neg_lo:[1,0,0] neg_hi:[1,0,0]
	v_mov_b32_e32 v8, v46
	v_mov_b32_e32 v9, v30
	v_pk_mul_f32 v[8:9], v[8:9], v[70:71] op_sel_hi:[1,0]
	v_pk_mul_f32 v[6:7], v[4:5], v[4:5]
	v_pk_fma_f32 v[8:9], v[142:143], v[8:9], v[10:11] neg_lo:[1,0,0] neg_hi:[1,0,0]
	v_add_f32_e32 v3, v6, v7
	v_pk_mul_f32 v[10:11], v[8:9], v[8:9]
	s_nop 0
	v_add_f32_e32 v3, v3, v11
	v_add_f32_e32 v3, v10, v3
	s_waitcnt lgkmcnt(0)
	s_nop 1
	v_add_f32_dpp v3, v3, v3 quad_perm:[1,0,3,2] row_mask:0xf bank_mask:0xf
	s_waitcnt lgkmcnt(0)
	s_nop 1
	v_add_f32_dpp v3, v3, v3 quad_perm:[2,3,0,1] row_mask:0xf bank_mask:0xf
	s_waitcnt lgkmcnt(0)
	s_nop 1
	v_add_f32_dpp v3, v3, v3 row_half_mirror row_mask:0xf bank_mask:0xf
	s_waitcnt lgkmcnt(0)
	s_nop 1
	v_add_f32_dpp v3, v3, v3 row_mirror row_mask:0xf bank_mask:0xf
	ds_bpermute_b32 v6, v170, v3
	s_waitcnt lgkmcnt(0)
	v_add_f32_e32 v3, v3, v6
	v_fmamk_f32 v3, v3, 0x3c000000, v249
	v_mul_f32_e32 v6, 0x4b800000, v3
	v_cmp_gt_f32_e32 vcc, s5, v3
	s_nop 1
	v_cndmask_b32_e32 v3, v3, v6, vcc
	v_rsq_f32_e32 v3, v3
	s_nop 0
	v_mul_f32_e32 v6, 0x45800000, v3
	v_cndmask_b32_e32 v3, v3, v6, vcc
	v_mul_f32_e32 v4, v4, v3
	v_mul_f32_e32 v5, v5, v3
	v_mul_f32_e32 v6, v9, v3
	v_mul_f32_e32 v3, v8, v3
	v_mul_f32_e32 v4, v67, v4
	v_mul_f32_e32 v5, v71, v5
	v_mul_f32_e32 v6, v73, v6
	v_mul_f32_e32 v3, v75, v3
	v_cvt_pk_bf16_f32 v4, v4, s0
	v_cvt_pk_bf16_f32 v5, v5, s0
	v_cvt_pk_bf16_f32 v6, v6, s0
	v_cvt_pk_bf16_f32 v3, v3, s0
	ds_write_b16 v76, v4 offset:6528
	ds_write_b16 v76, v5 offset:6592
	ds_write_b16 v76, v6 offset:6656
	ds_write_b16 v76, v3 offset:6720
	ds_read2st64_b32 v[4:5], v79 offset0:26 offset1:27
	v_mov_b32_e32 v62, v15
	v_mov_b32_e32 v30, v47
	v_pk_mul_f32 v[10:11], v[30:31], v[68:69] op_sel_hi:[1,0]
	s_waitcnt lgkmcnt(0)
	v_lshlrev_b32_e32 v6, 16, v4
	v_and_b32_e32 v7, 0xffff0000, v4
	v_lshlrev_b32_e32 v9, 16, v5
	v_and_b32_e32 v8, 0xffff0000, v5
	v_pk_mul_f32 v[4:5], v[62:63], v[68:69] op_sel_hi:[1,0]
	v_pk_fma_f32 v[8:9], v[142:143], v[10:11], v[8:9] neg_lo:[1,0,0] neg_hi:[1,0,0]
	v_pk_fma_f32 v[4:5], v[142:143], v[4:5], v[6:7] neg_lo:[1,0,0] neg_hi:[1,0,0]
	v_pk_mul_f32 v[10:11], v[8:9], v[8:9]
	v_pk_mul_f32 v[6:7], v[4:5], v[4:5]
	s_nop 0
	v_add_f32_e32 v3, v6, v7
	v_add_f32_e32 v3, v3, v11
	v_add_f32_e32 v3, v10, v3
	s_waitcnt lgkmcnt(0)
	s_nop 1
	v_add_f32_dpp v3, v3, v3 quad_perm:[1,0,3,2] row_mask:0xf bank_mask:0xf
	s_waitcnt lgkmcnt(0)
	s_nop 1
	v_add_f32_dpp v3, v3, v3 quad_perm:[2,3,0,1] row_mask:0xf bank_mask:0xf
	s_waitcnt lgkmcnt(0)
	s_nop 1
	v_add_f32_dpp v3, v3, v3 row_half_mirror row_mask:0xf bank_mask:0xf
	s_waitcnt lgkmcnt(0)
	s_nop 1
	v_add_f32_dpp v3, v3, v3 row_mirror row_mask:0xf bank_mask:0xf
	ds_bpermute_b32 v6, v170, v3
	s_waitcnt lgkmcnt(0)
	v_add_f32_e32 v3, v3, v6
	v_fmamk_f32 v3, v3, 0x3c000000, v249
	v_mul_f32_e32 v6, 0x4b800000, v3
	v_cmp_gt_f32_e32 vcc, s5, v3
	s_nop 1
	v_cndmask_b32_e32 v3, v3, v6, vcc
	v_rsq_f32_e32 v3, v3
	s_nop 0
	v_mul_f32_e32 v6, 0x45800000, v3
	v_cndmask_b32_e32 v3, v3, v6, vcc
	v_mul_f32_e32 v4, v4, v3
	v_mul_f32_e32 v5, v5, v3
	v_mul_f32_e32 v6, v9, v3
	v_mul_f32_e32 v3, v8, v3
	v_mul_f32_e32 v4, v67, v4
	v_mul_f32_e32 v5, v71, v5
	v_mul_f32_e32 v6, v73, v6
	v_mul_f32_e32 v3, v75, v3
	v_cvt_pk_bf16_f32 v4, v4, s0
	v_cvt_pk_bf16_f32 v5, v5, s0
	v_cvt_pk_bf16_f32 v6, v6, s0
	v_cvt_pk_bf16_f32 v3, v3, s0
	ds_write_b16 v76, v4 offset:6800
	ds_write_b16 v76, v5 offset:6864
	ds_write_b16 v76, v6 offset:6928
	ds_write_b16 v76, v3 offset:6992
	ds_read2st64_b32 v[4:5], v79 offset0:28 offset1:29
	v_mov_b32_e32 v6, v16
	v_mov_b32_e32 v7, v64
	s_waitcnt lgkmcnt(0)
	v_lshlrev_b32_e32 v8, 16, v4
	v_and_b32_e32 v9, 0xffff0000, v4
	v_lshlrev_b32_e32 v11, 16, v5
	v_and_b32_e32 v10, 0xffff0000, v5
	v_pk_mul_f32 v[4:5], v[6:7], v[66:67] op_sel_hi:[1,0]
	s_nop 0
	v_pk_fma_f32 v[4:5], v[142:143], v[4:5], v[8:9] neg_lo:[1,0,0] neg_hi:[1,0,0]
	v_mov_b32_e32 v8, v48
	v_mov_b32_e32 v9, v32
	v_pk_mul_f32 v[8:9], v[8:9], v[66:67] op_sel_hi:[1,0]
	v_pk_mul_f32 v[6:7], v[4:5], v[4:5]
	v_pk_fma_f32 v[8:9], v[142:143], v[8:9], v[10:11] neg_lo:[1,0,0] neg_hi:[1,0,0]
	v_add_f32_e32 v3, v6, v7
	v_pk_mul_f32 v[10:11], v[8:9], v[8:9]
	s_nop 0
	v_add_f32_e32 v3, v3, v11
	v_add_f32_e32 v3, v10, v3
	s_waitcnt lgkmcnt(0)
	s_nop 1
	v_add_f32_dpp v3, v3, v3 quad_perm:[1,0,3,2] row_mask:0xf bank_mask:0xf
	s_waitcnt lgkmcnt(0)
	s_nop 1
	v_add_f32_dpp v3, v3, v3 quad_perm:[2,3,0,1] row_mask:0xf bank_mask:0xf
	s_waitcnt lgkmcnt(0)
	s_nop 1
	v_add_f32_dpp v3, v3, v3 row_half_mirror row_mask:0xf bank_mask:0xf
	s_waitcnt lgkmcnt(0)
	s_nop 1
	v_add_f32_dpp v3, v3, v3 row_mirror row_mask:0xf bank_mask:0xf
	ds_bpermute_b32 v6, v170, v3
	s_waitcnt lgkmcnt(0)
	v_add_f32_e32 v3, v3, v6
	v_fmamk_f32 v3, v3, 0x3c000000, v249
	v_mul_f32_e32 v6, 0x4b800000, v3
	v_cmp_gt_f32_e32 vcc, s5, v3
	s_nop 1
	v_cndmask_b32_e32 v3, v3, v6, vcc
	v_rsq_f32_e32 v3, v3
	s_nop 0
	v_mul_f32_e32 v6, 0x45800000, v3
	v_cndmask_b32_e32 v3, v3, v6, vcc
	v_mul_f32_e32 v4, v4, v3
	v_mul_f32_e32 v5, v5, v3
	v_mul_f32_e32 v6, v9, v3
	v_mul_f32_e32 v3, v8, v3
	v_mul_f32_e32 v4, v67, v4
	v_mul_f32_e32 v5, v71, v5
	v_mul_f32_e32 v6, v73, v6
	v_mul_f32_e32 v3, v75, v3
	v_cvt_pk_bf16_f32 v4, v4, s0
	v_cvt_pk_bf16_f32 v5, v5, s0
	v_cvt_pk_bf16_f32 v6, v6, s0
	v_cvt_pk_bf16_f32 v3, v3, s0
	ds_write_b16 v76, v4 offset:7072
	ds_write_b16 v76, v5 offset:7136
	ds_write_b16 v76, v6 offset:7200
	ds_write_b16 v76, v3 offset:7264
	ds_read2st64_b32 v[4:5], v79 offset0:30 offset1:31
	v_mov_b32_e32 v64, v17
	v_mov_b32_e32 v32, v49
	v_pk_mul_f32 v[10:11], v[32:33], v[0:1] op_sel_hi:[1,0]
	s_waitcnt lgkmcnt(0)
	v_lshlrev_b32_e32 v6, 16, v4
	v_and_b32_e32 v7, 0xffff0000, v4
	v_lshlrev_b32_e32 v9, 16, v5
	v_and_b32_e32 v8, 0xffff0000, v5
	v_pk_mul_f32 v[4:5], v[64:65], v[0:1] op_sel_hi:[1,0]
	v_pk_fma_f32 v[8:9], v[142:143], v[10:11], v[8:9] neg_lo:[1,0,0] neg_hi:[1,0,0]
	v_pk_fma_f32 v[4:5], v[142:143], v[4:5], v[6:7] neg_lo:[1,0,0] neg_hi:[1,0,0]
	v_pk_mul_f32 v[10:11], v[8:9], v[8:9]
	v_pk_mul_f32 v[6:7], v[4:5], v[4:5]
	s_nop 0
	v_add_f32_e32 v0, v6, v7
	v_add_f32_e32 v0, v0, v11
	v_add_f32_e32 v0, v10, v0
	s_waitcnt lgkmcnt(0)
	s_nop 1
	v_add_f32_dpp v0, v0, v0 quad_perm:[1,0,3,2] row_mask:0xf bank_mask:0xf
	s_waitcnt lgkmcnt(0)
	s_nop 1
	v_add_f32_dpp v0, v0, v0 quad_perm:[2,3,0,1] row_mask:0xf bank_mask:0xf
	s_waitcnt lgkmcnt(0)
	s_nop 1
	v_add_f32_dpp v0, v0, v0 row_half_mirror row_mask:0xf bank_mask:0xf
	s_waitcnt lgkmcnt(0)
	s_nop 1
	v_add_f32_dpp v0, v0, v0 row_mirror row_mask:0xf bank_mask:0xf
	ds_bpermute_b32 v3, v170, v0
	s_waitcnt lgkmcnt(0)
	v_add_f32_e32 v0, v0, v3
	v_fmamk_f32 v0, v0, 0x3c000000, v249
	v_mul_f32_e32 v3, 0x4b800000, v0
	v_cmp_gt_f32_e32 vcc, s5, v0
	s_nop 1
	v_cndmask_b32_e32 v0, v0, v3, vcc
	v_rsq_f32_e32 v0, v0
	s_nop 0
	v_mul_f32_e32 v3, 0x45800000, v0
	v_cndmask_b32_e32 v0, v0, v3, vcc
	v_mul_f32_e32 v3, v4, v0
	v_mul_f32_e32 v4, v5, v0
	v_mul_f32_e32 v5, v9, v0
	v_mul_f32_e32 v0, v8, v0
	v_mul_f32_e32 v3, v67, v3
	v_mul_f32_e32 v4, v71, v4
	v_mul_f32_e32 v5, v73, v5
	v_mul_f32_e32 v0, v75, v0
	v_cvt_pk_bf16_f32 v3, v3, s0
	v_cvt_pk_bf16_f32 v4, v4, s0
	v_cvt_pk_bf16_f32 v5, v5, s0
	v_cvt_pk_bf16_f32 v0, v0, s0
	ds_write_b16 v2, v3 offset:6528
	ds_write_b16 v2, v4 offset:6592
	ds_write_b16 v2, v5 offset:6656
	ds_write_b16 v2, v0 offset:6720
	s_lshl_b32 s60, s70, 12
	s_add_i32 s22, s1, s60
	s_ashr_i32 s23, s22, 31
	s_lshl_b64 s[22:23], s[22:23], 11
	s_add_u32 s1, s41, s22
	s_addc_u32 s5, s66, s23
	s_lshl_b32 s61, s71, 1
	s_add_u32 s22, s1, s61
	v_ashrrev_i32_e32 v6, 4, v162
	v_lshlrev_b32_e32 v0, 4, v162
	s_addc_u32 s23, s5, 0
	v_and_b32_e32 v0, 0xf0, v0
	v_mul_lo_u32 v2, v6, s77
	s_waitcnt lgkmcnt(0)
	v_lshl_add_u64 v[8:9], s[22:23], 0, v[0:1]
	v_add3_u32 v0, v69, v0, v2
	ds_read_b128 v[2:5], v0
	v_ashrrev_i32_e32 v7, 31, v6
	v_lshlrev_b64 v[6:7], 11, v[6:7]
	v_lshl_add_u64 v[10:11], v[8:9], 0, v[6:7]
	ds_read_b128 v[6:9], v0 offset:1088
	s_waitcnt lgkmcnt(1)
	global_store_dwordx4 v[10:11], v[2:5], off
	v_mov_b32_e32 v172, v226
	s_movk_i32 s26, 0x1800
	v_add_co_u32_e32 v2, vcc, s88, v10
	v_mov_b32_e32 v145, v1
	s_nop 0
	v_addc_co_u32_e32 v3, vcc, 0, v11, vcc
	s_waitcnt lgkmcnt(0)
	global_store_dwordx4 v[2:3], v[6:9], off
	ds_read_b128 v[2:5], v0 offset:2176
	ds_read_b128 v[6:9], v0 offset:3264
	v_add_co_u32_e32 v12, vcc, s14, v10
	v_readlane_b32 s1, v251, 7
	s_nop 0
	v_addc_co_u32_e32 v13, vcc, 0, v11, vcc
	s_waitcnt lgkmcnt(1)
	global_store_dwordx4 v[12:13], v[2:5], off
	s_add_i32 s1, s11, s1
	v_mov_b32_e32 v16, v1
	v_add_co_u32_e32 v2, vcc, s89, v10
	v_mov_b32_e32 v17, v1
	s_nop 0
	v_addc_co_u32_e32 v3, vcc, 0, v11, vcc
	s_waitcnt lgkmcnt(0)
	global_store_dwordx4 v[2:3], v[6:9], off
	ds_read_b128 v[2:5], v0 offset:4352
	ds_read_b128 v[6:9], v0 offset:5440
	v_add_co_u32_e32 v12, vcc, s81, v10
	s_add_i32 s5, s11, 0x100
	s_nop 0
	v_addc_co_u32_e32 v13, vcc, 0, v11, vcc
	s_waitcnt lgkmcnt(1)
	global_store_dwordx4 v[12:13], v[2:5], off
	v_mov_b32_e32 v14, v1
	v_mov_b32_e32 v15, v1
	v_add_co_u32_e32 v2, vcc, s20, v10
	s_lshr_b32 s5, s5, 6
	s_nop 0
	v_addc_co_u32_e32 v3, vcc, 0, v11, vcc
	s_waitcnt lgkmcnt(0)
	global_store_dwordx4 v[2:3], v[6:9], off
	ds_read_b128 v[2:5], v0 offset:6528
	ds_read_b128 v[6:9], v0 offset:7616
	v_add_co_u32_e32 v12, vcc, s18, v10
	s_or_b32 s11, s1, 31
	s_nop 0
	v_addc_co_u32_e32 v13, vcc, 0, v11, vcc
	s_waitcnt lgkmcnt(1)
	global_store_dwordx4 v[12:13], v[2:5], off
	v_mov_b32_e32 v12, v1
	v_mov_b32_e32 v13, v1
	v_add_co_u32_e32 v2, vcc, s3, v10
	s_nop 0
	v_addc_co_u32_e32 v3, vcc, 0, v11, vcc
	s_waitcnt lgkmcnt(0)
	global_store_dwordx4 v[2:3], v[6:9], off
	s_barrier
	s_nop 0
	v_mov_b32_e32 v6, v227
	v_mov_b64_e32 v[2:3], s[48:49]
	v_ashrrev_i32_e32 v8, 3, v6
	v_lshlrev_b32_e32 v7, 4, v6
	v_mad_i64_i32 v[4:5], s[22:23], v8, s26, v[2:3]
	v_and_b32_e32 v0, 0x70, v7
	v_and_b32_e32 v144, 0xf0, v7
	v_add_u32_e32 v7, 0x200, v6
	v_lshl_add_u64 v[150:151], v[4:5], 0, v[0:1]
	v_lshl_add_u64 v[4:5], s[30:31], 0, v[144:145]
	v_ashrrev_i32_e32 v9, 4, v6
	v_ashrrev_i32_e32 v7, 4, v7
	v_and_b32_e32 v145, 31, v172
	v_ashrrev_i32_e32 v10, 5, v172
	v_mad_i64_i32 v[152:153], s[22:23], v9, s26, v[4:5]
	v_mad_i64_i32 v[154:155], s[22:23], v7, s26, v[4:5]
	v_or_b32_e32 v173, s1, v145
	v_lshlrev_b32_e32 v4, 3, v10
	v_mad_u64_u32 v[2:3], s[30:31], v173, s26, v[2:3]
	v_ashrrev_i32_e32 v5, 31, v4
	v_lshl_add_u64 v[156:157], v[4:5], 1, v[2:3]
	global_load_dwordx4 v[114:117], v[150:151], off offset:2048
	global_load_dwordx4 v[118:121], v[152:153], off
	global_load_dwordx4 v[122:125], v[154:155], off
	global_load_dwordx4 v[126:129], v[156:157], off
	global_load_dwordx4 v[130:133], v[156:157], off offset:32
	global_load_dwordx4 v[134:137], v[156:157], off offset:64
	global_load_dwordx4 v[138:141], v[156:157], off offset:96
	v_mul_lo_u32 v174, v8, s96
	v_add_u32_e32 v2, 0, v174
	v_add_u32_e32 v238, v2, v0
	v_add_u32_e32 v2, 0, v144
	s_movk_i32 s78, 0x140
	v_mul_lo_u32 v175, v9, s78
	s_movk_i32 s78, 0x140
	v_mul_lo_u32 v176, v7, s78
	v_lshlrev_b32_e32 v241, 2, v172
	v_add_u32_e32 v239, v2, v175
	v_add_u32_e32 v240, v2, v176
	v_and_b32_e32 v2, 16, v172
	v_lshrrev_b32_e32 v3, 2, v172
	v_lshlrev_b32_e32 v179, 2, v10
	v_and_or_b32 v3, v3, 3, v179
	v_and_or_b32 v2, v241, 12, v2
	v_lshlrev_b32_e32 v181, 1, v2
	s_movk_i32 s78, 0x140
	v_mul_lo_u32 v182, v3, s78
	v_mov_b64_e32 v[2:3], s[28:29]
	v_and_b32_e32 v6, 15, v6
	v_mad_i64_i32 v[4:5], s[28:29], v7, s26, v[2:3]
	v_lshlrev_b32_e32 v6, 4, v6
	v_mov_b32_e32 v7, v1
	v_lshl_add_u64 v[4:5], v[4:5], 0, v[6:7]
	v_lshl_add_u64 v[146:147], s[16:17], 0, v[4:5]
	v_mad_i64_i32 v[4:5], s[28:29], v9, s26, v[2:3]
	v_lshl_add_u64 v[4:5], v[4:5], 0, v[6:7]
	v_mad_i64_i32 v[2:3], s[28:29], v8, s26, v[2:3]
	v_lshlrev_b32_e32 v178, 4, v10
	v_lshl_add_u64 v[148:149], s[16:17], 0, v[4:5]
	v_lshl_add_u64 v[158:159], v[2:3], 0, v[0:1]
	v_mov_b32_e32 v2, v1
	v_mov_b32_e32 v3, v1
	v_mov_b32_e32 v4, v1
	v_mov_b32_e32 v5, v1
	v_mov_b32_e32 v6, v1
	v_mov_b32_e32 v8, v1
	v_mov_b32_e32 v9, v1
	v_mov_b32_e32 v10, v1
	v_mov_b32_e32 v11, v1
	v_mov_b64_e32 v[64:65], v[16:17]
	v_mov_b64_e32 v[48:49], v[16:17]
	v_mov_b64_e32 v[32:33], v[16:17]
	v_mov_b64_e32 v[80:81], v[16:17]
	s_mov_b32 s22, 0
	v_mul_u32_u24_e32 v177, 0x90, v145
	v_cmp_gt_u32_e64 s[42:43], 32, v172
	v_lshl_add_u32 v180, v145, 2, s91
	v_subrev_u32_e32 v183, 32, v173
	v_subrev_u32_e32 v184, 33, v173
	v_subrev_u32_e32 v185, 34, v173
	v_subrev_u32_e32 v186, 35, v173
	v_add_u32_e32 v187, -8, v173
	v_subrev_u32_e32 v188, 40, v173
	v_add_u32_e32 v189, -9, v173
	v_subrev_u32_e32 v195, 41, v173
	v_add_u32_e32 v196, -10, v173
	v_subrev_u32_e32 v197, 42, v173
	v_add_u32_e32 v198, -11, v173
	v_subrev_u32_e32 v199, 43, v173
	v_add_u32_e32 v200, -16, v173
	v_subrev_u32_e32 v201, 48, v173
	v_subrev_u32_e32 v202, 17, v173
	v_subrev_u32_e32 v203, 49, v173
	v_subrev_u32_e32 v204, 18, v173
	v_subrev_u32_e32 v205, 50, v173
	v_subrev_u32_e32 v228, 19, v173
	v_subrev_u32_e32 v229, 51, v173
	v_subrev_u32_e32 v230, 24, v173
	v_subrev_u32_e32 v231, 56, v173
	v_subrev_u32_e32 v232, 25, v173
	v_subrev_u32_e32 v233, 57, v173
	v_subrev_u32_e32 v234, 26, v173
	v_subrev_u32_e32 v235, 58, v173
	v_subrev_u32_e32 v236, 27, v173
	v_subrev_u32_e32 v237, 59, v173
	v_lshl_add_u64 v[160:161], s[44:45], 0, v[158:159]
	v_mov_b64_e32 v[162:163], v[148:149]
	v_mov_b64_e32 v[164:165], v[146:147]
	v_mov_b64_e32 v[62:63], v[14:15]
	v_mov_b64_e32 v[60:61], v[12:13]
	v_mov_b64_e32 v[58:59], v[10:11]
	v_mov_b64_e32 v[56:57], v[8:9]
	v_mov_b64_e32 v[54:55], v[6:7]
	v_mov_b64_e32 v[52:53], v[4:5]
	v_mov_b64_e32 v[50:51], v[2:3]
	v_mov_b64_e32 v[46:47], v[14:15]
	v_mov_b64_e32 v[44:45], v[12:13]
	v_mov_b64_e32 v[42:43], v[10:11]
	v_mov_b64_e32 v[40:41], v[8:9]
	v_mov_b64_e32 v[38:39], v[6:7]
	v_mov_b64_e32 v[36:37], v[4:5]
	v_mov_b64_e32 v[34:35], v[2:3]
	v_mov_b64_e32 v[30:31], v[14:15]
	v_mov_b64_e32 v[28:29], v[12:13]
	v_mov_b64_e32 v[26:27], v[10:11]
	v_mov_b64_e32 v[24:25], v[8:9]
	v_mov_b64_e32 v[22:23], v[6:7]
	v_mov_b64_e32 v[20:21], v[4:5]
	v_mov_b64_e32 v[18:19], v[2:3]
	v_mov_b64_e32 v[78:79], v[14:15]
	v_mov_b64_e32 v[76:77], v[12:13]
	v_mov_b64_e32 v[74:75], v[10:11]
	v_mov_b64_e32 v[72:73], v[8:9]
	v_mov_b64_e32 v[70:71], v[6:7]
	v_mov_b64_e32 v[68:69], v[4:5]
	v_mov_b64_e32 v[66:67], v[2:3]
	s_waitcnt vmcnt(6)
	ds_write_b128 v238, v[114:117]
	s_waitcnt vmcnt(5)
	ds_write_b128 v239, v[118:121] offset:9216
	s_waitcnt vmcnt(4)
	ds_write_b128 v240, v[122:125] offset:9216
	s_waitcnt vmcnt(0) lgkmcnt(0)
	s_barrier
	v_mov_b32_e32 v243, 0
	s_mov_b32 s79, 1
	s_cmp_lt_u32 s4, s5
	s_cselect_b64 s[28:29], -1, 0
	s_cmp_ge_u32 s4, s5
	s_cbranch_scc1 .LBB0_66

.LBB0_66:
	s_add_i32 s23, s4, -1
	s_and_b32 s23, s23, 1
	s_cmp_gt_u32 s22, s11
	s_cbranch_scc1 .LBB0_73
	s_mul_i32 s26, s23, 0x7400
	s_add_i32 s26, s26, 0
	s_add_i32 s30, s22, 63
	s_cmp_le_u32 s30, s1
	v_add3_u32 v206, s26, v177, v178
	ds_read_b128 v[98:101], v206
	ds_read_b128 v[102:105], v206 offset:32
	ds_read_b128 v[106:109], v206 offset:64
	ds_read_b128 v[110:113], v206 offset:96
	ds_read_b128 v[190:193], v206 offset:4608
	ds_read_b128 v[214:217], v206 offset:4640
	ds_read_b128 v[244:247], v206 offset:4672
	ds_read_b128 v[206:209], v206 offset:4704
	s_setprio 1
	s_waitcnt lgkmcnt(7)
	v_mfma_f32_32x32x16_bf16 v[82:97], v[98:101], v[126:129], v[66:81]
	s_waitcnt lgkmcnt(6)
	v_mfma_f32_32x32x16_bf16 v[82:97], v[102:105], v[130:133], v[82:97]
	s_waitcnt lgkmcnt(5)
	v_mfma_f32_32x32x16_bf16 v[82:97], v[106:109], v[134:137], v[82:97]
	s_waitcnt lgkmcnt(4)
	v_mfma_f32_32x32x16_bf16 v[82:97], v[110:113], v[138:141], v[82:97]
	s_waitcnt lgkmcnt(3)
	v_mfma_f32_32x32x16_bf16 v[98:113], v[190:193], v[126:129], v[66:81]
	s_waitcnt lgkmcnt(2)
	v_mfma_f32_32x32x16_bf16 v[98:113], v[214:217], v[130:133], v[98:113]
	s_waitcnt lgkmcnt(1)
	v_mfma_f32_32x32x16_bf16 v[98:113], v[244:247], v[134:137], v[98:113]
	s_waitcnt lgkmcnt(0)
	v_mfma_f32_32x32x16_bf16 v[98:113], v[206:209], v[138:141], v[98:113]
	s_setprio 0
	s_cbranch_scc1 .LBB0_69
	v_add_u32_e32 v190, s22, v179
	v_cmp_le_i32_e32 vcc, v190, v183
	v_add_u32_e32 v191, 2, v190
	s_nop 7
	v_cndmask_b32_e32 v98, v220, v98, vcc
	v_cmp_lt_i32_e32 vcc, v190, v173
	s_nop 1
	v_cndmask_b32_e32 v83, v220, v83, vcc
	v_cmp_le_i32_e32 vcc, v190, v173
	s_nop 1
	v_cndmask_b32_e32 v82, v220, v82, vcc
	v_cmp_le_i32_e32 vcc, v190, v184
	s_nop 1
	v_cndmask_b32_e32 v99, v220, v99, vcc
	v_cmp_le_i32_e32 vcc, v191, v173
	v_add_u32_e32 v191, 3, v190
	s_nop 0
	v_cndmask_b32_e32 v84, v220, v84, vcc
	v_cmp_le_i32_e32 vcc, v190, v185
	s_nop 1
	v_cndmask_b32_e32 v100, v220, v100, vcc
	v_cmp_le_i32_e32 vcc, v191, v173
	s_nop 1
	v_cndmask_b32_e32 v85, v220, v85, vcc
	v_cmp_le_i32_e32 vcc, v190, v186
	s_nop 1
	v_cndmask_b32_e32 v101, v220, v101, vcc
	v_cmp_le_i32_e32 vcc, v190, v187
	s_nop 1
	v_cndmask_b32_e32 v86, v220, v86, vcc
	v_cmp_le_i32_e32 vcc, v190, v188
	s_nop 1
	v_cndmask_b32_e32 v102, v220, v102, vcc
	v_cmp_le_i32_e32 vcc, v190, v189
	s_nop 1
	v_cndmask_b32_e32 v87, v220, v87, vcc
	v_cmp_le_i32_e32 vcc, v190, v195
	s_nop 1
	v_cndmask_b32_e32 v103, v220, v103, vcc
	v_cmp_le_i32_e32 vcc, v190, v196
	s_nop 1
	v_cndmask_b32_e32 v88, v220, v88, vcc
	v_cmp_le_i32_e32 vcc, v190, v197
	s_nop 1
	v_cndmask_b32_e32 v104, v220, v104, vcc
	v_cmp_le_i32_e32 vcc, v190, v198
	s_nop 1
	v_cndmask_b32_e32 v89, v220, v89, vcc
	v_cmp_le_i32_e32 vcc, v190, v199
	s_nop 1
	v_cndmask_b32_e32 v105, v220, v105, vcc
	v_cmp_le_i32_e32 vcc, v190, v200
	s_nop 1
	v_cndmask_b32_e32 v90, v220, v90, vcc
	v_cmp_le_i32_e32 vcc, v190, v201
	s_nop 1
	v_cndmask_b32_e32 v106, v220, v106, vcc
	v_cmp_le_i32_e32 vcc, v190, v202
	s_nop 1
	v_cndmask_b32_e32 v91, v220, v91, vcc
	v_cmp_le_i32_e32 vcc, v190, v203
	s_nop 1
	v_cndmask_b32_e32 v107, v220, v107, vcc
	v_cmp_le_i32_e32 vcc, v190, v204
	s_nop 1
	v_cndmask_b32_e32 v92, v220, v92, vcc
	v_cmp_le_i32_e32 vcc, v190, v205
	s_nop 1
	v_cndmask_b32_e32 v108, v220, v108, vcc
	v_cmp_le_i32_e32 vcc, v190, v228
	s_nop 1
	v_cndmask_b32_e32 v93, v220, v93, vcc
	v_cmp_le_i32_e32 vcc, v190, v229
	s_nop 1
	v_cndmask_b32_e32 v109, v220, v109, vcc
	v_cmp_le_i32_e32 vcc, v190, v230
	s_nop 1
	v_cndmask_b32_e32 v94, v220, v94, vcc
	v_cmp_le_i32_e32 vcc, v190, v231
	s_nop 1
	v_cndmask_b32_e32 v110, v220, v110, vcc
	v_cmp_le_i32_e32 vcc, v190, v232
	s_nop 1
	v_cndmask_b32_e32 v95, v220, v95, vcc
	v_cmp_le_i32_e32 vcc, v190, v233
	s_nop 1
	v_cndmask_b32_e32 v111, v220, v111, vcc
	v_cmp_le_i32_e32 vcc, v190, v234
	s_nop 1
	v_cndmask_b32_e32 v96, v220, v96, vcc
	v_cmp_le_i32_e32 vcc, v190, v235
	s_nop 1
	v_cndmask_b32_e32 v112, v220, v112, vcc
	v_cmp_le_i32_e32 vcc, v190, v236
	s_nop 1
	v_cndmask_b32_e32 v97, v220, v97, vcc
	v_cmp_le_i32_e32 vcc, v190, v237
	s_nop 1
	v_cndmask_b32_e32 v113, v220, v113, vcc
.LBB0_69:
	s_nop 10
	v_max3_f32 v190, v82, v83, v84
	v_max3_f32 v191, v98, v99, v100
	v_max3_f32 v192, v90, v91, v92
	v_max3_f32 v193, v106, v107, v108
	v_max3_f32 v190, v190, v85, v86
	v_max3_f32 v191, v191, v101, v102
	v_max3_f32 v192, v192, v93, v94
	v_max3_f32 v193, v193, v109, v110
	v_max3_f32 v190, v190, v87, v88
	v_max3_f32 v191, v191, v103, v104
	v_max3_f32 v192, v192, v95, v96
	v_max3_f32 v193, v193, v111, v112
	v_max3_f32 v190, v190, v89, v105
	v_max3_f32 v192, v192, v97, v113
	v_max3_f32 v190, v190, v191, v192
	v_max_f32_e32 v190, v190, v193
	v_mov_b32_e32 v191, v190
	s_nop 1
	v_permlane32_swap_b32_e32 v190, v191
	v_max_f32_e32 v242, v190, v191
	s_cmp_lg_u32 s79, 0
	s_cbranch_scc1 .Lfo_first_c3
	v_cmp_lt_f32_e32 vcc, 0x41000000, v242
	s_cbranch_vccz .LBB0_74
	v_max_f32_e32 v242, 0, v242
	v_mov_b32_e32 v191, v242
	s_branch .Lfo_resc_c3
.Lfo_first_c3:
	s_mov_b32 s79, 0
	v_max_f32_e32 v191, 0, v242
.Lfo_resc_c3:
	v_exp_f32_e64 v191, -v191
	v_sub_f32_e32 v66, v66, v242
	v_sub_f32_e32 v82, v82, v242
	v_sub_f32_e32 v83, v83, v242
	v_sub_f32_e32 v84, v84, v242
	v_sub_f32_e32 v85, v85, v242
	v_sub_f32_e32 v86, v86, v242
	v_sub_f32_e32 v87, v87, v242
	v_sub_f32_e32 v88, v88, v242
	v_sub_f32_e32 v89, v89, v242
	v_sub_f32_e32 v90, v90, v242
	v_sub_f32_e32 v91, v91, v242
	v_sub_f32_e32 v92, v92, v242
	v_sub_f32_e32 v93, v93, v242
	v_sub_f32_e32 v94, v94, v242
	v_sub_f32_e32 v95, v95, v242
	v_sub_f32_e32 v96, v96, v242
	v_sub_f32_e32 v97, v97, v242
	v_sub_f32_e32 v98, v98, v242
	v_sub_f32_e32 v99, v99, v242
	v_sub_f32_e32 v100, v100, v242
	v_sub_f32_e32 v101, v101, v242
	v_sub_f32_e32 v102, v102, v242
	v_sub_f32_e32 v103, v103, v242
	v_sub_f32_e32 v104, v104, v242
	v_sub_f32_e32 v105, v105, v242
	v_sub_f32_e32 v106, v106, v242
	v_sub_f32_e32 v107, v107, v242
	v_sub_f32_e32 v108, v108, v242
	v_sub_f32_e32 v109, v109, v242
	v_sub_f32_e32 v110, v110, v242
	v_sub_f32_e32 v111, v111, v242
	v_sub_f32_e32 v112, v112, v242
	v_sub_f32_e32 v113, v113, v242
	v_mov_b32_e32 v67, v66
	v_mov_b32_e32 v68, v66
	v_mov_b32_e32 v69, v66
	v_mov_b32_e32 v70, v66
	v_mov_b32_e32 v71, v66
	v_mov_b32_e32 v72, v66
	v_mov_b32_e32 v73, v66
	v_mov_b32_e32 v74, v66
	v_mov_b32_e32 v75, v66
	v_mov_b32_e32 v76, v66
	v_mov_b32_e32 v77, v66
	v_mov_b32_e32 v78, v66
	v_mov_b32_e32 v79, v66
	v_mov_b32_e32 v80, v66
	v_mov_b32_e32 v81, v66
	v_mul_f32_e32 v243, v243, v191
	s_and_saveexec_b64 s[30:31], s[42:43]
	s_cbranch_execz .LBB0_72
	ds_write_b32 v180, v191 offset:59392
.LBB0_72:
	s_or_b64 exec, exec, s[30:31]
	v_add_u32_e32 v206, s91, v178
	ds_read_b128 v[190:193], v206 offset:59488
	ds_read_b128 v[214:217], v206 offset:59456
	ds_read_b128 v[244:247], v206 offset:59424
	ds_read_b128 v[206:209], v206 offset:59392
	s_waitcnt lgkmcnt(3)
	v_pk_mul_f32 v[14:15], v[14:15], v[190:191]
	s_waitcnt lgkmcnt(2)
	v_pk_mul_f32 v[10:11], v[10:11], v[214:215]
	s_waitcnt lgkmcnt(1)
	v_pk_mul_f32 v[6:7], v[6:7], v[244:245]
	v_pk_mul_f32 v[16:17], v[16:17], v[192:193]
	v_pk_mul_f32 v[12:13], v[12:13], v[216:217]
	v_pk_mul_f32 v[8:9], v[8:9], v[246:247]
	s_waitcnt lgkmcnt(0)
	v_pk_mul_f32 v[4:5], v[4:5], v[208:209]
	v_pk_mul_f32 v[2:3], v[2:3], v[206:207]
	v_pk_mul_f32 v[62:63], v[62:63], v[190:191]
	v_pk_mul_f32 v[58:59], v[58:59], v[214:215]
	v_pk_mul_f32 v[54:55], v[54:55], v[244:245]
	v_pk_mul_f32 v[64:65], v[64:65], v[192:193]
	v_pk_mul_f32 v[60:61], v[60:61], v[216:217]
	v_pk_mul_f32 v[56:57], v[56:57], v[246:247]
	v_pk_mul_f32 v[52:53], v[52:53], v[208:209]
	v_pk_mul_f32 v[50:51], v[50:51], v[206:207]
	v_pk_mul_f32 v[46:47], v[46:47], v[190:191]
	v_pk_mul_f32 v[42:43], v[42:43], v[214:215]
	v_pk_mul_f32 v[38:39], v[38:39], v[244:245]
	v_pk_mul_f32 v[48:49], v[48:49], v[192:193]
	v_pk_mul_f32 v[44:45], v[44:45], v[216:217]
	v_pk_mul_f32 v[40:41], v[40:41], v[246:247]
	v_pk_mul_f32 v[36:37], v[36:37], v[208:209]
	v_pk_mul_f32 v[34:35], v[34:35], v[206:207]
	v_pk_mul_f32 v[30:31], v[30:31], v[190:191]
	v_pk_mul_f32 v[26:27], v[26:27], v[214:215]
	v_pk_mul_f32 v[22:23], v[22:23], v[244:245]
	v_pk_mul_f32 v[32:33], v[32:33], v[192:193]
	v_pk_mul_f32 v[28:29], v[28:29], v[216:217]
	v_pk_mul_f32 v[24:25], v[24:25], v[246:247]
	v_pk_mul_f32 v[20:21], v[20:21], v[208:209]
	v_pk_mul_f32 v[18:19], v[18:19], v[206:207]
	s_branch .LBB0_75
.LBB0_73:
	s_andn2_b64 vcc, exec, s[28:29]
	s_cbranch_vccz .LBB0_76
	s_branch .LBB0_77
.LBB0_74:
.LBB0_75:
	v_add3_u32 v190, s26, v182, v181
	ds_read_b64_tr_b16 v[214:215], v190 offset:9216
	ds_read_b64_tr_b16 v[216:217], v190 offset:11776
	ds_read_b64_tr_b16 v[244:245], v190 offset:9280
	ds_read_b64_tr_b16 v[246:247], v190 offset:11840
	ds_read_b64_tr_b16 v[206:207], v190 offset:9344
	ds_read_b64_tr_b16 v[208:209], v190 offset:11904
	v_exp_f32_e32 v82, v82
	v_exp_f32_e32 v83, v83
	v_exp_f32_e32 v84, v84
	v_exp_f32_e32 v85, v85
	v_exp_f32_e32 v86, v86
	v_exp_f32_e32 v87, v87
	v_exp_f32_e32 v88, v88
	v_exp_f32_e32 v89, v89
	v_add_f32_e32 v242, v82, v83
	v_add_f32_e32 v243, v243, v84
	v_add_f32_e32 v242, v242, v85
	v_cvt_pk_bf16_f32 v82, v82, v83
	v_cvt_pk_bf16_f32 v83, v84, v85
	v_cvt_pk_bf16_f32 v84, v86, v87
	v_cvt_pk_bf16_f32 v85, v88, v89
	s_setprio 1
	s_waitcnt lgkmcnt(4)
	v_mfma_f32_32x32x16_bf16 v[2:17], v[82:85], v[214:217], v[2:17]
	v_add_f32_e32 v243, v243, v86
	v_add_f32_e32 v242, v242, v87
	v_add_f32_e32 v243, v243, v88
	v_add_f32_e32 v242, v242, v89
	v_exp_f32_e32 v90, v90
	v_exp_f32_e32 v91, v91
	ds_read_b64_tr_b16 v[214:215], v190 offset:9408
	ds_read_b64_tr_b16 v[216:217], v190 offset:11968
	s_waitcnt lgkmcnt(4)
	v_mfma_f32_32x32x16_bf16 v[50:65], v[82:85], v[244:247], v[50:65]
	v_exp_f32_e32 v92, v92
	v_exp_f32_e32 v93, v93
	v_exp_f32_e32 v94, v94
	ds_read_b64_tr_b16 v[244:245], v190 offset:14336
	ds_read_b64_tr_b16 v[246:247], v190 offset:16896
	s_waitcnt lgkmcnt(4)
	v_mfma_f32_32x32x16_bf16 v[34:49], v[82:85], v[206:209], v[34:49]
	v_exp_f32_e32 v95, v95
	v_exp_f32_e32 v96, v96
	v_exp_f32_e32 v97, v97
	v_add_f32_e32 v243, v243, v90
	ds_read_b64_tr_b16 v[206:207], v190 offset:14400
	ds_read_b64_tr_b16 v[208:209], v190 offset:16960
	s_waitcnt lgkmcnt(4)
	v_mfma_f32_32x32x16_bf16 v[18:33], v[82:85], v[214:217], v[18:33]
	v_add_f32_e32 v242, v242, v91
	v_add_f32_e32 v243, v243, v92
	v_add_f32_e32 v242, v242, v93
	v_cvt_pk_bf16_f32 v90, v90, v91
	v_cvt_pk_bf16_f32 v91, v92, v93
	v_cvt_pk_bf16_f32 v92, v94, v95
	v_cvt_pk_bf16_f32 v93, v96, v97
	s_nop 0
	ds_read_b64_tr_b16 v[214:215], v190 offset:14464
	ds_read_b64_tr_b16 v[216:217], v190 offset:17024
	s_waitcnt lgkmcnt(4)
	v_mfma_f32_32x32x16_bf16 v[2:17], v[90:93], v[244:247], v[2:17]
	v_add_f32_e32 v243, v243, v94
	v_add_f32_e32 v242, v242, v95
	v_add_f32_e32 v243, v243, v96
	v_add_f32_e32 v242, v242, v97
	v_exp_f32_e32 v98, v98
	v_exp_f32_e32 v99, v99
	ds_read_b64_tr_b16 v[244:245], v190 offset:14528
	ds_read_b64_tr_b16 v[246:247], v190 offset:17088
	s_waitcnt lgkmcnt(4)
	v_mfma_f32_32x32x16_bf16 v[50:65], v[90:93], v[206:209], v[50:65]
	v_exp_f32_e32 v100, v100
	v_exp_f32_e32 v101, v101
	v_exp_f32_e32 v102, v102
	ds_read_b64_tr_b16 v[206:207], v190 offset:19456
	ds_read_b64_tr_b16 v[208:209], v190 offset:22016
	s_waitcnt lgkmcnt(4)
	v_mfma_f32_32x32x16_bf16 v[34:49], v[90:93], v[214:217], v[34:49]
	v_exp_f32_e32 v103, v103
	v_exp_f32_e32 v104, v104
	v_exp_f32_e32 v105, v105
	v_add_f32_e32 v243, v243, v98
	ds_read_b64_tr_b16 v[214:215], v190 offset:19520
	ds_read_b64_tr_b16 v[216:217], v190 offset:22080
	s_waitcnt lgkmcnt(4)
	v_mfma_f32_32x32x16_bf16 v[18:33], v[90:93], v[244:247], v[18:33]
	v_add_f32_e32 v242, v242, v99
	v_add_f32_e32 v243, v243, v100
	v_add_f32_e32 v242, v242, v101
	v_cvt_pk_bf16_f32 v98, v98, v99
	v_cvt_pk_bf16_f32 v99, v100, v101
	v_cvt_pk_bf16_f32 v100, v102, v103
	v_cvt_pk_bf16_f32 v101, v104, v105
	s_nop 0
	ds_read_b64_tr_b16 v[244:245], v190 offset:19584
	ds_read_b64_tr_b16 v[246:247], v190 offset:22144
	s_waitcnt lgkmcnt(4)
	v_mfma_f32_32x32x16_bf16 v[2:17], v[98:101], v[206:209], v[2:17]
	v_add_f32_e32 v243, v243, v102
	v_add_f32_e32 v242, v242, v103
	v_add_f32_e32 v243, v243, v104
	v_add_f32_e32 v242, v242, v105
	v_exp_f32_e32 v106, v106
	v_exp_f32_e32 v107, v107
	ds_read_b64_tr_b16 v[206:207], v190 offset:19648
	ds_read_b64_tr_b16 v[208:209], v190 offset:22208
	s_waitcnt lgkmcnt(4)
	v_mfma_f32_32x32x16_bf16 v[50:65], v[98:101], v[214:217], v[50:65]
	v_exp_f32_e32 v108, v108
	v_exp_f32_e32 v109, v109
	v_exp_f32_e32 v110, v110
	ds_read_b64_tr_b16 v[214:215], v190 offset:24576
	ds_read_b64_tr_b16 v[216:217], v190 offset:27136
	s_waitcnt lgkmcnt(4)
	v_mfma_f32_32x32x16_bf16 v[34:49], v[98:101], v[244:247], v[34:49]
	v_exp_f32_e32 v111, v111
	v_exp_f32_e32 v112, v112
	v_exp_f32_e32 v113, v113
	v_add_f32_e32 v243, v243, v106
	ds_read_b64_tr_b16 v[244:245], v190 offset:24640
	ds_read_b64_tr_b16 v[246:247], v190 offset:27200
	s_waitcnt lgkmcnt(4)
	v_mfma_f32_32x32x16_bf16 v[18:33], v[98:101], v[206:209], v[18:33]
	v_add_f32_e32 v242, v242, v107
	v_add_f32_e32 v243, v243, v108
	v_add_f32_e32 v242, v242, v109
	v_cvt_pk_bf16_f32 v106, v106, v107
	v_cvt_pk_bf16_f32 v107, v108, v109
	v_cvt_pk_bf16_f32 v108, v110, v111
	v_cvt_pk_bf16_f32 v109, v112, v113
	s_nop 0
	ds_read_b64_tr_b16 v[206:207], v190 offset:24704
	ds_read_b64_tr_b16 v[208:209], v190 offset:27264
	s_waitcnt lgkmcnt(4)
	v_mfma_f32_32x32x16_bf16 v[2:17], v[106:109], v[214:217], v[2:17]
	v_add_f32_e32 v243, v243, v110
	v_add_f32_e32 v242, v242, v111
	v_add_f32_e32 v243, v243, v112
	v_add_f32_e32 v242, v242, v113
	v_add_f32_e32 v243, v243, v242
	ds_read_b64_tr_b16 v[214:215], v190 offset:24768
	ds_read_b64_tr_b16 v[216:217], v190 offset:27328
	s_waitcnt lgkmcnt(4)
	v_mfma_f32_32x32x16_bf16 v[50:65], v[106:109], v[244:247], v[50:65]
	s_waitcnt lgkmcnt(2)
	v_mfma_f32_32x32x16_bf16 v[34:49], v[106:109], v[206:209], v[34:49]
	s_waitcnt lgkmcnt(0)
	v_mfma_f32_32x32x16_bf16 v[18:33], v[106:109], v[214:217], v[18:33]
	s_setprio 0
	s_movk_i32 s77, 0x110
	s_andn2_b64 vcc, exec, s[28:29]
	s_cbranch_vccnz .LBB0_77

.LBB0_77:
	s_add_i32 s22, s22, 64
	s_mov_b64 s[28:29], 0x60000
	s_add_i32 s4, s4, 1
	v_lshl_add_u64 v[164:165], v[164:165], 0, s[28:29]
	v_lshl_add_u64 v[162:163], v[162:163], 0, s[28:29]
	s_cmp_lg_u32 s10, s22
	v_lshl_add_u64 v[160:161], v[160:161], 0, s[28:29]
	s_waitcnt lgkmcnt(0)
	s_barrier
	s_cbranch_scc0 .Lfo_out_c3
	s_cmp_lt_u32 s4, s5
	s_cselect_b64 s[28:29], -1, 0
	s_cmp_ge_u32 s4, s5
	s_cbranch_scc0 .LBB0_65
	s_branch .LBB0_66
.Lfo_out_c3:
	v_mov_b32_e32 v191, v243
	s_nop 1
	v_permlane32_swap_b32_e32 v243, v191
	v_add_f32_e32 v243, v243, v191
	ds_write_b32 v180, v243 offset:59392
	v_add_u32_e32 v190, s91, v178
	s_waitcnt lgkmcnt(0)
	ds_read_b128 v[66:69], v190 offset:59392
	ds_read_b128 v[70:73], v190 offset:59424
	ds_read_b128 v[74:77], v190 offset:59456
	ds_read_b128 v[78:81], v190 offset:59488
	s_waitcnt lgkmcnt(0)
	s_branch .LBB0_79
.LBB0_79:
	v_mov_b32_e32 v82, v2
	v_rcp_f32_e32 v2, v67
	v_mov_b32_e32 v83, v50
	v_mov_b32_e32 v85, v18
	v_mov_b32_e32 v50, v3
	v_mov_b32_e32 v18, v35
	v_pk_mul_f32 v[50:51], v[50:51], v[2:3] op_sel_hi:[1,0]
	v_pk_mul_f32 v[2:3], v[18:19], v[2:3] op_sel_hi:[1,0]
	v_mov_b32_e32 v18, v4
	v_rcp_f32_e32 v4, v69
	v_mov_b32_e32 v84, v34
	v_rcp_f32_e32 v34, v68
	v_mov_b32_e32 v19, v52
	v_mov_b32_e32 v69, v20
	v_mov_b32_e32 v52, v5
	v_mov_b32_e32 v20, v37
	v_pk_mul_f32 v[52:53], v[52:53], v[4:5] op_sel_hi:[1,0]
	v_pk_mul_f32 v[4:5], v[20:21], v[4:5] op_sel_hi:[1,0]
	v_mov_b32_e32 v20, v6
	v_rcp_f32_e32 v6, v71
	v_mov_b32_e32 v68, v36
	v_pk_mul_f32 v[18:19], v[18:19], v[34:35] op_sel_hi:[1,0]
	v_pk_mul_f32 v[34:35], v[68:69], v[34:35] op_sel_hi:[1,0]
	v_rcp_f32_e32 v36, v70
	v_mov_b32_e32 v21, v54
	v_mov_b32_e32 v69, v22
	v_mov_b32_e32 v54, v7
	v_mov_b32_e32 v22, v39
	v_pk_mul_f32 v[54:55], v[54:55], v[6:7] op_sel_hi:[1,0]
	v_pk_mul_f32 v[6:7], v[22:23], v[6:7] op_sel_hi:[1,0]
	v_mov_b32_e32 v22, v8
	v_rcp_f32_e32 v8, v73
	v_mov_b32_e32 v68, v38
	v_pk_mul_f32 v[20:21], v[20:21], v[36:37] op_sel_hi:[1,0]
	v_pk_mul_f32 v[36:37], v[68:69], v[36:37] op_sel_hi:[1,0]
	v_rcp_f32_e32 v38, v72
	v_mov_b32_e32 v23, v56
	v_mov_b32_e32 v69, v24
	v_mov_b32_e32 v56, v9
	v_mov_b32_e32 v24, v41
	v_pk_mul_f32 v[56:57], v[56:57], v[8:9] op_sel_hi:[1,0]
	v_pk_mul_f32 v[8:9], v[24:25], v[8:9] op_sel_hi:[1,0]
	v_mov_b32_e32 v24, v10
	v_rcp_f32_e32 v10, v75
	v_mov_b32_e32 v68, v40
	v_pk_mul_f32 v[22:23], v[22:23], v[38:39] op_sel_hi:[1,0]
	v_pk_mul_f32 v[38:39], v[68:69], v[38:39] op_sel_hi:[1,0]
	v_rcp_f32_e32 v40, v74
	v_mov_b32_e32 v25, v58
	v_mov_b32_e32 v69, v26
	v_mov_b32_e32 v58, v11
	v_mov_b32_e32 v26, v43
	v_pk_mul_f32 v[58:59], v[58:59], v[10:11] op_sel_hi:[1,0]
	v_pk_mul_f32 v[10:11], v[26:27], v[10:11] op_sel_hi:[1,0]
	v_mov_b32_e32 v26, v12
	v_rcp_f32_e32 v12, v77
	v_mov_b32_e32 v68, v42
	v_pk_mul_f32 v[24:25], v[24:25], v[40:41] op_sel_hi:[1,0]
	v_pk_mul_f32 v[40:41], v[68:69], v[40:41] op_sel_hi:[1,0]
	v_rcp_f32_e32 v42, v76
	v_mov_b32_e32 v27, v60
	v_mov_b32_e32 v69, v28
	v_mov_b32_e32 v60, v13
	v_mov_b32_e32 v28, v45
	v_pk_mul_f32 v[60:61], v[60:61], v[12:13] op_sel_hi:[1,0]
	v_pk_mul_f32 v[12:13], v[28:29], v[12:13] op_sel_hi:[1,0]
	v_mov_b32_e32 v28, v14
	v_rcp_f32_e32 v14, v79
	v_mov_b32_e32 v68, v44
	v_rcp_f32_e32 v66, v66
	v_pk_mul_f32 v[26:27], v[26:27], v[42:43] op_sel_hi:[1,0]
	v_pk_mul_f32 v[42:43], v[68:69], v[42:43] op_sel_hi:[1,0]
	v_rcp_f32_e32 v44, v78
	v_mov_b32_e32 v29, v62
	v_mov_b32_e32 v69, v30
	v_mov_b32_e32 v62, v15
	v_mov_b32_e32 v30, v47
	v_pk_mul_f32 v[62:63], v[62:63], v[14:15] op_sel_hi:[1,0]
	v_pk_mul_f32 v[14:15], v[30:31], v[14:15] op_sel_hi:[1,0]
	v_mov_b32_e32 v30, v16
	v_rcp_f32_e32 v16, v81
	v_readlane_b32 s4, v251, 9
	v_mov_b32_e32 v68, v46
	v_pk_mul_f32 v[82:83], v[82:83], v[66:67] op_sel_hi:[1,0]
	v_add_u32_e32 v160, s4, v241
	v_pk_mul_f32 v[66:67], v[84:85], v[66:67] op_sel_hi:[1,0]
	v_pk_mul_f32 v[28:29], v[28:29], v[44:45] op_sel_hi:[1,0]
	v_pk_mul_f32 v[44:45], v[68:69], v[44:45] op_sel_hi:[1,0]
	v_mov_b32_e32 v31, v64
	v_mov_b32_e32 v69, v32
	v_mov_b32_e32 v64, v17
	v_mov_b32_e32 v32, v49
	v_mov_b32_e32 v68, v48
	v_pk_mul_f32 v[64:65], v[64:65], v[16:17] op_sel_hi:[1,0]
	v_pk_mul_f32 v[16:17], v[32:33], v[16:17] op_sel_hi:[1,0]
	v_cvt_pk_bf16_f32 v33, v82, v83
	v_add_u32_e32 v32, 0, v160
	v_cvt_pk_bf16_f32 v48, v66, v67
	ds_write2st64_b32 v32, v33, v48 offset1:1
	v_cvt_pk_bf16_f32 v33, v50, v51
	v_cvt_pk_bf16_f32 v2, v2, v3
	ds_write2st64_b32 v32, v33, v2 offset0:2 offset1:3
	v_cvt_pk_bf16_f32 v2, v18, v19
	v_cvt_pk_bf16_f32 v3, v34, v35
	ds_write2st64_b32 v32, v2, v3 offset0:4 offset1:5
	v_cvt_pk_bf16_f32 v2, v52, v53
	v_cvt_pk_bf16_f32 v3, v4, v5
	ds_write2st64_b32 v32, v2, v3 offset0:6 offset1:7
	v_cvt_pk_bf16_f32 v2, v20, v21
	v_cvt_pk_bf16_f32 v3, v36, v37
	ds_write2st64_b32 v32, v2, v3 offset0:8 offset1:9
	v_cvt_pk_bf16_f32 v2, v54, v55
	v_cvt_pk_bf16_f32 v3, v6, v7
	ds_write2st64_b32 v32, v2, v3 offset0:10 offset1:11
	v_cvt_pk_bf16_f32 v2, v22, v23
	v_cvt_pk_bf16_f32 v3, v38, v39
	ds_write2st64_b32 v32, v2, v3 offset0:12 offset1:13
	v_cvt_pk_bf16_f32 v2, v56, v57
	v_cvt_pk_bf16_f32 v3, v8, v9
	ds_write2st64_b32 v32, v2, v3 offset0:14 offset1:15
	v_cvt_pk_bf16_f32 v2, v24, v25
	v_cvt_pk_bf16_f32 v3, v40, v41
	v_rcp_f32_e32 v46, v80
	ds_write2st64_b32 v32, v2, v3 offset0:16 offset1:17
	v_cvt_pk_bf16_f32 v2, v58, v59
	v_cvt_pk_bf16_f32 v3, v10, v11
	ds_write2st64_b32 v32, v2, v3 offset0:18 offset1:19
	v_cvt_pk_bf16_f32 v2, v26, v27
	v_cvt_pk_bf16_f32 v3, v42, v43
	ds_write2st64_b32 v32, v2, v3 offset0:20 offset1:21
	v_cvt_pk_bf16_f32 v2, v60, v61
	v_cvt_pk_bf16_f32 v3, v12, v13
	ds_write2st64_b32 v32, v2, v3 offset0:22 offset1:23
	v_cvt_pk_bf16_f32 v2, v28, v29
	v_cvt_pk_bf16_f32 v3, v44, v45
	v_pk_mul_f32 v[30:31], v[30:31], v[46:47] op_sel_hi:[1,0]
	v_pk_mul_f32 v[46:47], v[68:69], v[46:47] op_sel_hi:[1,0]
	ds_write2st64_b32 v32, v2, v3 offset0:24 offset1:25
	v_cvt_pk_bf16_f32 v2, v62, v63
	v_cvt_pk_bf16_f32 v3, v14, v15
	ds_write2st64_b32 v32, v2, v3 offset0:26 offset1:27
	v_cvt_pk_bf16_f32 v2, v30, v31
	v_cvt_pk_bf16_f32 v3, v46, v47
	ds_write2st64_b32 v32, v2, v3 offset0:28 offset1:29
	v_cvt_pk_bf16_f32 v2, v64, v65
	v_cvt_pk_bf16_f32 v3, v16, v17
	ds_write2st64_b32 v32, v2, v3 offset0:30 offset1:31
	global_load_dwordx4 v[114:117], v[150:151], off offset:2176
	global_load_dwordx4 v[130:133], v[152:153], off
	global_load_dwordx4 v[138:141], v[154:155], off
	global_load_dwordx4 v[118:121], v[156:157], off offset:128
	global_load_dwordx4 v[122:125], v[156:157], off offset:160
	global_load_dwordx4 v[126:129], v[156:157], off offset:192
	global_load_dwordx4 v[134:137], v[156:157], off offset:224
	v_mov_b32_e32 v16, v1
	v_mov_b32_e32 v17, v1
	v_mov_b32_e32 v2, v1
	v_mov_b32_e32 v3, v1
	v_mov_b32_e32 v4, v1
	v_mov_b32_e32 v5, v1
	v_mov_b32_e32 v6, v1
	v_mov_b32_e32 v7, v1
	v_mov_b32_e32 v8, v1
	v_mov_b32_e32 v9, v1
	v_mov_b32_e32 v10, v1
	v_mov_b32_e32 v11, v1
	v_mov_b32_e32 v12, v1
	v_mov_b32_e32 v13, v1
	v_mov_b32_e32 v14, v1
	v_mov_b32_e32 v15, v1
	v_mov_b64_e32 v[64:65], v[16:17]
	v_mov_b64_e32 v[32:33], v[16:17]
	v_mov_b64_e32 v[48:49], v[16:17]
	v_mov_b64_e32 v[80:81], v[16:17]
	v_lshl_add_u64 v[150:151], s[46:47], 0, v[158:159]
	s_mov_b32 s4, 0
	s_mov_b32 s22, 1
	v_mov_b64_e32 v[62:63], v[14:15]
	v_mov_b64_e32 v[60:61], v[12:13]
	v_mov_b64_e32 v[58:59], v[10:11]
	v_mov_b64_e32 v[56:57], v[8:9]
	v_mov_b64_e32 v[54:55], v[6:7]
	v_mov_b64_e32 v[52:53], v[4:5]
	v_mov_b64_e32 v[50:51], v[2:3]
	v_mov_b64_e32 v[30:31], v[14:15]
	v_mov_b64_e32 v[28:29], v[12:13]
	v_mov_b64_e32 v[26:27], v[10:11]
	v_mov_b64_e32 v[24:25], v[8:9]
	v_mov_b64_e32 v[22:23], v[6:7]
	v_mov_b64_e32 v[20:21], v[4:5]
	v_mov_b64_e32 v[18:19], v[2:3]
	v_mov_b64_e32 v[46:47], v[14:15]
	v_mov_b64_e32 v[44:45], v[12:13]
	v_mov_b64_e32 v[42:43], v[10:11]
	v_mov_b64_e32 v[40:41], v[8:9]
	v_mov_b64_e32 v[38:39], v[6:7]
	v_mov_b64_e32 v[36:37], v[4:5]
	v_mov_b64_e32 v[34:35], v[2:3]
	v_mov_b64_e32 v[78:79], v[14:15]
	v_mov_b64_e32 v[76:77], v[12:13]
	v_mov_b64_e32 v[74:75], v[10:11]
	v_mov_b64_e32 v[72:73], v[8:9]
	v_mov_b64_e32 v[70:71], v[6:7]
	v_mov_b64_e32 v[68:69], v[4:5]
	v_mov_b64_e32 v[66:67], v[2:3]
	s_waitcnt vmcnt(6)
	ds_write_b128 v238, v[114:117]
	s_waitcnt vmcnt(5)
	ds_write_b128 v239, v[130:133] offset:9216
	s_waitcnt vmcnt(4)
	ds_write_b128 v240, v[138:141] offset:9216
	s_waitcnt vmcnt(0) lgkmcnt(0)
	s_barrier
	v_mov_b32_e32 v238, 0
	s_mov_b32 s79, 1
	s_cmp_lt_u32 s22, s5
	s_cselect_b64 s[28:29], -1, 0
	s_cmp_ge_u32 s22, s5
	s_cbranch_scc1 .LBB0_81

.LBB0_81:
	s_add_i32 s23, s22, -1
	s_and_b32 s23, s23, 1
	s_cmp_gt_u32 s4, s11
	s_cbranch_scc1 .LBB0_88
	s_mul_i32 s26, s23, 0x7400
	s_add_i32 s26, s26, 0
	s_add_i32 s30, s4, 63
	s_cmp_le_u32 s30, s1
	v_add3_u32 v152, s26, v177, v178
	ds_read_b128 v[98:101], v152
	ds_read_b128 v[102:105], v152 offset:32
	ds_read_b128 v[106:109], v152 offset:64
	ds_read_b128 v[110:113], v152 offset:96
	ds_read_b128 v[154:157], v152 offset:4608
	ds_read_b128 v[162:165], v152 offset:4640
	ds_read_b128 v[190:193], v152 offset:4672
	ds_read_b128 v[206:209], v152 offset:4704
	s_setprio 1
	s_waitcnt lgkmcnt(7)
	v_mfma_f32_32x32x16_bf16 v[82:97], v[98:101], v[118:121], v[66:81]
	s_waitcnt lgkmcnt(6)
	v_mfma_f32_32x32x16_bf16 v[82:97], v[102:105], v[122:125], v[82:97]
	s_waitcnt lgkmcnt(5)
	v_mfma_f32_32x32x16_bf16 v[82:97], v[106:109], v[126:129], v[82:97]
	s_waitcnt lgkmcnt(4)
	v_mfma_f32_32x32x16_bf16 v[82:97], v[110:113], v[134:137], v[82:97]
	s_waitcnt lgkmcnt(3)
	v_mfma_f32_32x32x16_bf16 v[98:113], v[154:157], v[118:121], v[66:81]
	s_waitcnt lgkmcnt(2)
	v_mfma_f32_32x32x16_bf16 v[98:113], v[162:165], v[122:125], v[98:113]
	s_waitcnt lgkmcnt(1)
	v_mfma_f32_32x32x16_bf16 v[98:113], v[190:193], v[126:129], v[98:113]
	s_waitcnt lgkmcnt(0)
	v_mfma_f32_32x32x16_bf16 v[98:113], v[206:209], v[134:137], v[98:113]
	s_setprio 0
	s_cbranch_scc1 .LBB0_84
	v_add_u32_e32 v152, s4, v179
	v_cmp_le_i32_e32 vcc, v152, v183
	v_add_u32_e32 v154, 2, v152
	s_nop 7
	v_cndmask_b32_e32 v98, v220, v98, vcc
	v_cmp_lt_i32_e32 vcc, v152, v173
	s_nop 1
	v_cndmask_b32_e32 v83, v220, v83, vcc
	v_cmp_le_i32_e32 vcc, v152, v173
	s_nop 1
	v_cndmask_b32_e32 v82, v220, v82, vcc
	v_cmp_le_i32_e32 vcc, v152, v184
	s_nop 1
	v_cndmask_b32_e32 v99, v220, v99, vcc
	v_cmp_le_i32_e32 vcc, v154, v173
	v_add_u32_e32 v154, 3, v152
	s_nop 0
	v_cndmask_b32_e32 v84, v220, v84, vcc
	v_cmp_le_i32_e32 vcc, v152, v185
	s_nop 1
	v_cndmask_b32_e32 v100, v220, v100, vcc
	v_cmp_le_i32_e32 vcc, v154, v173
	s_nop 1
	v_cndmask_b32_e32 v85, v220, v85, vcc
	v_cmp_le_i32_e32 vcc, v152, v186
	s_nop 1
	v_cndmask_b32_e32 v101, v220, v101, vcc
	v_cmp_le_i32_e32 vcc, v152, v187
	s_nop 1
	v_cndmask_b32_e32 v86, v220, v86, vcc
	v_cmp_le_i32_e32 vcc, v152, v188
	s_nop 1
	v_cndmask_b32_e32 v102, v220, v102, vcc
	v_cmp_le_i32_e32 vcc, v152, v189
	s_nop 1
	v_cndmask_b32_e32 v87, v220, v87, vcc
	v_cmp_le_i32_e32 vcc, v152, v195
	s_nop 1
	v_cndmask_b32_e32 v103, v220, v103, vcc
	v_cmp_le_i32_e32 vcc, v152, v196
	s_nop 1
	v_cndmask_b32_e32 v88, v220, v88, vcc
	v_cmp_le_i32_e32 vcc, v152, v197
	s_nop 1
	v_cndmask_b32_e32 v104, v220, v104, vcc
	v_cmp_le_i32_e32 vcc, v152, v198
	s_nop 1
	v_cndmask_b32_e32 v89, v220, v89, vcc
	v_cmp_le_i32_e32 vcc, v152, v199
	s_nop 1
	v_cndmask_b32_e32 v105, v220, v105, vcc
	v_cmp_le_i32_e32 vcc, v152, v200
	s_nop 1
	v_cndmask_b32_e32 v90, v220, v90, vcc
	v_cmp_le_i32_e32 vcc, v152, v201
	s_nop 1
	v_cndmask_b32_e32 v106, v220, v106, vcc
	v_cmp_le_i32_e32 vcc, v152, v202
	s_nop 1
	v_cndmask_b32_e32 v91, v220, v91, vcc
	v_cmp_le_i32_e32 vcc, v152, v203
	s_nop 1
	v_cndmask_b32_e32 v107, v220, v107, vcc
	v_cmp_le_i32_e32 vcc, v152, v204
	s_nop 1
	v_cndmask_b32_e32 v92, v220, v92, vcc
	v_cmp_le_i32_e32 vcc, v152, v205
	s_nop 1
	v_cndmask_b32_e32 v108, v220, v108, vcc
	v_cmp_le_i32_e32 vcc, v152, v228
	s_nop 1
	v_cndmask_b32_e32 v93, v220, v93, vcc
	v_cmp_le_i32_e32 vcc, v152, v229
	s_nop 1
	v_cndmask_b32_e32 v109, v220, v109, vcc
	v_cmp_le_i32_e32 vcc, v152, v230
	s_nop 1
	v_cndmask_b32_e32 v94, v220, v94, vcc
	v_cmp_le_i32_e32 vcc, v152, v231
	s_nop 1
	v_cndmask_b32_e32 v110, v220, v110, vcc
	v_cmp_le_i32_e32 vcc, v152, v232
	s_nop 1
	v_cndmask_b32_e32 v95, v220, v95, vcc
	v_cmp_le_i32_e32 vcc, v152, v233
	s_nop 1
	v_cndmask_b32_e32 v111, v220, v111, vcc
	v_cmp_le_i32_e32 vcc, v152, v234
	s_nop 1
	v_cndmask_b32_e32 v96, v220, v96, vcc
	v_cmp_le_i32_e32 vcc, v152, v235
	s_nop 1
	v_cndmask_b32_e32 v112, v220, v112, vcc
	v_cmp_le_i32_e32 vcc, v152, v236
	s_nop 1
	v_cndmask_b32_e32 v97, v220, v97, vcc
	v_cmp_le_i32_e32 vcc, v152, v237
	s_nop 1
	v_cndmask_b32_e32 v113, v220, v113, vcc

.Lfo_resc_c4:
	v_exp_f32_e64 v155, -v155
	v_sub_f32_e32 v66, v66, v152
	v_sub_f32_e32 v82, v82, v152
	v_sub_f32_e32 v83, v83, v152
	v_sub_f32_e32 v84, v84, v152
	v_sub_f32_e32 v85, v85, v152
	v_sub_f32_e32 v86, v86, v152
	v_sub_f32_e32 v87, v87, v152
	v_sub_f32_e32 v88, v88, v152
	v_sub_f32_e32 v89, v89, v152
	v_sub_f32_e32 v90, v90, v152
	v_sub_f32_e32 v91, v91, v152
	v_sub_f32_e32 v92, v92, v152
	v_sub_f32_e32 v93, v93, v152
	v_sub_f32_e32 v94, v94, v152
	v_sub_f32_e32 v95, v95, v152
	v_sub_f32_e32 v96, v96, v152
	v_sub_f32_e32 v97, v97, v152
	v_sub_f32_e32 v98, v98, v152
	v_sub_f32_e32 v99, v99, v152
	v_sub_f32_e32 v100, v100, v152
	v_sub_f32_e32 v101, v101, v152
	v_sub_f32_e32 v102, v102, v152
	v_sub_f32_e32 v103, v103, v152
	v_sub_f32_e32 v104, v104, v152
	v_sub_f32_e32 v105, v105, v152
	v_sub_f32_e32 v106, v106, v152
	v_sub_f32_e32 v107, v107, v152
	v_sub_f32_e32 v108, v108, v152
	v_sub_f32_e32 v109, v109, v152
	v_sub_f32_e32 v110, v110, v152
	v_sub_f32_e32 v111, v111, v152
	v_sub_f32_e32 v112, v112, v152
	v_sub_f32_e32 v113, v113, v152
	v_mov_b32_e32 v67, v66
	v_mov_b32_e32 v68, v66
	v_mov_b32_e32 v69, v66
	v_mov_b32_e32 v70, v66
	v_mov_b32_e32 v71, v66
	v_mov_b32_e32 v72, v66
	v_mov_b32_e32 v73, v66
	v_mov_b32_e32 v74, v66
	v_mov_b32_e32 v75, v66
	v_mov_b32_e32 v76, v66
	v_mov_b32_e32 v77, v66
	v_mov_b32_e32 v78, v66
	v_mov_b32_e32 v79, v66
	v_mov_b32_e32 v80, v66
	v_mov_b32_e32 v81, v66
	v_mul_f32_e32 v238, v238, v155
	s_and_saveexec_b64 s[30:31], s[42:43]
	s_cbranch_execz .LBB0_87
	ds_write_b32 v180, v155 offset:59392
.LBB0_87:
	s_or_b64 exec, exec, s[30:31]
	v_add_u32_e32 v153, s91, v178
	ds_read_b128 v[154:157], v153 offset:59488
	ds_read_b128 v[162:165], v153 offset:59456
	ds_read_b128 v[190:193], v153 offset:59424
	ds_read_b128 v[206:209], v153 offset:59392
	s_waitcnt lgkmcnt(3)
	v_pk_mul_f32 v[14:15], v[14:15], v[154:155]
	s_waitcnt lgkmcnt(2)
	v_pk_mul_f32 v[10:11], v[10:11], v[162:163]
	s_waitcnt lgkmcnt(1)
	v_pk_mul_f32 v[6:7], v[6:7], v[190:191]
	v_pk_mul_f32 v[16:17], v[16:17], v[156:157]
	v_pk_mul_f32 v[12:13], v[12:13], v[164:165]
	v_pk_mul_f32 v[8:9], v[8:9], v[192:193]
	s_waitcnt lgkmcnt(0)
	v_pk_mul_f32 v[4:5], v[4:5], v[208:209]
	v_pk_mul_f32 v[2:3], v[2:3], v[206:207]
	v_pk_mul_f32 v[62:63], v[62:63], v[154:155]
	v_pk_mul_f32 v[58:59], v[58:59], v[162:163]
	v_pk_mul_f32 v[54:55], v[54:55], v[190:191]
	v_pk_mul_f32 v[64:65], v[64:65], v[156:157]
	v_pk_mul_f32 v[60:61], v[60:61], v[164:165]
	v_pk_mul_f32 v[56:57], v[56:57], v[192:193]
	v_pk_mul_f32 v[52:53], v[52:53], v[208:209]
	v_pk_mul_f32 v[50:51], v[50:51], v[206:207]
	v_pk_mul_f32 v[30:31], v[30:31], v[154:155]
	v_pk_mul_f32 v[26:27], v[26:27], v[162:163]
	v_pk_mul_f32 v[22:23], v[22:23], v[190:191]
	v_pk_mul_f32 v[32:33], v[32:33], v[156:157]
	v_pk_mul_f32 v[28:29], v[28:29], v[164:165]
	v_pk_mul_f32 v[24:25], v[24:25], v[192:193]
	v_pk_mul_f32 v[20:21], v[20:21], v[208:209]
	v_pk_mul_f32 v[18:19], v[18:19], v[206:207]
	v_pk_mul_f32 v[46:47], v[46:47], v[154:155]
	v_pk_mul_f32 v[42:43], v[42:43], v[162:163]
	v_pk_mul_f32 v[38:39], v[38:39], v[190:191]
	v_pk_mul_f32 v[48:49], v[48:49], v[156:157]
	v_pk_mul_f32 v[44:45], v[44:45], v[164:165]
	v_pk_mul_f32 v[40:41], v[40:41], v[192:193]
	v_pk_mul_f32 v[36:37], v[36:37], v[208:209]
	v_pk_mul_f32 v[34:35], v[34:35], v[206:207]
	s_branch .LBB0_90

.LBB0_89:
.LBB0_90:
	v_add3_u32 v153, s26, v182, v181
	ds_read_b64_tr_b16 v[154:155], v153 offset:9216
	ds_read_b64_tr_b16 v[156:157], v153 offset:11776
	ds_read_b64_tr_b16 v[162:163], v153 offset:9280
	ds_read_b64_tr_b16 v[164:165], v153 offset:11840
	ds_read_b64_tr_b16 v[190:191], v153 offset:9344
	ds_read_b64_tr_b16 v[192:193], v153 offset:11904
	ds_read_b64_tr_b16 v[206:207], v153 offset:9408
	ds_read_b64_tr_b16 v[208:209], v153 offset:11968
	v_exp_f32_e32 v82, v82
	v_exp_f32_e32 v83, v83
	v_exp_f32_e32 v84, v84
	v_exp_f32_e32 v85, v85
	v_exp_f32_e32 v86, v86
	v_exp_f32_e32 v87, v87
	v_exp_f32_e32 v88, v88
	v_exp_f32_e32 v89, v89
	v_add_f32_e32 v239, v82, v83
	v_add_f32_e32 v238, v238, v84
	v_add_f32_e32 v239, v239, v85
	v_cvt_pk_bf16_f32 v82, v82, v83
	v_cvt_pk_bf16_f32 v83, v84, v85
	v_cvt_pk_bf16_f32 v84, v86, v87
	v_cvt_pk_bf16_f32 v85, v88, v89
	s_setprio 1
	s_waitcnt lgkmcnt(6)
	v_mfma_f32_32x32x16_bf16 v[2:17], v[82:85], v[154:157], v[2:17]
	v_add_f32_e32 v238, v238, v86
	v_add_f32_e32 v239, v239, v87
	v_add_f32_e32 v238, v238, v88
	v_add_f32_e32 v239, v239, v89
	v_exp_f32_e32 v90, v90
	v_exp_f32_e32 v91, v91
	ds_read_b64_tr_b16 v[154:155], v153 offset:14336
	ds_read_b64_tr_b16 v[156:157], v153 offset:16896
	s_waitcnt lgkmcnt(6)
	v_mfma_f32_32x32x16_bf16 v[50:65], v[82:85], v[162:165], v[50:65]
	v_exp_f32_e32 v92, v92
	v_exp_f32_e32 v93, v93
	v_exp_f32_e32 v94, v94
	ds_read_b64_tr_b16 v[162:163], v153 offset:14400
	ds_read_b64_tr_b16 v[164:165], v153 offset:16960
	s_waitcnt lgkmcnt(6)
	v_mfma_f32_32x32x16_bf16 v[18:33], v[82:85], v[190:193], v[18:33]
	v_exp_f32_e32 v95, v95
	v_exp_f32_e32 v96, v96
	v_exp_f32_e32 v97, v97
	v_add_f32_e32 v238, v238, v90
	ds_read_b64_tr_b16 v[190:191], v153 offset:14464
	ds_read_b64_tr_b16 v[192:193], v153 offset:17024
	s_waitcnt lgkmcnt(6)
	v_mfma_f32_32x32x16_bf16 v[34:49], v[82:85], v[206:209], v[34:49]
	v_add_f32_e32 v239, v239, v91
	v_add_f32_e32 v238, v238, v92
	v_add_f32_e32 v239, v239, v93
	v_cvt_pk_bf16_f32 v90, v90, v91
	v_cvt_pk_bf16_f32 v91, v92, v93
	v_cvt_pk_bf16_f32 v92, v94, v95
	v_cvt_pk_bf16_f32 v93, v96, v97
	s_nop 0
	ds_read_b64_tr_b16 v[206:207], v153 offset:14528
	ds_read_b64_tr_b16 v[208:209], v153 offset:17088
	s_waitcnt lgkmcnt(6)
	v_mfma_f32_32x32x16_bf16 v[2:17], v[90:93], v[154:157], v[2:17]
	v_add_f32_e32 v238, v238, v94
	v_add_f32_e32 v239, v239, v95
	v_add_f32_e32 v238, v238, v96
	v_add_f32_e32 v239, v239, v97
	v_exp_f32_e32 v98, v98
	v_exp_f32_e32 v99, v99
	ds_read_b64_tr_b16 v[154:155], v153 offset:19456
	ds_read_b64_tr_b16 v[156:157], v153 offset:22016
	s_waitcnt lgkmcnt(6)
	v_mfma_f32_32x32x16_bf16 v[50:65], v[90:93], v[162:165], v[50:65]
	v_exp_f32_e32 v100, v100
	v_exp_f32_e32 v101, v101
	v_exp_f32_e32 v102, v102
	ds_read_b64_tr_b16 v[162:163], v153 offset:19520
	ds_read_b64_tr_b16 v[164:165], v153 offset:22080
	s_waitcnt lgkmcnt(6)
	v_mfma_f32_32x32x16_bf16 v[18:33], v[90:93], v[190:193], v[18:33]
	v_exp_f32_e32 v103, v103
	v_exp_f32_e32 v104, v104
	v_exp_f32_e32 v105, v105
	v_add_f32_e32 v238, v238, v98
	ds_read_b64_tr_b16 v[190:191], v153 offset:19584
	ds_read_b64_tr_b16 v[192:193], v153 offset:22144
	s_waitcnt lgkmcnt(6)
	v_mfma_f32_32x32x16_bf16 v[34:49], v[90:93], v[206:209], v[34:49]
	v_add_f32_e32 v239, v239, v99
	v_add_f32_e32 v238, v238, v100
	v_add_f32_e32 v239, v239, v101
	v_cvt_pk_bf16_f32 v98, v98, v99
	v_cvt_pk_bf16_f32 v99, v100, v101
	v_cvt_pk_bf16_f32 v100, v102, v103
	v_cvt_pk_bf16_f32 v101, v104, v105
	s_nop 0
	ds_read_b64_tr_b16 v[206:207], v153 offset:19648
	ds_read_b64_tr_b16 v[208:209], v153 offset:22208
	s_waitcnt lgkmcnt(6)
	v_mfma_f32_32x32x16_bf16 v[2:17], v[98:101], v[154:157], v[2:17]
	v_add_f32_e32 v238, v238, v102
	v_add_f32_e32 v239, v239, v103
	v_add_f32_e32 v238, v238, v104
	v_add_f32_e32 v239, v239, v105
	v_exp_f32_e32 v106, v106
	v_exp_f32_e32 v107, v107
	ds_read_b64_tr_b16 v[154:155], v153 offset:24576
	ds_read_b64_tr_b16 v[156:157], v153 offset:27136
	s_waitcnt lgkmcnt(6)
	v_mfma_f32_32x32x16_bf16 v[50:65], v[98:101], v[162:165], v[50:65]
	v_exp_f32_e32 v108, v108
	v_exp_f32_e32 v109, v109
	v_exp_f32_e32 v110, v110
	ds_read_b64_tr_b16 v[162:163], v153 offset:24640
	ds_read_b64_tr_b16 v[164:165], v153 offset:27200
	s_waitcnt lgkmcnt(6)
	v_mfma_f32_32x32x16_bf16 v[18:33], v[98:101], v[190:193], v[18:33]
	v_exp_f32_e32 v111, v111
	v_exp_f32_e32 v112, v112
	v_exp_f32_e32 v113, v113
	v_add_f32_e32 v238, v238, v106
	ds_read_b64_tr_b16 v[190:191], v153 offset:24704
	ds_read_b64_tr_b16 v[192:193], v153 offset:27264
	s_waitcnt lgkmcnt(6)
	v_mfma_f32_32x32x16_bf16 v[34:49], v[98:101], v[206:209], v[34:49]
	v_add_f32_e32 v239, v239, v107
	v_add_f32_e32 v238, v238, v108
	v_add_f32_e32 v239, v239, v109
	v_cvt_pk_bf16_f32 v106, v106, v107
	v_cvt_pk_bf16_f32 v107, v108, v109
	v_cvt_pk_bf16_f32 v108, v110, v111
	v_cvt_pk_bf16_f32 v109, v112, v113
	s_nop 0
	ds_read_b64_tr_b16 v[206:207], v153 offset:24768
	ds_read_b64_tr_b16 v[208:209], v153 offset:27328
	s_waitcnt lgkmcnt(6)
	v_mfma_f32_32x32x16_bf16 v[2:17], v[106:109], v[154:157], v[2:17]
	v_add_f32_e32 v238, v238, v110
	v_add_f32_e32 v239, v239, v111
	v_add_f32_e32 v238, v238, v112
	v_add_f32_e32 v239, v239, v113
	v_add_f32_e32 v238, v238, v239
	s_waitcnt lgkmcnt(4)
	v_mfma_f32_32x32x16_bf16 v[50:65], v[106:109], v[162:165], v[50:65]
	s_waitcnt lgkmcnt(2)
	v_mfma_f32_32x32x16_bf16 v[18:33], v[106:109], v[190:193], v[18:33]
	s_waitcnt lgkmcnt(0)
	v_mfma_f32_32x32x16_bf16 v[34:49], v[106:109], v[206:209], v[34:49]
	s_setprio 0
	s_movk_i32 s77, 0x110
	s_andn2_b64 vcc, exec, s[28:29]
	s_cbranch_vccnz .LBB0_92

.LBB0_92:
	s_add_i32 s4, s4, 64
	s_mov_b64 s[28:29], 0x60000
	s_add_i32 s22, s22, 1
	v_lshl_add_u64 v[146:147], v[146:147], 0, s[28:29]
	v_lshl_add_u64 v[148:149], v[148:149], 0, s[28:29]
	s_cmp_lg_u32 s10, s4
	v_lshl_add_u64 v[150:151], v[150:151], 0, s[28:29]
	s_waitcnt lgkmcnt(0)
	s_barrier
	s_cbranch_scc0 .Lfo_out_c4
	s_cmp_lt_u32 s22, s5
	s_cselect_b64 s[28:29], -1, 0
	s_cmp_ge_u32 s22, s5
	s_cbranch_scc0 .LBB0_80
	s_branch .LBB0_81
.Lfo_out_c4:
	v_mov_b32_e32 v155, v238
	s_nop 1
	v_permlane32_swap_b32_e32 v238, v155
	v_add_f32_e32 v238, v238, v155
	ds_write_b32 v180, v238 offset:59392
	v_add_u32_e32 v154, s91, v178
	s_waitcnt lgkmcnt(0)
	ds_read_b128 v[66:69], v154 offset:59392
	ds_read_b128 v[70:73], v154 offset:59424
	ds_read_b128 v[74:77], v154 offset:59456
	ds_read_b128 v[78:81], v154 offset:59488
	s_waitcnt lgkmcnt(0)
	s_branch .LBB0_33
